# plus: all per-block s_setprio flips removed from the 13 GEMM K-loops (both half-workgroups stay at priority 0)
# speedup vs baseline: 1.0077x; 1.0044x over previous
; #define PG8_STAGE(bufoff, gbase, voff) do { _Pragma("unroll") for (int _i = 0; _i < 2; ++_i) \
;         __builtin_amdgcn_global_load_lds((const unsigned*)((const char*)(gbase) + (voff)[_i]), (LAS unsigned*)(lds + (bufoff) + ldsw + _i * 8192), 16, 0, 0); } while (0)
; #define PG8_LDA(dst, b, h) do { _Pragma("unroll") for (int m = 0; m < 4; ++m) _Pragma("unroll") for (int k = 0; k < 2; ++k) dst[m][k] = *(const LAS bf16x8*)(lds + PG8_SA(b, h) + aoff + m * 2048 + k * 1024); } while (0)
; #define PG8_LDB(dst, b, h) do { _Pragma("unroll") for (int n = 0; n < 2; ++n) _Pragma("unroll") for (int k = 0; k < 2; ++k) dst[n][k] = *(const LAS bf16x8*)(lds + PG8_SB(b, h) + boff + n * 2048 + k * 1024); } while (0)
; #define PG8_MMA(ai, bj, At, Bt) do { __builtin_amdgcn_s_setprio(1); _Pragma("unroll") for (int m = 0; m < 4; ++m) _Pragma("unroll") for (int n = 0; n < 2; ++n) _Pragma("unroll") for (int k = 0; k < 2; ++k) \
;         acc[ai][bj][m][n] = __builtin_amdgcn_mfma_f32_16x16x32_bf16(Bt[n][k], At[m][k], acc[ai][bj][m][n], 0, 0, 0); __builtin_amdgcn_s_setprio(0); } while (0)
; #define PG8_WAIT_V(n) asm volatile("s_waitcnt vmcnt(" #n ")" ::: "memory")
; #define PG8_WAIT_L(n) asm volatile("s_waitcnt lgkmcnt(" #n ")" ::: "memory")
; #define PG8_BAR __builtin_amdgcn_s_barrier()
; #define PG8_SCHED __builtin_amdgcn_sched_barrier(0)
; template <class Epi, class Map>
; __device__ __forceinline__ void gemm_phase(LAS unsigned char* lds, const Gemm g, const Sched<Map>& S, const Epi& E) {
;     ...
;         for (int t = 0; t < nt; t += 2) {
;             const bool last = (t == nt - 2);
;             const char* a1 = cA + (size_t)(t + 1) * kstep;
;             const char* a2 = last ? nA : cA + (size_t)(t + 2) * kstep; const char* b2 = last ? nB : cB + (size_t)(t + 2) * kstep;
;             const char* a3 = a2 + kstep; const char* b3 = b2 + kstep;
;             PG8_LDB(B0, 0, 0); PG8_LDB(B1, 0, 1); PG8_SCHED; PG8_LDA(At, 0, 0); PG8_STAGE(PG8_SA(1, 1), a1 + hstepA, voffA);
;             PG8_WAIT_V(8); PG8_WAIT_L(0); PG8_BAR; PG8_MMA(0, 0, At, B0); PG8_MMA(0, 1, At, B1); PG8_BAR; PG8_SCHED;
;             PG8_LDA(At, 0, 1); PG8_STAGE(PG8_SB(0, 0), b2, voffB); PG8_STAGE(PG8_SB(0, 1), b2 + hstepB, voffB); PG8_STAGE(PG8_SA(0, 0), a2, voffA);
.LBB0_223:
	s_add_u32 s48, s42, s46
	s_addc_u32 s49, s43, s47
	s_add_u32 s48, s48, 0x100
	s_addc_u32 s49, s49, 0
	s_add_u32 s62, s65, s46
	s_addc_u32 s63, s66, s47
	s_add_i32 s68, 0, 0x10000
	s_cmpk_eq_i32 s46, 0xf00
	s_cselect_b32 s51, s56, s49
	s_cselect_b32 s50, s57, s48
	v_add_u32_e32 v136, s68, v170
	s_cselect_b32 s49, s58, s63
	s_cselect_b32 s48, s59, s62
	s_add_i32 s62, 0, 0x14000
	ds_read_b128 v[132:135], v136
	ds_read_b128 v[162:165], v136 offset:1024
	ds_read_b128 v[172:175], v136 offset:2048
	ds_read_b128 v[176:179], v136 offset:3072
	v_add_u32_e32 v136, s62, v170
	ds_read_b128 v[192:195], v136
	ds_read_b128 v[196:199], v136 offset:1024
	ds_read_b128 v[200:203], v136 offset:2048
	ds_read_b128 v[204:207], v136 offset:3072
	v_lshl_add_u64 v[136:137], v[130:131], 0, s[46:47]
	s_add_i32 m0, s6, 0xc000
	ds_read_b128 v[208:211], v171
	ds_read_b128 v[212:215], v171 offset:1024
	ds_read_b128 v[216:219], v171 offset:2048
	ds_read_b128 v[220:223], v171 offset:3072
	ds_read_b128 v[224:227], v171 offset:4096
	ds_read_b128 v[228:231], v171 offset:5120
	ds_read_b128 v[232:235], v171 offset:6144
	ds_read_b128 v[236:239], v171 offset:7168
	global_load_lds_dwordx4 v[136:137], off
	v_lshl_add_u64 v[136:137], v[128:129], 0, s[46:47]
	s_add_i32 m0, s6, 0xe000
	s_nop 0
	global_load_lds_dwordx4 v[136:137], off
	s_waitcnt vmcnt(8)
	s_waitcnt lgkmcnt(0)
	s_barrier
	s_waitcnt lgkmcnt(0)
	v_mfma_f32_16x16x32_bf16 v[124:127], v[132:135], v[208:211], v[124:127]
	v_mfma_f32_16x16x32_bf16 v[120:123], v[172:175], v[208:211], v[120:123]
	v_mfma_f32_16x16x32_bf16 v[108:111], v[132:135], v[216:219], v[108:111]
	v_mfma_f32_16x16x32_bf16 v[104:107], v[172:175], v[216:219], v[104:107]
	v_mfma_f32_16x16x32_bf16 v[92:95], v[132:135], v[224:227], v[92:95]
	v_mfma_f32_16x16x32_bf16 v[88:91], v[172:175], v[224:227], v[88:91]
	v_mfma_f32_16x16x32_bf16 v[76:79], v[132:135], v[232:235], v[76:79]
	v_mfma_f32_16x16x32_bf16 v[72:75], v[172:175], v[232:235], v[72:75]
	v_mfma_f32_16x16x32_bf16 v[124:127], v[162:165], v[212:215], v[124:127]
	v_mfma_f32_16x16x32_bf16 v[120:123], v[176:179], v[212:215], v[120:123]
	v_mfma_f32_16x16x32_bf16 v[108:111], v[162:165], v[220:223], v[108:111]
	v_mfma_f32_16x16x32_bf16 v[104:107], v[176:179], v[220:223], v[104:107]
	v_mfma_f32_16x16x32_bf16 v[92:95], v[162:165], v[228:231], v[92:95]
	v_mfma_f32_16x16x32_bf16 v[88:91], v[176:179], v[228:231], v[88:91]
	v_mfma_f32_16x16x32_bf16 v[76:79], v[162:165], v[236:239], v[76:79]
	v_mfma_f32_16x16x32_bf16 v[72:75], v[176:179], v[236:239], v[72:75]
	v_mfma_f32_16x16x32_bf16 v[116:119], v[192:195], v[208:211], v[116:119]
	v_mfma_f32_16x16x32_bf16 v[112:115], v[200:203], v[208:211], v[112:115]
	v_mfma_f32_16x16x32_bf16 v[100:103], v[192:195], v[216:219], v[100:103]
	v_mfma_f32_16x16x32_bf16 v[96:99], v[200:203], v[216:219], v[96:99]
	v_mfma_f32_16x16x32_bf16 v[84:87], v[192:195], v[224:227], v[84:87]
	v_mfma_f32_16x16x32_bf16 v[80:83], v[200:203], v[224:227], v[80:83]
	v_mfma_f32_16x16x32_bf16 v[68:71], v[192:195], v[232:235], v[68:71]
	v_mfma_f32_16x16x32_bf16 v[64:67], v[200:203], v[232:235], v[64:67]
	v_mfma_f32_16x16x32_bf16 v[116:119], v[196:199], v[212:215], v[116:119]
	v_mfma_f32_16x16x32_bf16 v[112:115], v[204:207], v[212:215], v[112:115]
	v_mfma_f32_16x16x32_bf16 v[100:103], v[196:199], v[220:223], v[100:103]
	v_mfma_f32_16x16x32_bf16 v[96:99], v[204:207], v[220:223], v[96:99]
	v_mfma_f32_16x16x32_bf16 v[84:87], v[196:199], v[228:231], v[84:87]
	v_mfma_f32_16x16x32_bf16 v[80:83], v[204:207], v[228:231], v[80:83]
	v_mfma_f32_16x16x32_bf16 v[68:71], v[196:199], v[236:239], v[68:71]
	v_mfma_f32_16x16x32_bf16 v[64:67], v[204:207], v[236:239], v[64:67]
	s_barrier
	s_add_i32 s63, s68, s5
	v_lshl_add_u64 v[136:137], s[48:49], 0, v[144:145]
	s_mov_b32 m0, s63
	ds_read_b128 v[208:211], v171 offset:16384
	ds_read_b128 v[212:215], v171 offset:17408
	ds_read_b128 v[216:219], v171 offset:18432
	ds_read_b128 v[220:223], v171 offset:19456
	ds_read_b128 v[224:227], v171 offset:20480
	ds_read_b128 v[228:231], v171 offset:21504
	ds_read_b128 v[232:235], v171 offset:22528
	ds_read_b128 v[236:239], v171 offset:23552
	global_load_lds_dwordx4 v[136:137], off
	s_add_i32 m0, s63, 0x2000
	s_add_u32 s68, s48, 0x80000
	v_lshl_add_u64 v[166:167], s[48:49], 0, v[142:143]
	s_addc_u32 s69, s49, 0
	s_add_i32 s62, s62, s5
	global_load_lds_dwordx4 v[166:167], off
	v_lshl_add_u64 v[180:181], s[68:69], 0, v[144:145]
	s_mov_b32 m0, s62
	v_lshl_add_u64 v[240:241], s[50:51], 0, v[140:141]
	global_load_lds_dwordx4 v[180:181], off
	v_lshl_add_u64 v[180:181], s[68:69], 0, v[142:143]
	s_add_i32 m0, s62, 0x2000
	s_nop 0
	global_load_lds_dwordx4 v[180:181], off
	v_lshl_add_u64 v[180:181], s[50:51], 0, v[138:139]
	s_mov_b32 m0, s6
	s_nop 0
	global_load_lds_dwordx4 v[180:181], off
	s_mov_b32 m0, s7
	s_nop 0
	global_load_lds_dwordx4 v[240:241], off
	s_waitcnt vmcnt(8)
	s_waitcnt lgkmcnt(0)
	s_barrier
; #define PG8_STAGE(bufoff, gbase, voff) do { _Pragma("unroll") for (int _i = 0; _i < 2; ++_i) \
;         __builtin_amdgcn_global_load_lds((const unsigned*)((const char*)(gbase) + (voff)[_i]), (LAS unsigned*)(lds + (bufoff) + ldsw + _i * 8192), 16, 0, 0); } while (0)
; #define PG8_LDA(dst, b, h) do { _Pragma("unroll") for (int m = 0; m < 4; ++m) _Pragma("unroll") for (int k = 0; k < 2; ++k) dst[m][k] = *(const LAS bf16x8*)(lds + PG8_SA(b, h) + aoff + m * 2048 + k * 1024); } while (0)
; #define PG8_LDB(dst, b, h) do { _Pragma("unroll") for (int n = 0; n < 2; ++n) _Pragma("unroll") for (int k = 0; k < 2; ++k) dst[n][k] = *(const LAS bf16x8*)(lds + PG8_SB(b, h) + boff + n * 2048 + k * 1024); } while (0)
; #define PG8_MMA(ai, bj, At, Bt) do { __builtin_amdgcn_s_setprio(1); _Pragma("unroll") for (int m = 0; m < 4; ++m) _Pragma("unroll") for (int n = 0; n < 2; ++n) _Pragma("unroll") for (int k = 0; k < 2; ++k) \
;         acc[ai][bj][m][n] = __builtin_amdgcn_mfma_f32_16x16x32_bf16(Bt[n][k], At[m][k], acc[ai][bj][m][n], 0, 0, 0); __builtin_amdgcn_s_setprio(0); } while (0)
; #define PG8_WAIT_V(n) asm volatile("s_waitcnt vmcnt(" #n ")" ::: "memory")
; #define PG8_WAIT_L(n) asm volatile("s_waitcnt lgkmcnt(" #n ")" ::: "memory")
; #define PG8_BAR __builtin_amdgcn_s_barrier()
; #define PG8_SCHED __builtin_amdgcn_sched_barrier(0)
; template <class Epi, class Map>
; __device__ __forceinline__ void gemm_phase(LAS unsigned char* lds, const Gemm g, const Sched<Map>& S, const Epi& E) {
;     ...
;             PG8_LDA(At, 0, 1); PG8_STAGE(PG8_SB(0, 0), b2, voffB); PG8_STAGE(PG8_SB(0, 1), b2 + hstepB, voffB); PG8_STAGE(PG8_SA(0, 0), a2, voffA);
;             PG8_WAIT_V(8); PG8_WAIT_L(0); PG8_BAR; PG8_MMA(1, 0, At, B0); PG8_MMA(1, 1, At, B1); PG8_BAR; PG8_SCHED;
;             PG8_LDB(B0, 1, 0); PG8_LDB(B1, 1, 1); PG8_SCHED; PG8_LDA(At, 1, 0); PG8_STAGE(PG8_SA(0, 1), a2 + hstepA, voffA);
;             PG8_WAIT_V(8); PG8_WAIT_L(0); PG8_BAR; PG8_MMA(0, 0, At, B0); PG8_MMA(0, 1, At, B1); PG8_BAR; PG8_SCHED;
	s_waitcnt lgkmcnt(0)
	v_mfma_f32_16x16x32_bf16 v[60:63], v[132:135], v[208:211], v[60:63]
	v_mfma_f32_16x16x32_bf16 v[56:59], v[172:175], v[208:211], v[56:59]
	v_mfma_f32_16x16x32_bf16 v[44:47], v[132:135], v[216:219], v[44:47]
	v_mfma_f32_16x16x32_bf16 v[40:43], v[172:175], v[216:219], v[40:43]
	v_mfma_f32_16x16x32_bf16 v[28:31], v[132:135], v[224:227], v[28:31]
	v_mfma_f32_16x16x32_bf16 v[24:27], v[172:175], v[224:227], v[24:27]
	v_mfma_f32_16x16x32_bf16 v[12:15], v[132:135], v[232:235], v[12:15]
	v_mfma_f32_16x16x32_bf16 v[8:11], v[172:175], v[232:235], v[8:11]
	v_mfma_f32_16x16x32_bf16 v[60:63], v[162:165], v[212:215], v[60:63]
	v_mfma_f32_16x16x32_bf16 v[56:59], v[176:179], v[212:215], v[56:59]
	v_mfma_f32_16x16x32_bf16 v[44:47], v[162:165], v[220:223], v[44:47]
	v_mfma_f32_16x16x32_bf16 v[40:43], v[176:179], v[220:223], v[40:43]
	v_mfma_f32_16x16x32_bf16 v[28:31], v[162:165], v[228:231], v[28:31]
	v_mfma_f32_16x16x32_bf16 v[24:27], v[176:179], v[228:231], v[24:27]
	v_mfma_f32_16x16x32_bf16 v[12:15], v[162:165], v[236:239], v[12:15]
	v_mfma_f32_16x16x32_bf16 v[8:11], v[176:179], v[236:239], v[8:11]
	v_mfma_f32_16x16x32_bf16 v[52:55], v[192:195], v[208:211], v[52:55]
	v_mfma_f32_16x16x32_bf16 v[48:51], v[200:203], v[208:211], v[48:51]
	v_mfma_f32_16x16x32_bf16 v[36:39], v[192:195], v[216:219], v[36:39]
	v_mfma_f32_16x16x32_bf16 v[32:35], v[200:203], v[216:219], v[32:35]
	v_mfma_f32_16x16x32_bf16 v[20:23], v[192:195], v[224:227], v[20:23]
	v_mfma_f32_16x16x32_bf16 v[16:19], v[200:203], v[224:227], v[16:19]
	v_mfma_f32_16x16x32_bf16 v[4:7], v[192:195], v[232:235], v[4:7]
	v_mfma_f32_16x16x32_bf16 v[0:3], v[200:203], v[232:235], v[0:3]
	v_mfma_f32_16x16x32_bf16 v[52:55], v[196:199], v[212:215], v[52:55]
	v_mfma_f32_16x16x32_bf16 v[48:51], v[204:207], v[212:215], v[48:51]
	v_mfma_f32_16x16x32_bf16 v[36:39], v[196:199], v[220:223], v[36:39]
	v_mfma_f32_16x16x32_bf16 v[32:35], v[204:207], v[220:223], v[32:35]
	v_mfma_f32_16x16x32_bf16 v[20:23], v[196:199], v[228:231], v[20:23]
	v_mfma_f32_16x16x32_bf16 v[16:19], v[204:207], v[228:231], v[16:19]
	v_mfma_f32_16x16x32_bf16 v[4:7], v[196:199], v[236:239], v[4:7]
	v_mfma_f32_16x16x32_bf16 v[0:3], v[204:207], v[236:239], v[0:3]
	s_barrier
	s_add_i32 s62, 0, 0x18000
	s_add_i32 s63, 0, 0x1c000
	v_add_u32_e32 v176, s62, v170
	v_add_u32_e32 v204, s63, v170
	ds_read_b128 v[132:135], v176
	ds_read_b128 v[162:165], v176 offset:1024
	ds_read_b128 v[172:175], v176 offset:2048
	ds_read_b128 v[176:179], v176 offset:3072
	ds_read_b128 v[192:195], v204
	ds_read_b128 v[196:199], v204 offset:1024
	ds_read_b128 v[200:203], v204 offset:2048
	ds_read_b128 v[204:207], v204 offset:3072
	s_add_u32 s50, s50, s20
	s_addc_u32 s51, s51, 0
	s_mov_b32 m0, s8
	v_lshl_add_u64 v[242:243], s[50:51], 0, v[138:139]
	ds_read_b128 v[208:211], v171 offset:32768
	ds_read_b128 v[212:215], v171 offset:33792
	ds_read_b128 v[216:219], v171 offset:34816
	ds_read_b128 v[220:223], v171 offset:35840
	ds_read_b128 v[224:227], v171 offset:36864
	ds_read_b128 v[228:231], v171 offset:37888
	ds_read_b128 v[232:235], v171 offset:38912
	ds_read_b128 v[236:239], v171 offset:39936
	global_load_lds_dwordx4 v[242:243], off
	v_lshl_add_u64 v[242:243], s[50:51], 0, v[140:141]
	s_mov_b32 m0, s9
	s_nop 0
	global_load_lds_dwordx4 v[242:243], off
	s_waitcnt vmcnt(8)
	s_waitcnt lgkmcnt(0)
	s_barrier
	s_waitcnt lgkmcnt(0)
	v_mfma_f32_16x16x32_bf16 v[124:127], v[132:135], v[208:211], v[124:127]
	v_mfma_f32_16x16x32_bf16 v[120:123], v[172:175], v[208:211], v[120:123]
	v_mfma_f32_16x16x32_bf16 v[108:111], v[132:135], v[216:219], v[108:111]
	v_mfma_f32_16x16x32_bf16 v[104:107], v[172:175], v[216:219], v[104:107]
	v_mfma_f32_16x16x32_bf16 v[92:95], v[132:135], v[224:227], v[92:95]
	v_mfma_f32_16x16x32_bf16 v[88:91], v[172:175], v[224:227], v[88:91]
	v_mfma_f32_16x16x32_bf16 v[76:79], v[132:135], v[232:235], v[76:79]
	v_mfma_f32_16x16x32_bf16 v[72:75], v[172:175], v[232:235], v[72:75]
	v_mfma_f32_16x16x32_bf16 v[124:127], v[162:165], v[212:215], v[124:127]
	v_mfma_f32_16x16x32_bf16 v[120:123], v[176:179], v[212:215], v[120:123]
	v_mfma_f32_16x16x32_bf16 v[108:111], v[162:165], v[220:223], v[108:111]
	v_mfma_f32_16x16x32_bf16 v[104:107], v[176:179], v[220:223], v[104:107]
	v_mfma_f32_16x16x32_bf16 v[92:95], v[162:165], v[228:231], v[92:95]
	v_mfma_f32_16x16x32_bf16 v[88:91], v[176:179], v[228:231], v[88:91]
	v_mfma_f32_16x16x32_bf16 v[76:79], v[162:165], v[236:239], v[76:79]
	v_mfma_f32_16x16x32_bf16 v[72:75], v[176:179], v[236:239], v[72:75]
	v_mfma_f32_16x16x32_bf16 v[116:119], v[192:195], v[208:211], v[116:119]
	v_mfma_f32_16x16x32_bf16 v[112:115], v[200:203], v[208:211], v[112:115]
	v_mfma_f32_16x16x32_bf16 v[100:103], v[192:195], v[216:219], v[100:103]
	v_mfma_f32_16x16x32_bf16 v[96:99], v[200:203], v[216:219], v[96:99]
	v_mfma_f32_16x16x32_bf16 v[84:87], v[192:195], v[224:227], v[84:87]
	v_mfma_f32_16x16x32_bf16 v[80:83], v[200:203], v[224:227], v[80:83]
	v_mfma_f32_16x16x32_bf16 v[68:71], v[192:195], v[232:235], v[68:71]
	v_mfma_f32_16x16x32_bf16 v[64:67], v[200:203], v[232:235], v[64:67]
	v_mfma_f32_16x16x32_bf16 v[116:119], v[196:199], v[212:215], v[116:119]
	v_mfma_f32_16x16x32_bf16 v[112:115], v[204:207], v[212:215], v[112:115]
	v_mfma_f32_16x16x32_bf16 v[100:103], v[196:199], v[220:223], v[100:103]
	v_mfma_f32_16x16x32_bf16 v[96:99], v[204:207], v[220:223], v[96:99]
	v_mfma_f32_16x16x32_bf16 v[84:87], v[196:199], v[228:231], v[84:87]
	v_mfma_f32_16x16x32_bf16 v[80:83], v[204:207], v[228:231], v[80:83]
	v_mfma_f32_16x16x32_bf16 v[68:71], v[196:199], v[236:239], v[68:71]
	v_mfma_f32_16x16x32_bf16 v[64:67], v[204:207], v[236:239], v[64:67]
	s_barrier
; #define PG8_STAGE(bufoff, gbase, voff) do { _Pragma("unroll") for (int _i = 0; _i < 2; ++_i) \
;         __builtin_amdgcn_global_load_lds((const unsigned*)((const char*)(gbase) + (voff)[_i]), (LAS unsigned*)(lds + (bufoff) + ldsw + _i * 8192), 16, 0, 0); } while (0)
; #define PG8_LDA(dst, b, h) do { _Pragma("unroll") for (int m = 0; m < 4; ++m) _Pragma("unroll") for (int k = 0; k < 2; ++k) dst[m][k] = *(const LAS bf16x8*)(lds + PG8_SA(b, h) + aoff + m * 2048 + k * 1024); } while (0)
; #define PG8_MMA(ai, bj, At, Bt) do { __builtin_amdgcn_s_setprio(1); _Pragma("unroll") for (int m = 0; m < 4; ++m) _Pragma("unroll") for (int n = 0; n < 2; ++n) _Pragma("unroll") for (int k = 0; k < 2; ++k) \
;         acc[ai][bj][m][n] = __builtin_amdgcn_mfma_f32_16x16x32_bf16(Bt[n][k], At[m][k], acc[ai][bj][m][n], 0, 0, 0); __builtin_amdgcn_s_setprio(0); } while (0)
; #define PG8_WAIT_V(n) asm volatile("s_waitcnt vmcnt(" #n ")" ::: "memory")
; #define PG8_WAIT_L(n) asm volatile("s_waitcnt lgkmcnt(" #n ")" ::: "memory")
; #define PG8_BAR __builtin_amdgcn_s_barrier()
; #define PG8_SCHED __builtin_amdgcn_sched_barrier(0)
; template <class Epi, class Map>
; __device__ __forceinline__ void gemm_phase(LAS unsigned char* lds, const Gemm g, const Sched<Map>& S, const Epi& E) {
;     ...
;             PG8_LDA(At, 1, 1); PG8_STAGE(PG8_SB(1, 0), b3, voffB); PG8_STAGE(PG8_SB(1, 1), b3 + hstepB, voffB); PG8_STAGE(PG8_SA(1, 0), a3, voffA);
;             PG8_WAIT_V(8); PG8_WAIT_L(0); PG8_BAR; PG8_MMA(1, 0, At, B0); PG8_MMA(1, 1, At, B1); PG8_BAR; PG8_SCHED;
;         }
;         if (wr == 0) PG8_BAR;
	s_add_i32 s50, s62, s5
	v_lshl_add_u64 v[136:137], v[136:137], 0, s[82:83]
	s_mov_b32 m0, s50
	ds_read_b128 v[208:211], v171 offset:49152
	ds_read_b128 v[212:215], v171 offset:50176
	ds_read_b128 v[216:219], v171 offset:51200
	ds_read_b128 v[220:223], v171 offset:52224
	ds_read_b128 v[224:227], v171 offset:53248
	ds_read_b128 v[228:231], v171 offset:54272
	ds_read_b128 v[232:235], v171 offset:55296
	ds_read_b128 v[236:239], v171 offset:56320
	global_load_lds_dwordx4 v[136:137], off
	s_add_i32 m0, s50, 0x2000
	s_add_u32 s48, s48, 0x80080
	v_lshl_add_u64 v[136:137], v[166:167], 0, s[82:83]
	s_addc_u32 s49, s49, 0
	s_add_i32 s50, s63, s5
	global_load_lds_dwordx4 v[136:137], off
	v_lshl_add_u64 v[136:137], s[48:49], 0, v[144:145]
	s_mov_b32 m0, s50
	s_nop 0
	global_load_lds_dwordx4 v[136:137], off
	v_lshl_add_u64 v[136:137], s[48:49], 0, v[142:143]
	s_add_i32 m0, s50, 0x2000
	s_nop 0
	global_load_lds_dwordx4 v[136:137], off
	v_lshl_add_u64 v[136:137], v[180:181], 0, s[82:83]
	s_mov_b32 m0, s14
	s_nop 0
	global_load_lds_dwordx4 v[136:137], off
	v_lshl_add_u64 v[136:137], v[240:241], 0, s[82:83]
	s_mov_b32 m0, s15
	s_nop 0
	global_load_lds_dwordx4 v[136:137], off
	s_waitcnt vmcnt(8)
	s_waitcnt lgkmcnt(0)
	s_barrier
	s_waitcnt lgkmcnt(0)
	v_mfma_f32_16x16x32_bf16 v[60:63], v[132:135], v[208:211], v[60:63]
	v_mfma_f32_16x16x32_bf16 v[56:59], v[172:175], v[208:211], v[56:59]
	v_mfma_f32_16x16x32_bf16 v[44:47], v[132:135], v[216:219], v[44:47]
	v_mfma_f32_16x16x32_bf16 v[40:43], v[172:175], v[216:219], v[40:43]
	v_mfma_f32_16x16x32_bf16 v[28:31], v[132:135], v[224:227], v[28:31]
	v_mfma_f32_16x16x32_bf16 v[24:27], v[172:175], v[224:227], v[24:27]
	v_mfma_f32_16x16x32_bf16 v[12:15], v[132:135], v[232:235], v[12:15]
	v_mfma_f32_16x16x32_bf16 v[8:11], v[172:175], v[232:235], v[8:11]
	v_mfma_f32_16x16x32_bf16 v[60:63], v[162:165], v[212:215], v[60:63]
	v_mfma_f32_16x16x32_bf16 v[56:59], v[176:179], v[212:215], v[56:59]
	v_mfma_f32_16x16x32_bf16 v[44:47], v[162:165], v[220:223], v[44:47]
	v_mfma_f32_16x16x32_bf16 v[40:43], v[176:179], v[220:223], v[40:43]
	v_mfma_f32_16x16x32_bf16 v[28:31], v[162:165], v[228:231], v[28:31]
	v_mfma_f32_16x16x32_bf16 v[24:27], v[176:179], v[228:231], v[24:27]
	v_mfma_f32_16x16x32_bf16 v[12:15], v[162:165], v[236:239], v[12:15]
	v_mfma_f32_16x16x32_bf16 v[8:11], v[176:179], v[236:239], v[8:11]
	v_mfma_f32_16x16x32_bf16 v[52:55], v[192:195], v[208:211], v[52:55]
	v_mfma_f32_16x16x32_bf16 v[48:51], v[200:203], v[208:211], v[48:51]
	v_mfma_f32_16x16x32_bf16 v[36:39], v[192:195], v[216:219], v[36:39]
	v_mfma_f32_16x16x32_bf16 v[32:35], v[200:203], v[216:219], v[32:35]
	v_mfma_f32_16x16x32_bf16 v[20:23], v[192:195], v[224:227], v[20:23]
	v_mfma_f32_16x16x32_bf16 v[16:19], v[200:203], v[224:227], v[16:19]
	v_mfma_f32_16x16x32_bf16 v[4:7], v[192:195], v[232:235], v[4:7]
	v_mfma_f32_16x16x32_bf16 v[0:3], v[200:203], v[232:235], v[0:3]
	v_mfma_f32_16x16x32_bf16 v[52:55], v[196:199], v[212:215], v[52:55]
	v_mfma_f32_16x16x32_bf16 v[48:51], v[204:207], v[212:215], v[48:51]
	v_mfma_f32_16x16x32_bf16 v[36:39], v[196:199], v[220:223], v[36:39]
	v_mfma_f32_16x16x32_bf16 v[32:35], v[204:207], v[220:223], v[32:35]
	v_mfma_f32_16x16x32_bf16 v[20:23], v[196:199], v[228:231], v[20:23]
	v_mfma_f32_16x16x32_bf16 v[16:19], v[204:207], v[228:231], v[16:19]
	v_mfma_f32_16x16x32_bf16 v[4:7], v[196:199], v[236:239], v[4:7]
	v_mfma_f32_16x16x32_bf16 v[0:3], v[204:207], v[236:239], v[0:3]
	s_barrier
	s_add_i32 s67, s67, 2
	s_add_u32 s46, s46, 0x100
	s_addc_u32 s47, s47, 0
	s_cmp_gt_u32 s67, 29
	s_cbranch_scc0 .LBB0_223
	s_and_b64 vcc, exec, s[28:29]
	s_cbranch_vccz .LBB0_226
	s_barrier

; #define PG8_STAGE(bufoff, gbase, voff) do { _Pragma("unroll") for (int _i = 0; _i < 2; ++_i) \
;         __builtin_amdgcn_global_load_lds((const unsigned*)((const char*)(gbase) + (voff)[_i]), (LAS unsigned*)(lds + (bufoff) + ldsw + _i * 8192), 16, 0, 0); } while (0)
; #define PG8_LDA(dst, b, h) do { _Pragma("unroll") for (int m = 0; m < 4; ++m) _Pragma("unroll") for (int k = 0; k < 2; ++k) dst[m][k] = *(const LAS bf16x8*)(lds + PG8_SA(b, h) + aoff + m * 2048 + k * 1024); } while (0)
; #define PG8_LDB(dst, b, h) do { _Pragma("unroll") for (int n = 0; n < 2; ++n) _Pragma("unroll") for (int k = 0; k < 2; ++k) dst[n][k] = *(const LAS bf16x8*)(lds + PG8_SB(b, h) + boff + n * 2048 + k * 1024); } while (0)
; #define PG8_MMA(ai, bj, At, Bt) do { __builtin_amdgcn_s_setprio(1); _Pragma("unroll") for (int m = 0; m < 4; ++m) _Pragma("unroll") for (int n = 0; n < 2; ++n) _Pragma("unroll") for (int k = 0; k < 2; ++k) \
;         acc[ai][bj][m][n] = __builtin_amdgcn_mfma_f32_16x16x32_bf16(Bt[n][k], At[m][k], acc[ai][bj][m][n], 0, 0, 0); __builtin_amdgcn_s_setprio(0); } while (0)
; #define PG8_WAIT_V(n) asm volatile("s_waitcnt vmcnt(" #n ")" ::: "memory")
; #define PG8_WAIT_L(n) asm volatile("s_waitcnt lgkmcnt(" #n ")" ::: "memory")
; #define PG8_BAR __builtin_amdgcn_s_barrier()
; #define PG8_SCHED __builtin_amdgcn_sched_barrier(0)
; template <class Epi, class Map>
; __device__ __forceinline__ void gemm_phase(LAS unsigned char* lds, const Gemm g, const Sched<Map>& S, const Epi& E) {
;     ...
;         for (int t = 0; t < nt; t += 2) {
;             const bool last = (t == nt - 2);
;             const char* a1 = cA + (size_t)(t + 1) * kstep;
;             const char* a2 = last ? nA : cA + (size_t)(t + 2) * kstep; const char* b2 = last ? nB : cB + (size_t)(t + 2) * kstep;
;             const char* a3 = a2 + kstep; const char* b3 = b2 + kstep;
;             PG8_LDB(B0, 0, 0); PG8_LDB(B1, 0, 1); PG8_SCHED; PG8_LDA(At, 0, 0); PG8_STAGE(PG8_SA(1, 1), a1 + hstepA, voffA);
;             PG8_WAIT_V(8); PG8_WAIT_L(0); PG8_BAR; PG8_MMA(0, 0, At, B0); PG8_MMA(0, 1, At, B1); PG8_BAR; PG8_SCHED;
.LBB0_261:
	s_add_u32 s36, s34, 0xfff80080
	s_addc_u32 s37, s35, -1
	s_add_i32 s54, 0, 0x10000
	s_cmp_eq_u32 s51, 28
	s_cselect_b32 s37, s25, s37
	s_cselect_b32 s36, s46, s36
	v_add_u32_e32 v138, s54, v142
	s_cselect_b32 s53, s47, s50
	s_cselect_b32 s52, s48, s49
	s_add_i32 s55, 0, 0x14000
	ds_read_b128 v[158:161], v138
	ds_read_b128 v[162:165], v138 offset:1024
	ds_read_b128 v[166:169], v138 offset:2048
	ds_read_b128 v[170:173], v138 offset:3072
	v_add_u32_e32 v138, s55, v142
	ds_read_b128 v[174:177], v138
	ds_read_b128 v[178:181], v138 offset:1024
	ds_read_b128 v[192:195], v138 offset:2048
	ds_read_b128 v[196:199], v138 offset:3072
	v_lshl_add_u64 v[138:139], s[34:35], 0, v[134:135]
	s_add_i32 m0, s7, 0xc000
	ds_read_b128 v[200:203], v143
	ds_read_b128 v[204:207], v143 offset:1024
	ds_read_b128 v[208:211], v143 offset:2048
	ds_read_b128 v[212:215], v143 offset:3072
	ds_read_b128 v[216:219], v143 offset:4096
	ds_read_b128 v[220:223], v143 offset:5120
	ds_read_b128 v[224:227], v143 offset:6144
	ds_read_b128 v[228:231], v143 offset:7168
	global_load_lds_dwordx4 v[138:139], off
	v_lshl_add_u64 v[138:139], s[34:35], 0, v[136:137]
	s_add_i32 m0, s7, 0xe000
	s_nop 0
	global_load_lds_dwordx4 v[138:139], off
	s_waitcnt vmcnt(8)
	s_waitcnt lgkmcnt(0)
	s_barrier
	s_waitcnt lgkmcnt(0)
	v_mfma_f32_16x16x32_bf16 v[124:127], v[158:161], v[200:203], v[124:127]
	v_mfma_f32_16x16x32_bf16 v[120:123], v[166:169], v[200:203], v[120:123]
	v_mfma_f32_16x16x32_bf16 v[116:119], v[158:161], v[208:211], v[116:119]
	v_mfma_f32_16x16x32_bf16 v[108:111], v[166:169], v[208:211], v[108:111]
	v_mfma_f32_16x16x32_bf16 v[100:103], v[158:161], v[216:219], v[100:103]
	v_mfma_f32_16x16x32_bf16 v[92:95], v[166:169], v[216:219], v[92:95]
	v_mfma_f32_16x16x32_bf16 v[84:87], v[158:161], v[224:227], v[84:87]
	v_mfma_f32_16x16x32_bf16 v[76:79], v[166:169], v[224:227], v[76:79]
	v_mfma_f32_16x16x32_bf16 v[124:127], v[162:165], v[204:207], v[124:127]
	v_mfma_f32_16x16x32_bf16 v[120:123], v[170:173], v[204:207], v[120:123]
	v_mfma_f32_16x16x32_bf16 v[116:119], v[162:165], v[212:215], v[116:119]
	v_mfma_f32_16x16x32_bf16 v[108:111], v[170:173], v[212:215], v[108:111]
	v_mfma_f32_16x16x32_bf16 v[100:103], v[162:165], v[220:223], v[100:103]
	v_mfma_f32_16x16x32_bf16 v[92:95], v[170:173], v[220:223], v[92:95]
	v_mfma_f32_16x16x32_bf16 v[84:87], v[162:165], v[228:231], v[84:87]
	v_mfma_f32_16x16x32_bf16 v[76:79], v[170:173], v[228:231], v[76:79]
	v_mfma_f32_16x16x32_bf16 v[112:115], v[174:177], v[200:203], v[112:115]
	v_mfma_f32_16x16x32_bf16 v[104:107], v[192:195], v[200:203], v[104:107]
	v_mfma_f32_16x16x32_bf16 v[96:99], v[174:177], v[208:211], v[96:99]
	v_mfma_f32_16x16x32_bf16 v[88:91], v[192:195], v[208:211], v[88:91]
	v_mfma_f32_16x16x32_bf16 v[80:83], v[174:177], v[216:219], v[80:83]
	v_mfma_f32_16x16x32_bf16 v[72:75], v[192:195], v[216:219], v[72:75]
	v_mfma_f32_16x16x32_bf16 v[68:71], v[174:177], v[224:227], v[68:71]
	v_mfma_f32_16x16x32_bf16 v[64:67], v[192:195], v[224:227], v[64:67]
	v_mfma_f32_16x16x32_bf16 v[112:115], v[178:181], v[204:207], v[112:115]
	v_mfma_f32_16x16x32_bf16 v[104:107], v[196:199], v[204:207], v[104:107]
	v_mfma_f32_16x16x32_bf16 v[96:99], v[178:181], v[212:215], v[96:99]
	v_mfma_f32_16x16x32_bf16 v[88:91], v[196:199], v[212:215], v[88:91]
	v_mfma_f32_16x16x32_bf16 v[80:83], v[178:181], v[220:223], v[80:83]
	v_mfma_f32_16x16x32_bf16 v[72:75], v[196:199], v[220:223], v[72:75]
	v_mfma_f32_16x16x32_bf16 v[68:71], v[178:181], v[228:231], v[68:71]
	v_mfma_f32_16x16x32_bf16 v[64:67], v[196:199], v[228:231], v[64:67]
	s_barrier
	s_add_i32 s54, s54, s6
	v_lshl_add_u64 v[138:139], s[52:53], 0, v[144:145]
	s_mov_b32 m0, s54
	ds_read_b128 v[200:203], v143 offset:16384
	ds_read_b128 v[204:207], v143 offset:17408
	ds_read_b128 v[208:211], v143 offset:18432
	ds_read_b128 v[212:215], v143 offset:19456
	ds_read_b128 v[216:219], v143 offset:20480
	ds_read_b128 v[220:223], v143 offset:21504
	ds_read_b128 v[224:227], v143 offset:22528
	ds_read_b128 v[228:231], v143 offset:23552
	global_load_lds_dwordx4 v[138:139], off
	s_add_i32 m0, s54, 0x2000
	v_lshl_add_u64 v[232:233], s[52:53], 0, v[128:129]
	s_add_u32 s52, s52, s5
	s_addc_u32 s53, s53, 0
	s_add_i32 s54, s55, s6
	global_load_lds_dwordx4 v[232:233], off
	v_lshl_add_u64 v[234:235], s[52:53], 0, v[144:145]
	s_mov_b32 m0, s54
	v_lshl_add_u64 v[236:237], s[52:53], 0, v[128:129]
	global_load_lds_dwordx4 v[234:235], off
	s_add_i32 m0, s54, 0x2000
	v_lshl_add_u64 v[238:239], s[36:37], 0, v[132:133]
	global_load_lds_dwordx4 v[236:237], off
	s_mov_b32 m0, s7
	v_lshl_add_u64 v[240:241], s[36:37], 0, v[130:131]
	global_load_lds_dwordx4 v[238:239], off
	s_mov_b32 m0, s8
	s_nop 0
	global_load_lds_dwordx4 v[240:241], off
	s_waitcnt vmcnt(8)
	s_waitcnt lgkmcnt(0)
	s_barrier
; #define PG8_STAGE(bufoff, gbase, voff) do { _Pragma("unroll") for (int _i = 0; _i < 2; ++_i) \
;         __builtin_amdgcn_global_load_lds((const unsigned*)((const char*)(gbase) + (voff)[_i]), (LAS unsigned*)(lds + (bufoff) + ldsw + _i * 8192), 16, 0, 0); } while (0)
; #define PG8_LDA(dst, b, h) do { _Pragma("unroll") for (int m = 0; m < 4; ++m) _Pragma("unroll") for (int k = 0; k < 2; ++k) dst[m][k] = *(const LAS bf16x8*)(lds + PG8_SA(b, h) + aoff + m * 2048 + k * 1024); } while (0)
; #define PG8_LDB(dst, b, h) do { _Pragma("unroll") for (int n = 0; n < 2; ++n) _Pragma("unroll") for (int k = 0; k < 2; ++k) dst[n][k] = *(const LAS bf16x8*)(lds + PG8_SB(b, h) + boff + n * 2048 + k * 1024); } while (0)
; #define PG8_MMA(ai, bj, At, Bt) do { __builtin_amdgcn_s_setprio(1); _Pragma("unroll") for (int m = 0; m < 4; ++m) _Pragma("unroll") for (int n = 0; n < 2; ++n) _Pragma("unroll") for (int k = 0; k < 2; ++k) \
;         acc[ai][bj][m][n] = __builtin_amdgcn_mfma_f32_16x16x32_bf16(Bt[n][k], At[m][k], acc[ai][bj][m][n], 0, 0, 0); __builtin_amdgcn_s_setprio(0); } while (0)
; #define PG8_WAIT_V(n) asm volatile("s_waitcnt vmcnt(" #n ")" ::: "memory")
; #define PG8_WAIT_L(n) asm volatile("s_waitcnt lgkmcnt(" #n ")" ::: "memory")
; #define PG8_BAR __builtin_amdgcn_s_barrier()
; #define PG8_SCHED __builtin_amdgcn_sched_barrier(0)
; template <class Epi, class Map>
; __device__ __forceinline__ void gemm_phase(LAS unsigned char* lds, const Gemm g, const Sched<Map>& S, const Epi& E) {
;     ...
;             PG8_LDA(At, 0, 1); PG8_STAGE(PG8_SB(0, 0), b2, voffB); PG8_STAGE(PG8_SB(0, 1), b2 + hstepB, voffB); PG8_STAGE(PG8_SA(0, 0), a2, voffA);
;             PG8_WAIT_V(8); PG8_WAIT_L(0); PG8_BAR; PG8_MMA(1, 0, At, B0); PG8_MMA(1, 1, At, B1); PG8_BAR; PG8_SCHED;
;             PG8_LDB(B0, 1, 0); PG8_LDB(B1, 1, 1); PG8_SCHED; PG8_LDA(At, 1, 0); PG8_STAGE(PG8_SA(0, 1), a2 + hstepA, voffA);
;             PG8_WAIT_V(8); PG8_WAIT_L(0); PG8_BAR; PG8_MMA(0, 0, At, B0); PG8_MMA(0, 1, At, B1); PG8_BAR; PG8_SCHED;
	s_waitcnt lgkmcnt(0)
	v_mfma_f32_16x16x32_bf16 v[60:63], v[158:161], v[200:203], v[60:63]
	v_mfma_f32_16x16x32_bf16 v[56:59], v[166:169], v[200:203], v[56:59]
	v_mfma_f32_16x16x32_bf16 v[52:55], v[158:161], v[208:211], v[52:55]
	v_mfma_f32_16x16x32_bf16 v[44:47], v[166:169], v[208:211], v[44:47]
	v_mfma_f32_16x16x32_bf16 v[36:39], v[158:161], v[216:219], v[36:39]
	v_mfma_f32_16x16x32_bf16 v[28:31], v[166:169], v[216:219], v[28:31]
	v_mfma_f32_16x16x32_bf16 v[20:23], v[158:161], v[224:227], v[20:23]
	v_mfma_f32_16x16x32_bf16 v[12:15], v[166:169], v[224:227], v[12:15]
	v_mfma_f32_16x16x32_bf16 v[60:63], v[162:165], v[204:207], v[60:63]
	v_mfma_f32_16x16x32_bf16 v[56:59], v[170:173], v[204:207], v[56:59]
	v_mfma_f32_16x16x32_bf16 v[52:55], v[162:165], v[212:215], v[52:55]
	v_mfma_f32_16x16x32_bf16 v[44:47], v[170:173], v[212:215], v[44:47]
	v_mfma_f32_16x16x32_bf16 v[36:39], v[162:165], v[220:223], v[36:39]
	v_mfma_f32_16x16x32_bf16 v[28:31], v[170:173], v[220:223], v[28:31]
	v_mfma_f32_16x16x32_bf16 v[20:23], v[162:165], v[228:231], v[20:23]
	v_mfma_f32_16x16x32_bf16 v[12:15], v[170:173], v[228:231], v[12:15]
	v_mfma_f32_16x16x32_bf16 v[48:51], v[174:177], v[200:203], v[48:51]
	v_mfma_f32_16x16x32_bf16 v[40:43], v[192:195], v[200:203], v[40:43]
	v_mfma_f32_16x16x32_bf16 v[32:35], v[174:177], v[208:211], v[32:35]
	v_mfma_f32_16x16x32_bf16 v[24:27], v[192:195], v[208:211], v[24:27]
	v_mfma_f32_16x16x32_bf16 v[16:19], v[174:177], v[216:219], v[16:19]
	v_mfma_f32_16x16x32_bf16 v[8:11], v[192:195], v[216:219], v[8:11]
	v_mfma_f32_16x16x32_bf16 v[4:7], v[174:177], v[224:227], v[4:7]
	v_mfma_f32_16x16x32_bf16 v[0:3], v[192:195], v[224:227], v[0:3]
	v_mfma_f32_16x16x32_bf16 v[48:51], v[178:181], v[204:207], v[48:51]
	v_mfma_f32_16x16x32_bf16 v[40:43], v[196:199], v[204:207], v[40:43]
	v_mfma_f32_16x16x32_bf16 v[32:35], v[178:181], v[212:215], v[32:35]
	v_mfma_f32_16x16x32_bf16 v[24:27], v[196:199], v[212:215], v[24:27]
	v_mfma_f32_16x16x32_bf16 v[16:19], v[178:181], v[220:223], v[16:19]
	v_mfma_f32_16x16x32_bf16 v[8:11], v[196:199], v[220:223], v[8:11]
	v_mfma_f32_16x16x32_bf16 v[4:7], v[178:181], v[228:231], v[4:7]
	v_mfma_f32_16x16x32_bf16 v[0:3], v[196:199], v[228:231], v[0:3]
	s_barrier
	s_add_i32 s52, 0, 0x18000
	s_add_i32 s53, 0, 0x1c000
	v_add_u32_e32 v170, s52, v142
	v_add_u32_e32 v196, s53, v142
	ds_read_b128 v[158:161], v170
	ds_read_b128 v[162:165], v170 offset:1024
	ds_read_b128 v[166:169], v170 offset:2048
	ds_read_b128 v[170:173], v170 offset:3072
	ds_read_b128 v[174:177], v196
	ds_read_b128 v[178:181], v196 offset:1024
	ds_read_b128 v[192:195], v196 offset:2048
	ds_read_b128 v[196:199], v196 offset:3072
	s_add_u32 s36, s36, 0x80000
	s_addc_u32 s37, s37, 0
	s_mov_b32 m0, s9
	v_lshl_add_u64 v[242:243], s[36:37], 0, v[132:133]
	ds_read_b128 v[200:203], v143 offset:32768
	ds_read_b128 v[204:207], v143 offset:33792
	ds_read_b128 v[208:211], v143 offset:34816
	ds_read_b128 v[212:215], v143 offset:35840
	ds_read_b128 v[216:219], v143 offset:36864
	ds_read_b128 v[220:223], v143 offset:37888
	ds_read_b128 v[224:227], v143 offset:38912
	ds_read_b128 v[228:231], v143 offset:39936
	global_load_lds_dwordx4 v[242:243], off
	v_lshl_add_u64 v[242:243], s[36:37], 0, v[130:131]
	s_mov_b32 m0, s10
	s_nop 0
	global_load_lds_dwordx4 v[242:243], off
	s_waitcnt vmcnt(8)
	s_waitcnt lgkmcnt(0)
	s_barrier
	s_waitcnt lgkmcnt(0)
	v_mfma_f32_16x16x32_bf16 v[124:127], v[158:161], v[200:203], v[124:127]
	v_mfma_f32_16x16x32_bf16 v[120:123], v[166:169], v[200:203], v[120:123]
	v_mfma_f32_16x16x32_bf16 v[116:119], v[158:161], v[208:211], v[116:119]
	v_mfma_f32_16x16x32_bf16 v[108:111], v[166:169], v[208:211], v[108:111]
	v_mfma_f32_16x16x32_bf16 v[100:103], v[158:161], v[216:219], v[100:103]
	v_mfma_f32_16x16x32_bf16 v[92:95], v[166:169], v[216:219], v[92:95]
	v_mfma_f32_16x16x32_bf16 v[84:87], v[158:161], v[224:227], v[84:87]
	v_mfma_f32_16x16x32_bf16 v[76:79], v[166:169], v[224:227], v[76:79]
	v_mfma_f32_16x16x32_bf16 v[124:127], v[162:165], v[204:207], v[124:127]
	v_mfma_f32_16x16x32_bf16 v[120:123], v[170:173], v[204:207], v[120:123]
	v_mfma_f32_16x16x32_bf16 v[116:119], v[162:165], v[212:215], v[116:119]
	v_mfma_f32_16x16x32_bf16 v[108:111], v[170:173], v[212:215], v[108:111]
	v_mfma_f32_16x16x32_bf16 v[100:103], v[162:165], v[220:223], v[100:103]
	v_mfma_f32_16x16x32_bf16 v[92:95], v[170:173], v[220:223], v[92:95]
	v_mfma_f32_16x16x32_bf16 v[84:87], v[162:165], v[228:231], v[84:87]
	v_mfma_f32_16x16x32_bf16 v[76:79], v[170:173], v[228:231], v[76:79]
	v_mfma_f32_16x16x32_bf16 v[112:115], v[174:177], v[200:203], v[112:115]
	v_mfma_f32_16x16x32_bf16 v[104:107], v[192:195], v[200:203], v[104:107]
	v_mfma_f32_16x16x32_bf16 v[96:99], v[174:177], v[208:211], v[96:99]
	v_mfma_f32_16x16x32_bf16 v[88:91], v[192:195], v[208:211], v[88:91]
	v_mfma_f32_16x16x32_bf16 v[80:83], v[174:177], v[216:219], v[80:83]
	v_mfma_f32_16x16x32_bf16 v[72:75], v[192:195], v[216:219], v[72:75]
	v_mfma_f32_16x16x32_bf16 v[68:71], v[174:177], v[224:227], v[68:71]
	v_mfma_f32_16x16x32_bf16 v[64:67], v[192:195], v[224:227], v[64:67]
	v_mfma_f32_16x16x32_bf16 v[112:115], v[178:181], v[204:207], v[112:115]
	v_mfma_f32_16x16x32_bf16 v[104:107], v[196:199], v[204:207], v[104:107]
	v_mfma_f32_16x16x32_bf16 v[96:99], v[178:181], v[212:215], v[96:99]
	v_mfma_f32_16x16x32_bf16 v[88:91], v[196:199], v[212:215], v[88:91]
	v_mfma_f32_16x16x32_bf16 v[80:83], v[178:181], v[220:223], v[80:83]
	v_mfma_f32_16x16x32_bf16 v[72:75], v[196:199], v[220:223], v[72:75]
	v_mfma_f32_16x16x32_bf16 v[68:71], v[178:181], v[228:231], v[68:71]
	v_mfma_f32_16x16x32_bf16 v[64:67], v[196:199], v[228:231], v[64:67]
	s_barrier
; #define PG8_STAGE(bufoff, gbase, voff) do { _Pragma("unroll") for (int _i = 0; _i < 2; ++_i) \
;         __builtin_amdgcn_global_load_lds((const unsigned*)((const char*)(gbase) + (voff)[_i]), (LAS unsigned*)(lds + (bufoff) + ldsw + _i * 8192), 16, 0, 0); } while (0)
; #define PG8_LDA(dst, b, h) do { _Pragma("unroll") for (int m = 0; m < 4; ++m) _Pragma("unroll") for (int k = 0; k < 2; ++k) dst[m][k] = *(const LAS bf16x8*)(lds + PG8_SA(b, h) + aoff + m * 2048 + k * 1024); } while (0)
; #define PG8_MMA(ai, bj, At, Bt) do { __builtin_amdgcn_s_setprio(1); _Pragma("unroll") for (int m = 0; m < 4; ++m) _Pragma("unroll") for (int n = 0; n < 2; ++n) _Pragma("unroll") for (int k = 0; k < 2; ++k) \
;         acc[ai][bj][m][n] = __builtin_amdgcn_mfma_f32_16x16x32_bf16(Bt[n][k], At[m][k], acc[ai][bj][m][n], 0, 0, 0); __builtin_amdgcn_s_setprio(0); } while (0)
; #define PG8_WAIT_V(n) asm volatile("s_waitcnt vmcnt(" #n ")" ::: "memory")
; #define PG8_WAIT_L(n) asm volatile("s_waitcnt lgkmcnt(" #n ")" ::: "memory")
; #define PG8_BAR __builtin_amdgcn_s_barrier()
; #define PG8_SCHED __builtin_amdgcn_sched_barrier(0)
; template <class Epi, class Map>
; __device__ __forceinline__ void gemm_phase(LAS unsigned char* lds, const Gemm g, const Sched<Map>& S, const Epi& E) {
;     ...
;             PG8_LDA(At, 1, 1); PG8_STAGE(PG8_SB(1, 0), b3, voffB); PG8_STAGE(PG8_SB(1, 1), b3 + hstepB, voffB); PG8_STAGE(PG8_SA(1, 0), a3, voffA);
;             PG8_WAIT_V(8); PG8_WAIT_L(0); PG8_BAR; PG8_MMA(1, 0, At, B0); PG8_MMA(1, 1, At, B1); PG8_BAR; PG8_SCHED;
;         }
;         if (wr == 0) PG8_BAR;
	s_add_i32 s36, s52, s6
	v_lshl_add_u64 v[138:139], v[138:139], 0, s[82:83]
	s_mov_b32 m0, s36
	ds_read_b128 v[200:203], v143 offset:49152
	ds_read_b128 v[204:207], v143 offset:50176
	ds_read_b128 v[208:211], v143 offset:51200
	ds_read_b128 v[212:215], v143 offset:52224
	ds_read_b128 v[216:219], v143 offset:53248
	ds_read_b128 v[220:223], v143 offset:54272
	ds_read_b128 v[224:227], v143 offset:55296
	ds_read_b128 v[228:231], v143 offset:56320
	global_load_lds_dwordx4 v[138:139], off
	v_lshl_add_u64 v[138:139], v[232:233], 0, s[82:83]
	s_add_i32 m0, s36, 0x2000
	s_add_i32 s36, s53, s6
	global_load_lds_dwordx4 v[138:139], off
	v_lshl_add_u64 v[138:139], v[234:235], 0, s[82:83]
	s_mov_b32 m0, s36
	s_nop 0
	global_load_lds_dwordx4 v[138:139], off
	v_lshl_add_u64 v[138:139], v[236:237], 0, s[82:83]
	s_add_i32 m0, s36, 0x2000
	s_nop 0
	global_load_lds_dwordx4 v[138:139], off
	v_lshl_add_u64 v[138:139], v[238:239], 0, s[82:83]
	s_mov_b32 m0, s15
	s_nop 0
	global_load_lds_dwordx4 v[138:139], off
	v_lshl_add_u64 v[138:139], v[240:241], 0, s[82:83]
	s_mov_b32 m0, s33
	s_nop 0
	global_load_lds_dwordx4 v[138:139], off
	s_waitcnt vmcnt(8)
	s_waitcnt lgkmcnt(0)
	s_barrier
	s_waitcnt lgkmcnt(0)
	v_mfma_f32_16x16x32_bf16 v[60:63], v[158:161], v[200:203], v[60:63]
	v_mfma_f32_16x16x32_bf16 v[56:59], v[166:169], v[200:203], v[56:59]
	v_mfma_f32_16x16x32_bf16 v[52:55], v[158:161], v[208:211], v[52:55]
	v_mfma_f32_16x16x32_bf16 v[44:47], v[166:169], v[208:211], v[44:47]
	v_mfma_f32_16x16x32_bf16 v[36:39], v[158:161], v[216:219], v[36:39]
	v_mfma_f32_16x16x32_bf16 v[28:31], v[166:169], v[216:219], v[28:31]
	v_mfma_f32_16x16x32_bf16 v[20:23], v[158:161], v[224:227], v[20:23]
	v_mfma_f32_16x16x32_bf16 v[12:15], v[166:169], v[224:227], v[12:15]
	v_mfma_f32_16x16x32_bf16 v[60:63], v[162:165], v[204:207], v[60:63]
	v_mfma_f32_16x16x32_bf16 v[56:59], v[170:173], v[204:207], v[56:59]
	v_mfma_f32_16x16x32_bf16 v[52:55], v[162:165], v[212:215], v[52:55]
	v_mfma_f32_16x16x32_bf16 v[44:47], v[170:173], v[212:215], v[44:47]
	v_mfma_f32_16x16x32_bf16 v[36:39], v[162:165], v[220:223], v[36:39]
	v_mfma_f32_16x16x32_bf16 v[28:31], v[170:173], v[220:223], v[28:31]
	v_mfma_f32_16x16x32_bf16 v[20:23], v[162:165], v[228:231], v[20:23]
	v_mfma_f32_16x16x32_bf16 v[12:15], v[170:173], v[228:231], v[12:15]
	v_mfma_f32_16x16x32_bf16 v[48:51], v[174:177], v[200:203], v[48:51]
	v_mfma_f32_16x16x32_bf16 v[40:43], v[192:195], v[200:203], v[40:43]
	v_mfma_f32_16x16x32_bf16 v[32:35], v[174:177], v[208:211], v[32:35]
	v_mfma_f32_16x16x32_bf16 v[24:27], v[192:195], v[208:211], v[24:27]
	v_mfma_f32_16x16x32_bf16 v[16:19], v[174:177], v[216:219], v[16:19]
	v_mfma_f32_16x16x32_bf16 v[8:11], v[192:195], v[216:219], v[8:11]
	v_mfma_f32_16x16x32_bf16 v[4:7], v[174:177], v[224:227], v[4:7]
	v_mfma_f32_16x16x32_bf16 v[0:3], v[192:195], v[224:227], v[0:3]
	v_mfma_f32_16x16x32_bf16 v[48:51], v[178:181], v[204:207], v[48:51]
	v_mfma_f32_16x16x32_bf16 v[40:43], v[196:199], v[204:207], v[40:43]
	v_mfma_f32_16x16x32_bf16 v[32:35], v[178:181], v[212:215], v[32:35]
	v_mfma_f32_16x16x32_bf16 v[24:27], v[196:199], v[212:215], v[24:27]
	v_mfma_f32_16x16x32_bf16 v[16:19], v[178:181], v[220:223], v[16:19]
	v_mfma_f32_16x16x32_bf16 v[8:11], v[196:199], v[220:223], v[8:11]
	v_mfma_f32_16x16x32_bf16 v[4:7], v[178:181], v[228:231], v[4:7]
	v_mfma_f32_16x16x32_bf16 v[0:3], v[196:199], v[228:231], v[0:3]
	s_barrier
	s_add_i32 s51, s51, 2
	s_add_u32 s34, s34, 0x100
	s_addc_u32 s35, s35, 0
	s_add_u32 s49, s49, 0x100
	s_addc_u32 s50, s50, 0
	s_cmp_gt_u32 s51, 29
	s_cbranch_scc0 .LBB0_261
	s_and_b64 vcc, exec, s[20:21]
	s_cbranch_vccz .LBB0_264
	s_barrier

; #define PG8_STAGE(bufoff, gbase, voff) do { _Pragma("unroll") for (int _i = 0; _i < 2; ++_i) \
;         __builtin_amdgcn_global_load_lds((const unsigned*)((const char*)(gbase) + (voff)[_i]), (LAS unsigned*)(lds + (bufoff) + ldsw + _i * 8192), 16, 0, 0); } while (0)
; #define PG8_LDA(dst, b, h) do { _Pragma("unroll") for (int m = 0; m < 4; ++m) _Pragma("unroll") for (int k = 0; k < 2; ++k) dst[m][k] = *(const LAS bf16x8*)(lds + PG8_SA(b, h) + aoff + m * 2048 + k * 1024); } while (0)
; #define PG8_LDB(dst, b, h) do { _Pragma("unroll") for (int n = 0; n < 2; ++n) _Pragma("unroll") for (int k = 0; k < 2; ++k) dst[n][k] = *(const LAS bf16x8*)(lds + PG8_SB(b, h) + boff + n * 2048 + k * 1024); } while (0)
; #define PG8_MMA(ai, bj, At, Bt) do { __builtin_amdgcn_s_setprio(1); _Pragma("unroll") for (int m = 0; m < 4; ++m) _Pragma("unroll") for (int n = 0; n < 2; ++n) _Pragma("unroll") for (int k = 0; k < 2; ++k) \
;         acc[ai][bj][m][n] = __builtin_amdgcn_mfma_f32_16x16x32_bf16(Bt[n][k], At[m][k], acc[ai][bj][m][n], 0, 0, 0); __builtin_amdgcn_s_setprio(0); } while (0)
; #define PG8_WAIT_V(n) asm volatile("s_waitcnt vmcnt(" #n ")" ::: "memory")
; #define PG8_WAIT_L(n) asm volatile("s_waitcnt lgkmcnt(" #n ")" ::: "memory")
; #define PG8_BAR __builtin_amdgcn_s_barrier()
; #define PG8_SCHED __builtin_amdgcn_sched_barrier(0)
; template <class Epi, class Map>
; __device__ __forceinline__ void gemm_phase(LAS unsigned char* lds, const Gemm g, const Sched<Map>& S, const Epi& E) {
;     ...
;         for (int t = 0; t < nt; t += 2) {
;             const bool last = (t == nt - 2);
;             const char* a1 = cA + (size_t)(t + 1) * kstep;
;             const char* a2 = last ? nA : cA + (size_t)(t + 2) * kstep; const char* b2 = last ? nB : cB + (size_t)(t + 2) * kstep;
;             const char* a3 = a2 + kstep; const char* b3 = b2 + kstep;
;             PG8_LDB(B0, 0, 0); PG8_LDB(B1, 0, 1); PG8_SCHED; PG8_LDA(At, 0, 0); PG8_STAGE(PG8_SA(1, 1), a1 + hstepA, voffA);
;             PG8_WAIT_V(8); PG8_WAIT_L(0); PG8_BAR; PG8_MMA(0, 0, At, B0); PG8_MMA(0, 1, At, B1); PG8_BAR; PG8_SCHED;
.LBB0_405:
	s_add_u32 s30, s28, 0xfff80080
	s_addc_u32 s31, s29, -1
	s_add_i32 s47, 0, 0x10000
	s_cmp_eq_u32 s46, 28
	s_cselect_b32 s35, s40, s31
	s_cselect_b32 s34, s41, s30
	s_cselect_b32 s31, s42, s45
	s_cselect_b32 s30, s43, s44
	s_add_i32 s50, 0, 0x14000
	v_add_u32_e32 v108, s47, v173
	v_add_u32_e32 v170, s50, v173
	ds_read_b128 v[64:67], v108
	ds_read_b128 v[68:71], v108 offset:1024
	ds_read_b128 v[72:75], v108 offset:2048
	ds_read_b128 v[108:111], v108 offset:3072
	ds_read_b128 v[166:169], v170
	ds_read_b128 v[176:179], v170 offset:1024
	ds_read_b128 v[192:195], v170 offset:2048
	ds_read_b128 v[196:199], v170 offset:3072
	v_lshl_add_u64 v[170:171], s[28:29], 0, v[162:163]
	s_add_i32 m0, s1, 0xc000
	ds_read_b128 v[200:203], v174
	ds_read_b128 v[204:207], v174 offset:1024
	ds_read_b128 v[208:211], v174 offset:2048
	ds_read_b128 v[212:215], v174 offset:3072
	ds_read_b128 v[216:219], v174 offset:4096
	ds_read_b128 v[220:223], v174 offset:5120
	ds_read_b128 v[224:227], v174 offset:6144
	ds_read_b128 v[228:231], v174 offset:7168
	global_load_lds_dwordx4 v[170:171], off
	v_lshl_add_u64 v[170:171], s[28:29], 0, v[164:165]
	s_add_i32 m0, s1, 0xe000
	s_nop 0
	global_load_lds_dwordx4 v[170:171], off
	s_waitcnt vmcnt(8)
	s_waitcnt lgkmcnt(0)
	s_barrier
	s_waitcnt lgkmcnt(0)
	v_mfma_f32_16x16x32_bf16 v[140:143], v[64:67], v[200:203], v[140:143]
	v_mfma_f32_16x16x32_bf16 v[136:139], v[72:75], v[200:203], v[136:139]
	v_mfma_f32_16x16x32_bf16 v[132:135], v[64:67], v[208:211], v[132:135]
	v_mfma_f32_16x16x32_bf16 v[128:131], v[72:75], v[208:211], v[128:131]
	v_mfma_f32_16x16x32_bf16 v[104:107], v[64:67], v[216:219], v[104:107]
	v_mfma_f32_16x16x32_bf16 v[100:103], v[72:75], v[216:219], v[100:103]
	v_mfma_f32_16x16x32_bf16 v[96:99], v[64:67], v[224:227], v[96:99]
	v_mfma_f32_16x16x32_bf16 v[92:95], v[72:75], v[224:227], v[92:95]
	v_mfma_f32_16x16x32_bf16 v[140:143], v[68:71], v[204:207], v[140:143]
	v_mfma_f32_16x16x32_bf16 v[136:139], v[108:111], v[204:207], v[136:139]
	v_mfma_f32_16x16x32_bf16 v[132:135], v[68:71], v[212:215], v[132:135]
	v_mfma_f32_16x16x32_bf16 v[128:131], v[108:111], v[212:215], v[128:131]
	v_mfma_f32_16x16x32_bf16 v[104:107], v[68:71], v[220:223], v[104:107]
	v_mfma_f32_16x16x32_bf16 v[100:103], v[108:111], v[220:223], v[100:103]
	v_mfma_f32_16x16x32_bf16 v[96:99], v[68:71], v[228:231], v[96:99]
	v_mfma_f32_16x16x32_bf16 v[92:95], v[108:111], v[228:231], v[92:95]
	v_mfma_f32_16x16x32_bf16 v[124:127], v[166:169], v[200:203], v[124:127]
	v_mfma_f32_16x16x32_bf16 v[120:123], v[192:195], v[200:203], v[120:123]
	v_mfma_f32_16x16x32_bf16 v[116:119], v[166:169], v[208:211], v[116:119]
	v_mfma_f32_16x16x32_bf16 v[112:115], v[192:195], v[208:211], v[112:115]
	v_mfma_f32_16x16x32_bf16 v[88:91], v[166:169], v[216:219], v[88:91]
	v_mfma_f32_16x16x32_bf16 v[84:87], v[192:195], v[216:219], v[84:87]
	v_mfma_f32_16x16x32_bf16 v[80:83], v[166:169], v[224:227], v[80:83]
	v_mfma_f32_16x16x32_bf16 v[76:79], v[192:195], v[224:227], v[76:79]
	v_mfma_f32_16x16x32_bf16 v[124:127], v[176:179], v[204:207], v[124:127]
	v_mfma_f32_16x16x32_bf16 v[120:123], v[196:199], v[204:207], v[120:123]
	v_mfma_f32_16x16x32_bf16 v[116:119], v[176:179], v[212:215], v[116:119]
	v_mfma_f32_16x16x32_bf16 v[112:115], v[196:199], v[212:215], v[112:115]
	v_mfma_f32_16x16x32_bf16 v[88:91], v[176:179], v[220:223], v[88:91]
	v_mfma_f32_16x16x32_bf16 v[84:87], v[196:199], v[220:223], v[84:87]
	v_mfma_f32_16x16x32_bf16 v[80:83], v[176:179], v[228:231], v[80:83]
	v_mfma_f32_16x16x32_bf16 v[76:79], v[196:199], v[228:231], v[76:79]
	s_barrier
	s_add_i32 s47, s47, s0
	v_lshl_add_u64 v[170:171], s[30:31], 0, v[144:145]
	s_mov_b32 m0, s47
	ds_read_b128 v[200:203], v174 offset:16384
	ds_read_b128 v[204:207], v174 offset:17408
	ds_read_b128 v[208:211], v174 offset:18432
	ds_read_b128 v[212:215], v174 offset:19456
	ds_read_b128 v[216:219], v174 offset:20480
	ds_read_b128 v[220:223], v174 offset:21504
	ds_read_b128 v[224:227], v174 offset:22528
	ds_read_b128 v[228:231], v174 offset:23552
	global_load_lds_dwordx4 v[170:171], off
	s_add_i32 m0, s47, 0x2000
	s_add_u32 s48, s30, 0x80000
	v_lshl_add_u64 v[180:181], s[30:31], 0, v[160:161]
	s_addc_u32 s49, s31, 0
	s_add_i32 s47, s50, s0
	global_load_lds_dwordx4 v[180:181], off
	v_lshl_add_u64 v[232:233], s[48:49], 0, v[144:145]
	s_mov_b32 m0, s47
	v_lshl_add_u64 v[234:235], s[34:35], 0, v[160:161]
	global_load_lds_dwordx4 v[232:233], off
	v_lshl_add_u64 v[232:233], s[48:49], 0, v[160:161]
	s_add_i32 m0, s47, 0x2000
	s_nop 0
	global_load_lds_dwordx4 v[232:233], off
	v_lshl_add_u64 v[232:233], s[34:35], 0, v[144:145]
	s_mov_b32 m0, s1
	s_nop 0
	global_load_lds_dwordx4 v[232:233], off
	s_mov_b32 m0, s2
	s_nop 0
	global_load_lds_dwordx4 v[234:235], off
	s_waitcnt vmcnt(8)
	s_waitcnt lgkmcnt(0)
	s_barrier
; #define PG8_STAGE(bufoff, gbase, voff) do { _Pragma("unroll") for (int _i = 0; _i < 2; ++_i) \
;         __builtin_amdgcn_global_load_lds((const unsigned*)((const char*)(gbase) + (voff)[_i]), (LAS unsigned*)(lds + (bufoff) + ldsw + _i * 8192), 16, 0, 0); } while (0)
; #define PG8_LDA(dst, b, h) do { _Pragma("unroll") for (int m = 0; m < 4; ++m) _Pragma("unroll") for (int k = 0; k < 2; ++k) dst[m][k] = *(const LAS bf16x8*)(lds + PG8_SA(b, h) + aoff + m * 2048 + k * 1024); } while (0)
; #define PG8_LDB(dst, b, h) do { _Pragma("unroll") for (int n = 0; n < 2; ++n) _Pragma("unroll") for (int k = 0; k < 2; ++k) dst[n][k] = *(const LAS bf16x8*)(lds + PG8_SB(b, h) + boff + n * 2048 + k * 1024); } while (0)
; #define PG8_MMA(ai, bj, At, Bt) do { __builtin_amdgcn_s_setprio(1); _Pragma("unroll") for (int m = 0; m < 4; ++m) _Pragma("unroll") for (int n = 0; n < 2; ++n) _Pragma("unroll") for (int k = 0; k < 2; ++k) \
;         acc[ai][bj][m][n] = __builtin_amdgcn_mfma_f32_16x16x32_bf16(Bt[n][k], At[m][k], acc[ai][bj][m][n], 0, 0, 0); __builtin_amdgcn_s_setprio(0); } while (0)
; #define PG8_WAIT_V(n) asm volatile("s_waitcnt vmcnt(" #n ")" ::: "memory")
; #define PG8_WAIT_L(n) asm volatile("s_waitcnt lgkmcnt(" #n ")" ::: "memory")
; #define PG8_BAR __builtin_amdgcn_s_barrier()
; #define PG8_SCHED __builtin_amdgcn_sched_barrier(0)
; template <class Epi, class Map>
; __device__ __forceinline__ void gemm_phase(LAS unsigned char* lds, const Gemm g, const Sched<Map>& S, const Epi& E) {
;     ...
;             PG8_LDA(At, 0, 1); PG8_STAGE(PG8_SB(0, 0), b2, voffB); PG8_STAGE(PG8_SB(0, 1), b2 + hstepB, voffB); PG8_STAGE(PG8_SA(0, 0), a2, voffA);
;             PG8_WAIT_V(8); PG8_WAIT_L(0); PG8_BAR; PG8_MMA(1, 0, At, B0); PG8_MMA(1, 1, At, B1); PG8_BAR; PG8_SCHED;
;             PG8_LDB(B0, 1, 0); PG8_LDB(B1, 1, 1); PG8_SCHED; PG8_LDA(At, 1, 0); PG8_STAGE(PG8_SA(0, 1), a2 + hstepA, voffA);
;             PG8_WAIT_V(8); PG8_WAIT_L(0); PG8_BAR; PG8_MMA(0, 0, At, B0); PG8_MMA(0, 1, At, B1); PG8_BAR; PG8_SCHED;
	s_waitcnt lgkmcnt(0)
	v_mfma_f32_16x16x32_bf16 v[60:63], v[64:67], v[200:203], v[60:63]
	v_mfma_f32_16x16x32_bf16 v[56:59], v[72:75], v[200:203], v[56:59]
	v_mfma_f32_16x16x32_bf16 v[52:55], v[64:67], v[208:211], v[52:55]
	v_mfma_f32_16x16x32_bf16 v[48:51], v[72:75], v[208:211], v[48:51]
	v_mfma_f32_16x16x32_bf16 v[28:31], v[64:67], v[216:219], v[28:31]
	v_mfma_f32_16x16x32_bf16 v[24:27], v[72:75], v[216:219], v[24:27]
	v_mfma_f32_16x16x32_bf16 v[20:23], v[64:67], v[224:227], v[20:23]
	v_mfma_f32_16x16x32_bf16 v[8:11], v[72:75], v[224:227], v[8:11]
	v_mfma_f32_16x16x32_bf16 v[60:63], v[68:71], v[204:207], v[60:63]
	v_mfma_f32_16x16x32_bf16 v[56:59], v[108:111], v[204:207], v[56:59]
	v_mfma_f32_16x16x32_bf16 v[52:55], v[68:71], v[212:215], v[52:55]
	v_mfma_f32_16x16x32_bf16 v[48:51], v[108:111], v[212:215], v[48:51]
	v_mfma_f32_16x16x32_bf16 v[28:31], v[68:71], v[220:223], v[28:31]
	v_mfma_f32_16x16x32_bf16 v[24:27], v[108:111], v[220:223], v[24:27]
	v_mfma_f32_16x16x32_bf16 v[20:23], v[68:71], v[228:231], v[20:23]
	v_mfma_f32_16x16x32_bf16 v[8:11], v[108:111], v[228:231], v[8:11]
	v_mfma_f32_16x16x32_bf16 v[44:47], v[166:169], v[200:203], v[44:47]
	v_mfma_f32_16x16x32_bf16 v[40:43], v[192:195], v[200:203], v[40:43]
	v_mfma_f32_16x16x32_bf16 v[36:39], v[166:169], v[208:211], v[36:39]
	v_mfma_f32_16x16x32_bf16 v[32:35], v[192:195], v[208:211], v[32:35]
	v_mfma_f32_16x16x32_bf16 v[16:19], v[166:169], v[216:219], v[16:19]
	v_mfma_f32_16x16x32_bf16 v[12:15], v[192:195], v[216:219], v[12:15]
	v_mfma_f32_16x16x32_bf16 v[4:7], v[166:169], v[224:227], v[4:7]
	v_mfma_f32_16x16x32_bf16 v[0:3], v[192:195], v[224:227], v[0:3]
	v_mfma_f32_16x16x32_bf16 v[44:47], v[176:179], v[204:207], v[44:47]
	v_mfma_f32_16x16x32_bf16 v[40:43], v[196:199], v[204:207], v[40:43]
	v_mfma_f32_16x16x32_bf16 v[36:39], v[176:179], v[212:215], v[36:39]
	v_mfma_f32_16x16x32_bf16 v[32:35], v[196:199], v[212:215], v[32:35]
	v_mfma_f32_16x16x32_bf16 v[16:19], v[176:179], v[220:223], v[16:19]
	v_mfma_f32_16x16x32_bf16 v[12:15], v[196:199], v[220:223], v[12:15]
	v_mfma_f32_16x16x32_bf16 v[4:7], v[176:179], v[228:231], v[4:7]
	v_mfma_f32_16x16x32_bf16 v[0:3], v[196:199], v[228:231], v[0:3]
	s_barrier
	s_add_i32 s47, 0, 0x18000
	s_add_i32 s48, 0, 0x1c000
	v_add_u32_e32 v108, s47, v173
	v_add_u32_e32 v175, s48, v173
	ds_read_b128 v[64:67], v108
	ds_read_b128 v[68:71], v108 offset:1024
	ds_read_b128 v[72:75], v108 offset:2048
	ds_read_b128 v[108:111], v108 offset:3072
	ds_read_b128 v[166:169], v175
	ds_read_b128 v[176:179], v175 offset:1024
	ds_read_b128 v[192:195], v175 offset:2048
	ds_read_b128 v[196:199], v175 offset:3072
	s_add_u32 s34, s34, 0x80000
	s_addc_u32 s35, s35, 0
	s_mov_b32 m0, s3
	v_lshl_add_u64 v[236:237], s[34:35], 0, v[144:145]
	ds_read_b128 v[200:203], v174 offset:32768
	ds_read_b128 v[204:207], v174 offset:33792
	ds_read_b128 v[208:211], v174 offset:34816
	ds_read_b128 v[212:215], v174 offset:35840
	ds_read_b128 v[216:219], v174 offset:36864
	ds_read_b128 v[220:223], v174 offset:37888
	ds_read_b128 v[224:227], v174 offset:38912
	ds_read_b128 v[228:231], v174 offset:39936
	global_load_lds_dwordx4 v[236:237], off
	v_lshl_add_u64 v[236:237], s[34:35], 0, v[160:161]
	s_mov_b32 m0, s4
	s_nop 0
	global_load_lds_dwordx4 v[236:237], off
	s_waitcnt vmcnt(8)
	s_waitcnt lgkmcnt(0)
	s_barrier
	s_waitcnt lgkmcnt(0)
	v_mfma_f32_16x16x32_bf16 v[140:143], v[64:67], v[200:203], v[140:143]
	v_mfma_f32_16x16x32_bf16 v[136:139], v[72:75], v[200:203], v[136:139]
	v_mfma_f32_16x16x32_bf16 v[132:135], v[64:67], v[208:211], v[132:135]
	v_mfma_f32_16x16x32_bf16 v[128:131], v[72:75], v[208:211], v[128:131]
	v_mfma_f32_16x16x32_bf16 v[104:107], v[64:67], v[216:219], v[104:107]
	v_mfma_f32_16x16x32_bf16 v[100:103], v[72:75], v[216:219], v[100:103]
	v_mfma_f32_16x16x32_bf16 v[96:99], v[64:67], v[224:227], v[96:99]
	v_mfma_f32_16x16x32_bf16 v[92:95], v[72:75], v[224:227], v[92:95]
	v_mfma_f32_16x16x32_bf16 v[140:143], v[68:71], v[204:207], v[140:143]
	v_mfma_f32_16x16x32_bf16 v[136:139], v[108:111], v[204:207], v[136:139]
	v_mfma_f32_16x16x32_bf16 v[132:135], v[68:71], v[212:215], v[132:135]
	v_mfma_f32_16x16x32_bf16 v[128:131], v[108:111], v[212:215], v[128:131]
	v_mfma_f32_16x16x32_bf16 v[104:107], v[68:71], v[220:223], v[104:107]
	v_mfma_f32_16x16x32_bf16 v[100:103], v[108:111], v[220:223], v[100:103]
	v_mfma_f32_16x16x32_bf16 v[96:99], v[68:71], v[228:231], v[96:99]
	v_mfma_f32_16x16x32_bf16 v[92:95], v[108:111], v[228:231], v[92:95]
	v_mfma_f32_16x16x32_bf16 v[124:127], v[166:169], v[200:203], v[124:127]
	v_mfma_f32_16x16x32_bf16 v[120:123], v[192:195], v[200:203], v[120:123]
	v_mfma_f32_16x16x32_bf16 v[116:119], v[166:169], v[208:211], v[116:119]
	v_mfma_f32_16x16x32_bf16 v[112:115], v[192:195], v[208:211], v[112:115]
	v_mfma_f32_16x16x32_bf16 v[88:91], v[166:169], v[216:219], v[88:91]
	v_mfma_f32_16x16x32_bf16 v[84:87], v[192:195], v[216:219], v[84:87]
	v_mfma_f32_16x16x32_bf16 v[80:83], v[166:169], v[224:227], v[80:83]
	v_mfma_f32_16x16x32_bf16 v[76:79], v[192:195], v[224:227], v[76:79]
	v_mfma_f32_16x16x32_bf16 v[124:127], v[176:179], v[204:207], v[124:127]
	v_mfma_f32_16x16x32_bf16 v[120:123], v[196:199], v[204:207], v[120:123]
	v_mfma_f32_16x16x32_bf16 v[116:119], v[176:179], v[212:215], v[116:119]
	v_mfma_f32_16x16x32_bf16 v[112:115], v[196:199], v[212:215], v[112:115]
	v_mfma_f32_16x16x32_bf16 v[88:91], v[176:179], v[220:223], v[88:91]
	v_mfma_f32_16x16x32_bf16 v[84:87], v[196:199], v[220:223], v[84:87]
	v_mfma_f32_16x16x32_bf16 v[80:83], v[176:179], v[228:231], v[80:83]
	v_mfma_f32_16x16x32_bf16 v[76:79], v[196:199], v[228:231], v[76:79]
	s_barrier
; #define PG8_STAGE(bufoff, gbase, voff) do { _Pragma("unroll") for (int _i = 0; _i < 2; ++_i) \
;         __builtin_amdgcn_global_load_lds((const unsigned*)((const char*)(gbase) + (voff)[_i]), (LAS unsigned*)(lds + (bufoff) + ldsw + _i * 8192), 16, 0, 0); } while (0)
; #define PG8_LDA(dst, b, h) do { _Pragma("unroll") for (int m = 0; m < 4; ++m) _Pragma("unroll") for (int k = 0; k < 2; ++k) dst[m][k] = *(const LAS bf16x8*)(lds + PG8_SA(b, h) + aoff + m * 2048 + k * 1024); } while (0)
; #define PG8_MMA(ai, bj, At, Bt) do { __builtin_amdgcn_s_setprio(1); _Pragma("unroll") for (int m = 0; m < 4; ++m) _Pragma("unroll") for (int n = 0; n < 2; ++n) _Pragma("unroll") for (int k = 0; k < 2; ++k) \
;         acc[ai][bj][m][n] = __builtin_amdgcn_mfma_f32_16x16x32_bf16(Bt[n][k], At[m][k], acc[ai][bj][m][n], 0, 0, 0); __builtin_amdgcn_s_setprio(0); } while (0)
; #define PG8_WAIT_V(n) asm volatile("s_waitcnt vmcnt(" #n ")" ::: "memory")
; #define PG8_WAIT_L(n) asm volatile("s_waitcnt lgkmcnt(" #n ")" ::: "memory")
; #define PG8_BAR __builtin_amdgcn_s_barrier()
; #define PG8_SCHED __builtin_amdgcn_sched_barrier(0)
; template <class Epi, class Map>
; __device__ __forceinline__ void gemm_phase(LAS unsigned char* lds, const Gemm g, const Sched<Map>& S, const Epi& E) {
;     ...
;             PG8_LDA(At, 1, 1); PG8_STAGE(PG8_SB(1, 0), b3, voffB); PG8_STAGE(PG8_SB(1, 1), b3 + hstepB, voffB); PG8_STAGE(PG8_SA(1, 0), a3, voffA);
;             PG8_WAIT_V(8); PG8_WAIT_L(0); PG8_BAR; PG8_MMA(1, 0, At, B0); PG8_MMA(1, 1, At, B1); PG8_BAR; PG8_SCHED;
;         }
;         if (wr == 0) PG8_BAR;
	s_add_i32 s34, s47, s0
	v_lshl_add_u64 v[170:171], v[170:171], 0, s[82:83]
	s_mov_b32 m0, s34
	ds_read_b128 v[200:203], v174 offset:49152
	ds_read_b128 v[204:207], v174 offset:50176
	ds_read_b128 v[208:211], v174 offset:51200
	ds_read_b128 v[212:215], v174 offset:52224
	ds_read_b128 v[216:219], v174 offset:53248
	ds_read_b128 v[220:223], v174 offset:54272
	ds_read_b128 v[224:227], v174 offset:55296
	ds_read_b128 v[228:231], v174 offset:56320
	global_load_lds_dwordx4 v[170:171], off
	s_add_i32 m0, s34, 0x2000
	s_add_u32 s30, s30, 0x80080
	v_lshl_add_u64 v[170:171], v[180:181], 0, s[82:83]
	s_addc_u32 s31, s31, 0
	s_add_i32 s34, s48, s0
	global_load_lds_dwordx4 v[170:171], off
	v_lshl_add_u64 v[170:171], s[30:31], 0, v[144:145]
	s_mov_b32 m0, s34
	s_nop 0
	global_load_lds_dwordx4 v[170:171], off
	v_lshl_add_u64 v[170:171], s[30:31], 0, v[160:161]
	s_add_i32 m0, s34, 0x2000
	s_nop 0
	global_load_lds_dwordx4 v[170:171], off
	v_lshl_add_u64 v[170:171], v[232:233], 0, s[82:83]
	s_mov_b32 m0, s10
	s_nop 0
	global_load_lds_dwordx4 v[170:171], off
	v_lshl_add_u64 v[170:171], v[234:235], 0, s[82:83]
	s_mov_b32 m0, s11
	s_nop 0
	global_load_lds_dwordx4 v[170:171], off
	s_waitcnt vmcnt(8)
	s_waitcnt lgkmcnt(0)
	s_barrier
	s_waitcnt lgkmcnt(0)
	v_mfma_f32_16x16x32_bf16 v[60:63], v[64:67], v[200:203], v[60:63]
	v_mfma_f32_16x16x32_bf16 v[56:59], v[72:75], v[200:203], v[56:59]
	v_mfma_f32_16x16x32_bf16 v[52:55], v[64:67], v[208:211], v[52:55]
	v_mfma_f32_16x16x32_bf16 v[48:51], v[72:75], v[208:211], v[48:51]
	v_mfma_f32_16x16x32_bf16 v[28:31], v[64:67], v[216:219], v[28:31]
	v_mfma_f32_16x16x32_bf16 v[24:27], v[72:75], v[216:219], v[24:27]
	v_mfma_f32_16x16x32_bf16 v[20:23], v[64:67], v[224:227], v[20:23]
	v_mfma_f32_16x16x32_bf16 v[8:11], v[72:75], v[224:227], v[8:11]
	v_mfma_f32_16x16x32_bf16 v[60:63], v[68:71], v[204:207], v[60:63]
	v_mfma_f32_16x16x32_bf16 v[56:59], v[108:111], v[204:207], v[56:59]
	v_mfma_f32_16x16x32_bf16 v[52:55], v[68:71], v[212:215], v[52:55]
	v_mfma_f32_16x16x32_bf16 v[48:51], v[108:111], v[212:215], v[48:51]
	v_mfma_f32_16x16x32_bf16 v[28:31], v[68:71], v[220:223], v[28:31]
	v_mfma_f32_16x16x32_bf16 v[24:27], v[108:111], v[220:223], v[24:27]
	v_mfma_f32_16x16x32_bf16 v[20:23], v[68:71], v[228:231], v[20:23]
	v_mfma_f32_16x16x32_bf16 v[8:11], v[108:111], v[228:231], v[8:11]
	v_mfma_f32_16x16x32_bf16 v[44:47], v[166:169], v[200:203], v[44:47]
	v_mfma_f32_16x16x32_bf16 v[40:43], v[192:195], v[200:203], v[40:43]
	v_mfma_f32_16x16x32_bf16 v[36:39], v[166:169], v[208:211], v[36:39]
	v_mfma_f32_16x16x32_bf16 v[32:35], v[192:195], v[208:211], v[32:35]
	v_mfma_f32_16x16x32_bf16 v[16:19], v[166:169], v[216:219], v[16:19]
	v_mfma_f32_16x16x32_bf16 v[12:15], v[192:195], v[216:219], v[12:15]
	v_mfma_f32_16x16x32_bf16 v[4:7], v[166:169], v[224:227], v[4:7]
	v_mfma_f32_16x16x32_bf16 v[0:3], v[192:195], v[224:227], v[0:3]
	v_mfma_f32_16x16x32_bf16 v[44:47], v[176:179], v[204:207], v[44:47]
	v_mfma_f32_16x16x32_bf16 v[40:43], v[196:199], v[204:207], v[40:43]
	v_mfma_f32_16x16x32_bf16 v[36:39], v[176:179], v[212:215], v[36:39]
	v_mfma_f32_16x16x32_bf16 v[32:35], v[196:199], v[212:215], v[32:35]
	v_mfma_f32_16x16x32_bf16 v[16:19], v[176:179], v[220:223], v[16:19]
	v_mfma_f32_16x16x32_bf16 v[12:15], v[196:199], v[220:223], v[12:15]
	v_mfma_f32_16x16x32_bf16 v[4:7], v[176:179], v[228:231], v[4:7]
	v_mfma_f32_16x16x32_bf16 v[0:3], v[196:199], v[228:231], v[0:3]
	s_barrier
	s_add_i32 s46, s46, 2
	s_add_u32 s28, s28, 0x100
	s_addc_u32 s29, s29, 0
	s_add_u32 s44, s44, 0x100
	s_addc_u32 s45, s45, 0
	s_cmp_gt_u32 s46, 29
	s_cbranch_scc0 .LBB0_405
	s_and_b64 vcc, exec, s[18:19]
	s_cbranch_vccz .LBB0_408
	s_barrier

; #define PG8_STAGE(bufoff, gbase, voff) do { _Pragma("unroll") for (int _i = 0; _i < 2; ++_i) \
;         __builtin_amdgcn_global_load_lds((const unsigned*)((const char*)(gbase) + (voff)[_i]), (LAS unsigned*)(lds + (bufoff) + ldsw + _i * 8192), 16, 0, 0); } while (0)
; #define PG8_LDA(dst, b, h) do { _Pragma("unroll") for (int m = 0; m < 4; ++m) _Pragma("unroll") for (int k = 0; k < 2; ++k) dst[m][k] = *(const LAS bf16x8*)(lds + PG8_SA(b, h) + aoff + m * 2048 + k * 1024); } while (0)
; #define PG8_LDB(dst, b, h) do { _Pragma("unroll") for (int n = 0; n < 2; ++n) _Pragma("unroll") for (int k = 0; k < 2; ++k) dst[n][k] = *(const LAS bf16x8*)(lds + PG8_SB(b, h) + boff + n * 2048 + k * 1024); } while (0)
; #define PG8_MMA(ai, bj, At, Bt) do { __builtin_amdgcn_s_setprio(1); _Pragma("unroll") for (int m = 0; m < 4; ++m) _Pragma("unroll") for (int n = 0; n < 2; ++n) _Pragma("unroll") for (int k = 0; k < 2; ++k) \
;         acc[ai][bj][m][n] = __builtin_amdgcn_mfma_f32_16x16x32_bf16(Bt[n][k], At[m][k], acc[ai][bj][m][n], 0, 0, 0); __builtin_amdgcn_s_setprio(0); } while (0)
; #define PG8_WAIT_V(n) asm volatile("s_waitcnt vmcnt(" #n ")" ::: "memory")
; #define PG8_WAIT_L(n) asm volatile("s_waitcnt lgkmcnt(" #n ")" ::: "memory")
; #define PG8_BAR __builtin_amdgcn_s_barrier()
; #define PG8_SCHED __builtin_amdgcn_sched_barrier(0)
; template <class Epi, class Map>
; __device__ __forceinline__ void gemm_phase(LAS unsigned char* lds, const Gemm g, const Sched<Map>& S, const Epi& E) {
;     ...
;         for (int t = 0; t < nt; t += 2) {
;             const bool last = (t == nt - 2);
;             const char* a1 = cA + (size_t)(t + 1) * kstep;
;             const char* a2 = last ? nA : cA + (size_t)(t + 2) * kstep; const char* b2 = last ? nB : cB + (size_t)(t + 2) * kstep;
;             const char* a3 = a2 + kstep; const char* b3 = b2 + kstep;
;             PG8_LDB(B0, 0, 0); PG8_LDB(B1, 0, 1); PG8_SCHED; PG8_LDA(At, 0, 0); PG8_STAGE(PG8_SA(1, 1), a1 + hstepA, voffA);
;             PG8_WAIT_V(8); PG8_WAIT_L(0); PG8_BAR; PG8_MMA(0, 0, At, B0); PG8_MMA(0, 1, At, B1); PG8_BAR; PG8_SCHED;
.LBB0_552:
	s_add_u32 s14, s24, 0xfff80080
	s_addc_u32 s15, s25, -1
	s_add_i32 s19, 0, 0x10000
	s_cmp_eq_u32 s13, 28
	s_cselect_b32 s31, s3, s15
	s_cselect_b32 s30, s8, s14
	v_add_u32_e32 v142, s19, v168
	s_cselect_b32 s29, s9, s12
	s_cselect_b32 s28, s10, s11
	s_add_i32 s21, 0, 0x14000
	ds_read_b128 v[128:131], v142
	ds_read_b128 v[160:163], v142 offset:1024
	ds_read_b128 v[170:173], v142 offset:2048
	ds_read_b128 v[174:177], v142 offset:3072
	v_add_u32_e32 v142, s21, v168
	ds_read_b128 v[178:181], v142
	ds_read_b128 v[192:195], v142 offset:1024
	ds_read_b128 v[196:199], v142 offset:2048
	ds_read_b128 v[200:203], v142 offset:3072
	v_lshl_add_u64 v[142:143], s[24:25], 0, v[138:139]
	s_add_i32 m0, s35, 0xc000
	ds_read_b128 v[204:207], v169
	ds_read_b128 v[208:211], v169 offset:1024
	ds_read_b128 v[212:215], v169 offset:2048
	ds_read_b128 v[216:219], v169 offset:3072
	ds_read_b128 v[220:223], v169 offset:4096
	ds_read_b128 v[224:227], v169 offset:5120
	ds_read_b128 v[228:231], v169 offset:6144
	ds_read_b128 v[232:235], v169 offset:7168
	global_load_lds_dwordx4 v[142:143], off
	v_lshl_add_u64 v[142:143], s[24:25], 0, v[140:141]
	s_add_i32 m0, s35, 0xe000
	s_nop 0
	global_load_lds_dwordx4 v[142:143], off
	s_waitcnt vmcnt(8)
	s_waitcnt lgkmcnt(0)
	s_barrier
	s_waitcnt lgkmcnt(0)
	v_mfma_f32_16x16x32_bf16 v[124:127], v[128:131], v[204:207], v[124:127]
	v_mfma_f32_16x16x32_bf16 v[116:119], v[170:173], v[204:207], v[116:119]
	v_mfma_f32_16x16x32_bf16 v[108:111], v[128:131], v[212:215], v[108:111]
	v_mfma_f32_16x16x32_bf16 v[96:99], v[170:173], v[212:215], v[96:99]
	v_mfma_f32_16x16x32_bf16 v[92:95], v[128:131], v[220:223], v[92:95]
	v_mfma_f32_16x16x32_bf16 v[80:83], v[170:173], v[220:223], v[80:83]
	v_mfma_f32_16x16x32_bf16 v[76:79], v[128:131], v[228:231], v[76:79]
	v_mfma_f32_16x16x32_bf16 v[64:67], v[170:173], v[228:231], v[64:67]
	v_mfma_f32_16x16x32_bf16 v[124:127], v[160:163], v[208:211], v[124:127]
	v_mfma_f32_16x16x32_bf16 v[116:119], v[174:177], v[208:211], v[116:119]
	v_mfma_f32_16x16x32_bf16 v[108:111], v[160:163], v[216:219], v[108:111]
	v_mfma_f32_16x16x32_bf16 v[96:99], v[174:177], v[216:219], v[96:99]
	v_mfma_f32_16x16x32_bf16 v[92:95], v[160:163], v[224:227], v[92:95]
	v_mfma_f32_16x16x32_bf16 v[80:83], v[174:177], v[224:227], v[80:83]
	v_mfma_f32_16x16x32_bf16 v[76:79], v[160:163], v[232:235], v[76:79]
	v_mfma_f32_16x16x32_bf16 v[64:67], v[174:177], v[232:235], v[64:67]
	v_mfma_f32_16x16x32_bf16 v[120:123], v[178:181], v[204:207], v[120:123]
	v_mfma_f32_16x16x32_bf16 v[112:115], v[196:199], v[204:207], v[112:115]
	v_mfma_f32_16x16x32_bf16 v[104:107], v[178:181], v[212:215], v[104:107]
	v_mfma_f32_16x16x32_bf16 v[100:103], v[196:199], v[212:215], v[100:103]
	v_mfma_f32_16x16x32_bf16 v[88:91], v[178:181], v[220:223], v[88:91]
	v_mfma_f32_16x16x32_bf16 v[84:87], v[196:199], v[220:223], v[84:87]
	v_mfma_f32_16x16x32_bf16 v[72:75], v[178:181], v[228:231], v[72:75]
	v_mfma_f32_16x16x32_bf16 v[68:71], v[196:199], v[228:231], v[68:71]
	v_mfma_f32_16x16x32_bf16 v[120:123], v[192:195], v[208:211], v[120:123]
	v_mfma_f32_16x16x32_bf16 v[112:115], v[200:203], v[208:211], v[112:115]
	v_mfma_f32_16x16x32_bf16 v[104:107], v[192:195], v[216:219], v[104:107]
	v_mfma_f32_16x16x32_bf16 v[100:103], v[200:203], v[216:219], v[100:103]
	v_mfma_f32_16x16x32_bf16 v[88:91], v[192:195], v[224:227], v[88:91]
	v_mfma_f32_16x16x32_bf16 v[84:87], v[200:203], v[224:227], v[84:87]
	v_mfma_f32_16x16x32_bf16 v[72:75], v[192:195], v[232:235], v[72:75]
	v_mfma_f32_16x16x32_bf16 v[68:71], v[200:203], v[232:235], v[68:71]
	s_barrier
	s_add_i32 s14, s19, s34
	v_lshl_add_u64 v[142:143], s[28:29], 0, v[144:145]
	s_mov_b32 m0, s14
	ds_read_b128 v[204:207], v169 offset:16384
	ds_read_b128 v[208:211], v169 offset:17408
	ds_read_b128 v[212:215], v169 offset:18432
	ds_read_b128 v[216:219], v169 offset:19456
	ds_read_b128 v[220:223], v169 offset:20480
	ds_read_b128 v[224:227], v169 offset:21504
	ds_read_b128 v[228:231], v169 offset:22528
	ds_read_b128 v[232:235], v169 offset:23552
	global_load_lds_dwordx4 v[142:143], off
	s_add_i32 m0, s14, 0x2000
	s_add_u32 s14, s28, 0x80000
	v_lshl_add_u64 v[164:165], s[28:29], 0, v[136:137]
	s_addc_u32 s15, s29, 0
	s_add_i32 s19, s21, s34
	global_load_lds_dwordx4 v[164:165], off
	v_lshl_add_u64 v[236:237], s[14:15], 0, v[144:145]
	s_mov_b32 m0, s19
	v_lshl_add_u64 v[238:239], s[30:31], 0, v[134:135]
	global_load_lds_dwordx4 v[236:237], off
	v_lshl_add_u64 v[236:237], s[14:15], 0, v[136:137]
	s_add_i32 m0, s19, 0x2000
	s_nop 0
	global_load_lds_dwordx4 v[236:237], off
	v_lshl_add_u64 v[236:237], s[30:31], 0, v[132:133]
	s_mov_b32 m0, s35
	s_nop 0
	global_load_lds_dwordx4 v[236:237], off
	s_mov_b32 m0, s84
	s_nop 0
	global_load_lds_dwordx4 v[238:239], off
	s_waitcnt vmcnt(8)
	s_waitcnt lgkmcnt(0)
	s_barrier
; #define PG8_STAGE(bufoff, gbase, voff) do { _Pragma("unroll") for (int _i = 0; _i < 2; ++_i) \
;         __builtin_amdgcn_global_load_lds((const unsigned*)((const char*)(gbase) + (voff)[_i]), (LAS unsigned*)(lds + (bufoff) + ldsw + _i * 8192), 16, 0, 0); } while (0)
; #define PG8_LDA(dst, b, h) do { _Pragma("unroll") for (int m = 0; m < 4; ++m) _Pragma("unroll") for (int k = 0; k < 2; ++k) dst[m][k] = *(const LAS bf16x8*)(lds + PG8_SA(b, h) + aoff + m * 2048 + k * 1024); } while (0)
; #define PG8_LDB(dst, b, h) do { _Pragma("unroll") for (int n = 0; n < 2; ++n) _Pragma("unroll") for (int k = 0; k < 2; ++k) dst[n][k] = *(const LAS bf16x8*)(lds + PG8_SB(b, h) + boff + n * 2048 + k * 1024); } while (0)
; #define PG8_MMA(ai, bj, At, Bt) do { __builtin_amdgcn_s_setprio(1); _Pragma("unroll") for (int m = 0; m < 4; ++m) _Pragma("unroll") for (int n = 0; n < 2; ++n) _Pragma("unroll") for (int k = 0; k < 2; ++k) \
;         acc[ai][bj][m][n] = __builtin_amdgcn_mfma_f32_16x16x32_bf16(Bt[n][k], At[m][k], acc[ai][bj][m][n], 0, 0, 0); __builtin_amdgcn_s_setprio(0); } while (0)
; #define PG8_WAIT_V(n) asm volatile("s_waitcnt vmcnt(" #n ")" ::: "memory")
; #define PG8_WAIT_L(n) asm volatile("s_waitcnt lgkmcnt(" #n ")" ::: "memory")
; #define PG8_BAR __builtin_amdgcn_s_barrier()
; #define PG8_SCHED __builtin_amdgcn_sched_barrier(0)
; template <class Epi, class Map>
; __device__ __forceinline__ void gemm_phase(LAS unsigned char* lds, const Gemm g, const Sched<Map>& S, const Epi& E) {
;     ...
;             PG8_LDA(At, 0, 1); PG8_STAGE(PG8_SB(0, 0), b2, voffB); PG8_STAGE(PG8_SB(0, 1), b2 + hstepB, voffB); PG8_STAGE(PG8_SA(0, 0), a2, voffA);
;             PG8_WAIT_V(8); PG8_WAIT_L(0); PG8_BAR; PG8_MMA(1, 0, At, B0); PG8_MMA(1, 1, At, B1); PG8_BAR; PG8_SCHED;
;             PG8_LDB(B0, 1, 0); PG8_LDB(B1, 1, 1); PG8_SCHED; PG8_LDA(At, 1, 0); PG8_STAGE(PG8_SA(0, 1), a2 + hstepA, voffA);
;             PG8_WAIT_V(8); PG8_WAIT_L(0); PG8_BAR; PG8_MMA(0, 0, At, B0); PG8_MMA(0, 1, At, B1); PG8_BAR; PG8_SCHED;
	s_waitcnt lgkmcnt(0)
	v_mfma_f32_16x16x32_bf16 v[60:63], v[128:131], v[204:207], v[60:63]
	v_mfma_f32_16x16x32_bf16 v[48:51], v[170:173], v[204:207], v[48:51]
	v_mfma_f32_16x16x32_bf16 v[44:47], v[128:131], v[212:215], v[44:47]
	v_mfma_f32_16x16x32_bf16 v[32:35], v[170:173], v[212:215], v[32:35]
	v_mfma_f32_16x16x32_bf16 v[28:31], v[128:131], v[220:223], v[28:31]
	v_mfma_f32_16x16x32_bf16 v[16:19], v[170:173], v[220:223], v[16:19]
	v_mfma_f32_16x16x32_bf16 v[12:15], v[128:131], v[228:231], v[12:15]
	v_mfma_f32_16x16x32_bf16 v[0:3], v[170:173], v[228:231], v[0:3]
	v_mfma_f32_16x16x32_bf16 v[60:63], v[160:163], v[208:211], v[60:63]
	v_mfma_f32_16x16x32_bf16 v[48:51], v[174:177], v[208:211], v[48:51]
	v_mfma_f32_16x16x32_bf16 v[44:47], v[160:163], v[216:219], v[44:47]
	v_mfma_f32_16x16x32_bf16 v[32:35], v[174:177], v[216:219], v[32:35]
	v_mfma_f32_16x16x32_bf16 v[28:31], v[160:163], v[224:227], v[28:31]
	v_mfma_f32_16x16x32_bf16 v[16:19], v[174:177], v[224:227], v[16:19]
	v_mfma_f32_16x16x32_bf16 v[12:15], v[160:163], v[232:235], v[12:15]
	v_mfma_f32_16x16x32_bf16 v[0:3], v[174:177], v[232:235], v[0:3]
	v_mfma_f32_16x16x32_bf16 v[56:59], v[178:181], v[204:207], v[56:59]
	v_mfma_f32_16x16x32_bf16 v[52:55], v[196:199], v[204:207], v[52:55]
	v_mfma_f32_16x16x32_bf16 v[40:43], v[178:181], v[212:215], v[40:43]
	v_mfma_f32_16x16x32_bf16 v[36:39], v[196:199], v[212:215], v[36:39]
	v_mfma_f32_16x16x32_bf16 v[24:27], v[178:181], v[220:223], v[24:27]
	v_mfma_f32_16x16x32_bf16 v[20:23], v[196:199], v[220:223], v[20:23]
	v_mfma_f32_16x16x32_bf16 v[8:11], v[178:181], v[228:231], v[8:11]
	v_mfma_f32_16x16x32_bf16 v[4:7], v[196:199], v[228:231], v[4:7]
	v_mfma_f32_16x16x32_bf16 v[56:59], v[192:195], v[208:211], v[56:59]
	v_mfma_f32_16x16x32_bf16 v[52:55], v[200:203], v[208:211], v[52:55]
	v_mfma_f32_16x16x32_bf16 v[40:43], v[192:195], v[216:219], v[40:43]
	v_mfma_f32_16x16x32_bf16 v[36:39], v[200:203], v[216:219], v[36:39]
	v_mfma_f32_16x16x32_bf16 v[24:27], v[192:195], v[224:227], v[24:27]
	v_mfma_f32_16x16x32_bf16 v[20:23], v[200:203], v[224:227], v[20:23]
	v_mfma_f32_16x16x32_bf16 v[8:11], v[192:195], v[232:235], v[8:11]
	v_mfma_f32_16x16x32_bf16 v[4:7], v[200:203], v[232:235], v[4:7]
	s_barrier
	s_add_i32 s19, 0, 0x18000
	s_add_i32 s21, 0, 0x1c000
	v_add_u32_e32 v174, s19, v168
	v_add_u32_e32 v200, s21, v168
	ds_read_b128 v[128:131], v174
	ds_read_b128 v[160:163], v174 offset:1024
	ds_read_b128 v[170:173], v174 offset:2048
	ds_read_b128 v[174:177], v174 offset:3072
	ds_read_b128 v[178:181], v200
	ds_read_b128 v[192:195], v200 offset:1024
	ds_read_b128 v[196:199], v200 offset:2048
	ds_read_b128 v[200:203], v200 offset:3072
	s_add_u32 s14, s30, 0x80000
	s_addc_u32 s15, s31, 0
	s_mov_b32 m0, s85
	v_lshl_add_u64 v[240:241], s[14:15], 0, v[132:133]
	ds_read_b128 v[204:207], v169 offset:32768
	ds_read_b128 v[208:211], v169 offset:33792
	ds_read_b128 v[212:215], v169 offset:34816
	ds_read_b128 v[216:219], v169 offset:35840
	ds_read_b128 v[220:223], v169 offset:36864
	ds_read_b128 v[224:227], v169 offset:37888
	ds_read_b128 v[228:231], v169 offset:38912
	ds_read_b128 v[232:235], v169 offset:39936
	global_load_lds_dwordx4 v[240:241], off
	v_lshl_add_u64 v[240:241], s[14:15], 0, v[134:135]
	s_mov_b32 m0, s90
	s_nop 0
	global_load_lds_dwordx4 v[240:241], off
	s_waitcnt vmcnt(8)
	s_waitcnt lgkmcnt(0)
	s_barrier
	s_waitcnt lgkmcnt(0)
	v_mfma_f32_16x16x32_bf16 v[124:127], v[128:131], v[204:207], v[124:127]
	v_mfma_f32_16x16x32_bf16 v[116:119], v[170:173], v[204:207], v[116:119]
	v_mfma_f32_16x16x32_bf16 v[108:111], v[128:131], v[212:215], v[108:111]
	v_mfma_f32_16x16x32_bf16 v[96:99], v[170:173], v[212:215], v[96:99]
	v_mfma_f32_16x16x32_bf16 v[92:95], v[128:131], v[220:223], v[92:95]
	v_mfma_f32_16x16x32_bf16 v[80:83], v[170:173], v[220:223], v[80:83]
	v_mfma_f32_16x16x32_bf16 v[76:79], v[128:131], v[228:231], v[76:79]
	v_mfma_f32_16x16x32_bf16 v[64:67], v[170:173], v[228:231], v[64:67]
	v_mfma_f32_16x16x32_bf16 v[124:127], v[160:163], v[208:211], v[124:127]
	v_mfma_f32_16x16x32_bf16 v[116:119], v[174:177], v[208:211], v[116:119]
	v_mfma_f32_16x16x32_bf16 v[108:111], v[160:163], v[216:219], v[108:111]
	v_mfma_f32_16x16x32_bf16 v[96:99], v[174:177], v[216:219], v[96:99]
	v_mfma_f32_16x16x32_bf16 v[92:95], v[160:163], v[224:227], v[92:95]
	v_mfma_f32_16x16x32_bf16 v[80:83], v[174:177], v[224:227], v[80:83]
	v_mfma_f32_16x16x32_bf16 v[76:79], v[160:163], v[232:235], v[76:79]
	v_mfma_f32_16x16x32_bf16 v[64:67], v[174:177], v[232:235], v[64:67]
	v_mfma_f32_16x16x32_bf16 v[120:123], v[178:181], v[204:207], v[120:123]
	v_mfma_f32_16x16x32_bf16 v[112:115], v[196:199], v[204:207], v[112:115]
	v_mfma_f32_16x16x32_bf16 v[104:107], v[178:181], v[212:215], v[104:107]
	v_mfma_f32_16x16x32_bf16 v[100:103], v[196:199], v[212:215], v[100:103]
	v_mfma_f32_16x16x32_bf16 v[88:91], v[178:181], v[220:223], v[88:91]
	v_mfma_f32_16x16x32_bf16 v[84:87], v[196:199], v[220:223], v[84:87]
	v_mfma_f32_16x16x32_bf16 v[72:75], v[178:181], v[228:231], v[72:75]
	v_mfma_f32_16x16x32_bf16 v[68:71], v[196:199], v[228:231], v[68:71]
	v_mfma_f32_16x16x32_bf16 v[120:123], v[192:195], v[208:211], v[120:123]
	v_mfma_f32_16x16x32_bf16 v[112:115], v[200:203], v[208:211], v[112:115]
	v_mfma_f32_16x16x32_bf16 v[104:107], v[192:195], v[216:219], v[104:107]
	v_mfma_f32_16x16x32_bf16 v[100:103], v[200:203], v[216:219], v[100:103]
	v_mfma_f32_16x16x32_bf16 v[88:91], v[192:195], v[224:227], v[88:91]
	v_mfma_f32_16x16x32_bf16 v[84:87], v[200:203], v[224:227], v[84:87]
	v_mfma_f32_16x16x32_bf16 v[72:75], v[192:195], v[232:235], v[72:75]
	v_mfma_f32_16x16x32_bf16 v[68:71], v[200:203], v[232:235], v[68:71]
	s_barrier
; #define PG8_STAGE(bufoff, gbase, voff) do { _Pragma("unroll") for (int _i = 0; _i < 2; ++_i) \
;         __builtin_amdgcn_global_load_lds((const unsigned*)((const char*)(gbase) + (voff)[_i]), (LAS unsigned*)(lds + (bufoff) + ldsw + _i * 8192), 16, 0, 0); } while (0)
; #define PG8_LDA(dst, b, h) do { _Pragma("unroll") for (int m = 0; m < 4; ++m) _Pragma("unroll") for (int k = 0; k < 2; ++k) dst[m][k] = *(const LAS bf16x8*)(lds + PG8_SA(b, h) + aoff + m * 2048 + k * 1024); } while (0)
; #define PG8_MMA(ai, bj, At, Bt) do { __builtin_amdgcn_s_setprio(1); _Pragma("unroll") for (int m = 0; m < 4; ++m) _Pragma("unroll") for (int n = 0; n < 2; ++n) _Pragma("unroll") for (int k = 0; k < 2; ++k) \
;         acc[ai][bj][m][n] = __builtin_amdgcn_mfma_f32_16x16x32_bf16(Bt[n][k], At[m][k], acc[ai][bj][m][n], 0, 0, 0); __builtin_amdgcn_s_setprio(0); } while (0)
; #define PG8_WAIT_V(n) asm volatile("s_waitcnt vmcnt(" #n ")" ::: "memory")
; #define PG8_WAIT_L(n) asm volatile("s_waitcnt lgkmcnt(" #n ")" ::: "memory")
; #define PG8_BAR __builtin_amdgcn_s_barrier()
; #define PG8_SCHED __builtin_amdgcn_sched_barrier(0)
; template <class Epi, class Map>
; __device__ __forceinline__ void gemm_phase(LAS unsigned char* lds, const Gemm g, const Sched<Map>& S, const Epi& E) {
;     ...
;             PG8_LDA(At, 1, 1); PG8_STAGE(PG8_SB(1, 0), b3, voffB); PG8_STAGE(PG8_SB(1, 1), b3 + hstepB, voffB); PG8_STAGE(PG8_SA(1, 0), a3, voffA);
;             PG8_WAIT_V(8); PG8_WAIT_L(0); PG8_BAR; PG8_MMA(1, 0, At, B0); PG8_MMA(1, 1, At, B1); PG8_BAR; PG8_SCHED;
;         }
;         if (wr == 0) PG8_BAR;
	s_add_i32 s14, s19, s34
	v_lshl_add_u64 v[142:143], v[142:143], 0, s[82:83]
	s_mov_b32 m0, s14
	ds_read_b128 v[204:207], v169 offset:49152
	ds_read_b128 v[208:211], v169 offset:50176
	ds_read_b128 v[212:215], v169 offset:51200
	ds_read_b128 v[216:219], v169 offset:52224
	ds_read_b128 v[220:223], v169 offset:53248
	ds_read_b128 v[224:227], v169 offset:54272
	ds_read_b128 v[228:231], v169 offset:55296
	ds_read_b128 v[232:235], v169 offset:56320
	global_load_lds_dwordx4 v[142:143], off
	s_add_i32 m0, s14, 0x2000
	s_add_u32 s14, s28, 0x80080
	v_lshl_add_u64 v[142:143], v[164:165], 0, s[82:83]
	s_addc_u32 s15, s29, 0
	s_add_i32 s19, s21, s34
	global_load_lds_dwordx4 v[142:143], off
	v_lshl_add_u64 v[142:143], s[14:15], 0, v[144:145]
	s_mov_b32 m0, s19
	s_nop 0
	global_load_lds_dwordx4 v[142:143], off
	v_lshl_add_u64 v[142:143], s[14:15], 0, v[136:137]
	s_add_i32 m0, s19, 0x2000
	s_nop 0
	global_load_lds_dwordx4 v[142:143], off
	v_lshl_add_u64 v[142:143], v[236:237], 0, s[82:83]
	s_mov_b32 m0, s97
	s_nop 0
	global_load_lds_dwordx4 v[142:143], off
	v_lshl_add_u64 v[142:143], v[238:239], 0, s[82:83]
	s_mov_b32 m0, s56
	s_nop 0
	global_load_lds_dwordx4 v[142:143], off
	s_waitcnt vmcnt(8)
	s_waitcnt lgkmcnt(0)
	s_barrier
	s_waitcnt lgkmcnt(0)
	v_mfma_f32_16x16x32_bf16 v[60:63], v[128:131], v[204:207], v[60:63]
	v_mfma_f32_16x16x32_bf16 v[48:51], v[170:173], v[204:207], v[48:51]
	v_mfma_f32_16x16x32_bf16 v[44:47], v[128:131], v[212:215], v[44:47]
	v_mfma_f32_16x16x32_bf16 v[32:35], v[170:173], v[212:215], v[32:35]
	v_mfma_f32_16x16x32_bf16 v[28:31], v[128:131], v[220:223], v[28:31]
	v_mfma_f32_16x16x32_bf16 v[16:19], v[170:173], v[220:223], v[16:19]
	v_mfma_f32_16x16x32_bf16 v[12:15], v[128:131], v[228:231], v[12:15]
	v_mfma_f32_16x16x32_bf16 v[0:3], v[170:173], v[228:231], v[0:3]
	v_mfma_f32_16x16x32_bf16 v[60:63], v[160:163], v[208:211], v[60:63]
	v_mfma_f32_16x16x32_bf16 v[48:51], v[174:177], v[208:211], v[48:51]
	v_mfma_f32_16x16x32_bf16 v[44:47], v[160:163], v[216:219], v[44:47]
	v_mfma_f32_16x16x32_bf16 v[32:35], v[174:177], v[216:219], v[32:35]
	v_mfma_f32_16x16x32_bf16 v[28:31], v[160:163], v[224:227], v[28:31]
	v_mfma_f32_16x16x32_bf16 v[16:19], v[174:177], v[224:227], v[16:19]
	v_mfma_f32_16x16x32_bf16 v[12:15], v[160:163], v[232:235], v[12:15]
	v_mfma_f32_16x16x32_bf16 v[0:3], v[174:177], v[232:235], v[0:3]
	v_mfma_f32_16x16x32_bf16 v[56:59], v[178:181], v[204:207], v[56:59]
	v_mfma_f32_16x16x32_bf16 v[52:55], v[196:199], v[204:207], v[52:55]
	v_mfma_f32_16x16x32_bf16 v[40:43], v[178:181], v[212:215], v[40:43]
	v_mfma_f32_16x16x32_bf16 v[36:39], v[196:199], v[212:215], v[36:39]
	v_mfma_f32_16x16x32_bf16 v[24:27], v[178:181], v[220:223], v[24:27]
	v_mfma_f32_16x16x32_bf16 v[20:23], v[196:199], v[220:223], v[20:23]
	v_mfma_f32_16x16x32_bf16 v[8:11], v[178:181], v[228:231], v[8:11]
	v_mfma_f32_16x16x32_bf16 v[4:7], v[196:199], v[228:231], v[4:7]
	v_mfma_f32_16x16x32_bf16 v[56:59], v[192:195], v[208:211], v[56:59]
	v_mfma_f32_16x16x32_bf16 v[52:55], v[200:203], v[208:211], v[52:55]
	v_mfma_f32_16x16x32_bf16 v[40:43], v[192:195], v[216:219], v[40:43]
	v_mfma_f32_16x16x32_bf16 v[36:39], v[200:203], v[216:219], v[36:39]
	v_mfma_f32_16x16x32_bf16 v[24:27], v[192:195], v[224:227], v[24:27]
	v_mfma_f32_16x16x32_bf16 v[20:23], v[200:203], v[224:227], v[20:23]
	v_mfma_f32_16x16x32_bf16 v[8:11], v[192:195], v[232:235], v[8:11]
	v_mfma_f32_16x16x32_bf16 v[4:7], v[200:203], v[232:235], v[4:7]
	s_barrier
	s_add_i32 s13, s13, 2
	s_add_u32 s24, s24, 0x100
	s_addc_u32 s25, s25, 0
	s_add_u32 s11, s11, 0x100
	s_addc_u32 s12, s12, 0
	s_cmp_gt_u32 s13, 29
	s_cbranch_scc0 .LBB0_552
	s_and_b64 vcc, exec, s[52:53]
	s_cbranch_vccz .LBB0_555
	s_barrier

; #define PG8_STAGE(bufoff, gbase, voff) do { _Pragma("unroll") for (int _i = 0; _i < 2; ++_i) \
;         __builtin_amdgcn_global_load_lds((const unsigned*)((const char*)(gbase) + (voff)[_i]), (LAS unsigned*)(lds + (bufoff) + ldsw + _i * 8192), 16, 0, 0); } while (0)
; #define PG8_LDA(dst, b, h) do { _Pragma("unroll") for (int m = 0; m < 4; ++m) _Pragma("unroll") for (int k = 0; k < 2; ++k) dst[m][k] = *(const LAS bf16x8*)(lds + PG8_SA(b, h) + aoff + m * 2048 + k * 1024); } while (0)
; #define PG8_LDB(dst, b, h) do { _Pragma("unroll") for (int n = 0; n < 2; ++n) _Pragma("unroll") for (int k = 0; k < 2; ++k) dst[n][k] = *(const LAS bf16x8*)(lds + PG8_SB(b, h) + boff + n * 2048 + k * 1024); } while (0)
; #define PG8_MMA(ai, bj, At, Bt) do { __builtin_amdgcn_s_setprio(1); _Pragma("unroll") for (int m = 0; m < 4; ++m) _Pragma("unroll") for (int n = 0; n < 2; ++n) _Pragma("unroll") for (int k = 0; k < 2; ++k) \
;         acc[ai][bj][m][n] = __builtin_amdgcn_mfma_f32_16x16x32_bf16(Bt[n][k], At[m][k], acc[ai][bj][m][n], 0, 0, 0); __builtin_amdgcn_s_setprio(0); } while (0)
; #define PG8_WAIT_V(n) asm volatile("s_waitcnt vmcnt(" #n ")" ::: "memory")
; #define PG8_WAIT_L(n) asm volatile("s_waitcnt lgkmcnt(" #n ")" ::: "memory")
; #define PG8_BAR __builtin_amdgcn_s_barrier()
; #define PG8_SCHED __builtin_amdgcn_sched_barrier(0)
; template <class Epi, class Map>
; __device__ __forceinline__ void gemm_phase(LAS unsigned char* lds, const Gemm g, const Sched<Map>& S, const Epi& E) {
;     ...
;         for (int t = 0; t < nt; t += 2) {
;             const bool last = (t == nt - 2);
;             const char* a1 = cA + (size_t)(t + 1) * kstep;
;             const char* a2 = last ? nA : cA + (size_t)(t + 2) * kstep; const char* b2 = last ? nB : cB + (size_t)(t + 2) * kstep;
;             const char* a3 = a2 + kstep; const char* b3 = b2 + kstep;
;             PG8_LDB(B0, 0, 0); PG8_LDB(B1, 0, 1); PG8_SCHED; PG8_LDA(At, 0, 0); PG8_STAGE(PG8_SA(1, 1), a1 + hstepA, voffA);
;             PG8_WAIT_V(8); PG8_WAIT_L(0); PG8_BAR; PG8_MMA(0, 0, At, B0); PG8_MMA(0, 1, At, B1); PG8_BAR; PG8_SCHED;
;             PG8_LDA(At, 0, 1); PG8_STAGE(PG8_SB(0, 0), b2, voffB); PG8_STAGE(PG8_SB(0, 1), b2 + hstepB, voffB); PG8_STAGE(PG8_SA(0, 0), a2, voffA);
.LBB0_587:
	s_add_u32 s34, s30, 0xfff80080
	s_addc_u32 s35, s31, -1
	s_add_i32 s39, 0, 0x10000
	s_cmp_eq_u32 s38, 28
	s_cselect_b32 s37, s12, s35
	s_cselect_b32 s36, s13, s34
	v_add_u32_e32 v138, s39, v142
	s_cselect_b32 s35, s14, s33
	s_cselect_b32 s34, s15, s21
	s_add_i32 s46, 0, 0x14000
	ds_read_b128 v[160:163], v138
	ds_read_b128 v[164:167], v138 offset:1024
	ds_read_b128 v[168:171], v138 offset:2048
	ds_read_b128 v[172:175], v138 offset:3072
	v_add_u32_e32 v138, s46, v142
	ds_read_b128 v[176:179], v138
	ds_read_b128 v[192:195], v138 offset:1024
	ds_read_b128 v[196:199], v138 offset:2048
	ds_read_b128 v[200:203], v138 offset:3072
	v_lshl_add_u64 v[138:139], s[30:31], 0, v[134:135]
	s_add_i32 m0, s1, 0xc000
	ds_read_b128 v[204:207], v143
	ds_read_b128 v[208:211], v143 offset:1024
	ds_read_b128 v[212:215], v143 offset:2048
	ds_read_b128 v[216:219], v143 offset:3072
	ds_read_b128 v[220:223], v143 offset:4096
	ds_read_b128 v[224:227], v143 offset:5120
	ds_read_b128 v[228:231], v143 offset:6144
	ds_read_b128 v[232:235], v143 offset:7168
	global_load_lds_dwordx4 v[138:139], off
	v_lshl_add_u64 v[138:139], s[30:31], 0, v[136:137]
	s_add_i32 m0, s1, 0xe000
	s_nop 0
	global_load_lds_dwordx4 v[138:139], off
	s_waitcnt vmcnt(8)
	s_waitcnt lgkmcnt(0)
	s_barrier
	s_waitcnt lgkmcnt(0)
	v_mfma_f32_16x16x32_bf16 v[124:127], v[160:163], v[204:207], v[124:127]
	v_mfma_f32_16x16x32_bf16 v[120:123], v[168:171], v[204:207], v[120:123]
	v_mfma_f32_16x16x32_bf16 v[116:119], v[160:163], v[212:215], v[116:119]
	v_mfma_f32_16x16x32_bf16 v[108:111], v[168:171], v[212:215], v[108:111]
	v_mfma_f32_16x16x32_bf16 v[100:103], v[160:163], v[220:223], v[100:103]
	v_mfma_f32_16x16x32_bf16 v[92:95], v[168:171], v[220:223], v[92:95]
	v_mfma_f32_16x16x32_bf16 v[84:87], v[160:163], v[228:231], v[84:87]
	v_mfma_f32_16x16x32_bf16 v[76:79], v[168:171], v[228:231], v[76:79]
	v_mfma_f32_16x16x32_bf16 v[124:127], v[164:167], v[208:211], v[124:127]
	v_mfma_f32_16x16x32_bf16 v[120:123], v[172:175], v[208:211], v[120:123]
	v_mfma_f32_16x16x32_bf16 v[116:119], v[164:167], v[216:219], v[116:119]
	v_mfma_f32_16x16x32_bf16 v[108:111], v[172:175], v[216:219], v[108:111]
	v_mfma_f32_16x16x32_bf16 v[100:103], v[164:167], v[224:227], v[100:103]
	v_mfma_f32_16x16x32_bf16 v[92:95], v[172:175], v[224:227], v[92:95]
	v_mfma_f32_16x16x32_bf16 v[84:87], v[164:167], v[232:235], v[84:87]
	v_mfma_f32_16x16x32_bf16 v[76:79], v[172:175], v[232:235], v[76:79]
	v_mfma_f32_16x16x32_bf16 v[112:115], v[176:179], v[204:207], v[112:115]
	v_mfma_f32_16x16x32_bf16 v[104:107], v[196:199], v[204:207], v[104:107]
	v_mfma_f32_16x16x32_bf16 v[96:99], v[176:179], v[212:215], v[96:99]
	v_mfma_f32_16x16x32_bf16 v[88:91], v[196:199], v[212:215], v[88:91]
	v_mfma_f32_16x16x32_bf16 v[80:83], v[176:179], v[220:223], v[80:83]
	v_mfma_f32_16x16x32_bf16 v[72:75], v[196:199], v[220:223], v[72:75]
	v_mfma_f32_16x16x32_bf16 v[68:71], v[176:179], v[228:231], v[68:71]
	v_mfma_f32_16x16x32_bf16 v[64:67], v[196:199], v[228:231], v[64:67]
	v_mfma_f32_16x16x32_bf16 v[112:115], v[192:195], v[208:211], v[112:115]
	v_mfma_f32_16x16x32_bf16 v[104:107], v[200:203], v[208:211], v[104:107]
	v_mfma_f32_16x16x32_bf16 v[96:99], v[192:195], v[216:219], v[96:99]
	v_mfma_f32_16x16x32_bf16 v[88:91], v[200:203], v[216:219], v[88:91]
	v_mfma_f32_16x16x32_bf16 v[80:83], v[192:195], v[224:227], v[80:83]
	v_mfma_f32_16x16x32_bf16 v[72:75], v[200:203], v[224:227], v[72:75]
	v_mfma_f32_16x16x32_bf16 v[68:71], v[192:195], v[232:235], v[68:71]
	v_mfma_f32_16x16x32_bf16 v[64:67], v[200:203], v[232:235], v[64:67]
	s_barrier
	s_add_i32 s39, s39, s0
	v_lshl_add_u64 v[138:139], s[34:35], 0, v[144:145]
	s_mov_b32 m0, s39
	ds_read_b128 v[204:207], v143 offset:16384
	ds_read_b128 v[208:211], v143 offset:17408
	ds_read_b128 v[212:215], v143 offset:18432
	ds_read_b128 v[216:219], v143 offset:19456
	ds_read_b128 v[220:223], v143 offset:20480
	ds_read_b128 v[224:227], v143 offset:21504
	ds_read_b128 v[228:231], v143 offset:22528
	ds_read_b128 v[232:235], v143 offset:23552
	global_load_lds_dwordx4 v[138:139], off
	s_add_i32 m0, s39, 0x2000
	s_add_u32 s44, s34, 0x80000
	v_lshl_add_u64 v[180:181], s[34:35], 0, v[128:129]
	s_addc_u32 s45, s35, 0
	s_add_i32 s39, s46, s0
	global_load_lds_dwordx4 v[180:181], off
	v_lshl_add_u64 v[236:237], s[44:45], 0, v[144:145]
	s_mov_b32 m0, s39
	v_lshl_add_u64 v[238:239], s[36:37], 0, v[130:131]
	global_load_lds_dwordx4 v[236:237], off
	v_lshl_add_u64 v[236:237], s[44:45], 0, v[128:129]
	s_add_i32 m0, s39, 0x2000
	s_nop 0
	global_load_lds_dwordx4 v[236:237], off
	v_lshl_add_u64 v[236:237], s[36:37], 0, v[132:133]
	s_mov_b32 m0, s1
	s_nop 0
	global_load_lds_dwordx4 v[236:237], off
	s_mov_b32 m0, s2
	s_nop 0
	global_load_lds_dwordx4 v[238:239], off
	s_waitcnt vmcnt(8)
	s_waitcnt lgkmcnt(0)
	s_barrier
; #define PG8_STAGE(bufoff, gbase, voff) do { _Pragma("unroll") for (int _i = 0; _i < 2; ++_i) \
;         __builtin_amdgcn_global_load_lds((const unsigned*)((const char*)(gbase) + (voff)[_i]), (LAS unsigned*)(lds + (bufoff) + ldsw + _i * 8192), 16, 0, 0); } while (0)
; #define PG8_LDA(dst, b, h) do { _Pragma("unroll") for (int m = 0; m < 4; ++m) _Pragma("unroll") for (int k = 0; k < 2; ++k) dst[m][k] = *(const LAS bf16x8*)(lds + PG8_SA(b, h) + aoff + m * 2048 + k * 1024); } while (0)
; #define PG8_LDB(dst, b, h) do { _Pragma("unroll") for (int n = 0; n < 2; ++n) _Pragma("unroll") for (int k = 0; k < 2; ++k) dst[n][k] = *(const LAS bf16x8*)(lds + PG8_SB(b, h) + boff + n * 2048 + k * 1024); } while (0)
; #define PG8_MMA(ai, bj, At, Bt) do { __builtin_amdgcn_s_setprio(1); _Pragma("unroll") for (int m = 0; m < 4; ++m) _Pragma("unroll") for (int n = 0; n < 2; ++n) _Pragma("unroll") for (int k = 0; k < 2; ++k) \
;         acc[ai][bj][m][n] = __builtin_amdgcn_mfma_f32_16x16x32_bf16(Bt[n][k], At[m][k], acc[ai][bj][m][n], 0, 0, 0); __builtin_amdgcn_s_setprio(0); } while (0)
; #define PG8_WAIT_V(n) asm volatile("s_waitcnt vmcnt(" #n ")" ::: "memory")
; #define PG8_WAIT_L(n) asm volatile("s_waitcnt lgkmcnt(" #n ")" ::: "memory")
; #define PG8_BAR __builtin_amdgcn_s_barrier()
; #define PG8_SCHED __builtin_amdgcn_sched_barrier(0)
; template <class Epi, class Map>
; __device__ __forceinline__ void gemm_phase(LAS unsigned char* lds, const Gemm g, const Sched<Map>& S, const Epi& E) {
;     ...
;             PG8_WAIT_V(8); PG8_WAIT_L(0); PG8_BAR; PG8_MMA(1, 0, At, B0); PG8_MMA(1, 1, At, B1); PG8_BAR; PG8_SCHED;
;             PG8_LDB(B0, 1, 0); PG8_LDB(B1, 1, 1); PG8_SCHED; PG8_LDA(At, 1, 0); PG8_STAGE(PG8_SA(0, 1), a2 + hstepA, voffA);
;             PG8_WAIT_V(8); PG8_WAIT_L(0); PG8_BAR; PG8_MMA(0, 0, At, B0); PG8_MMA(0, 1, At, B1); PG8_BAR; PG8_SCHED;
	s_waitcnt lgkmcnt(0)
	v_mfma_f32_16x16x32_bf16 v[60:63], v[160:163], v[204:207], v[60:63]
	v_mfma_f32_16x16x32_bf16 v[56:59], v[168:171], v[204:207], v[56:59]
	v_mfma_f32_16x16x32_bf16 v[52:55], v[160:163], v[212:215], v[52:55]
	v_mfma_f32_16x16x32_bf16 v[44:47], v[168:171], v[212:215], v[44:47]
	v_mfma_f32_16x16x32_bf16 v[36:39], v[160:163], v[220:223], v[36:39]
	v_mfma_f32_16x16x32_bf16 v[28:31], v[168:171], v[220:223], v[28:31]
	v_mfma_f32_16x16x32_bf16 v[20:23], v[160:163], v[228:231], v[20:23]
	v_mfma_f32_16x16x32_bf16 v[12:15], v[168:171], v[228:231], v[12:15]
	v_mfma_f32_16x16x32_bf16 v[60:63], v[164:167], v[208:211], v[60:63]
	v_mfma_f32_16x16x32_bf16 v[56:59], v[172:175], v[208:211], v[56:59]
	v_mfma_f32_16x16x32_bf16 v[52:55], v[164:167], v[216:219], v[52:55]
	v_mfma_f32_16x16x32_bf16 v[44:47], v[172:175], v[216:219], v[44:47]
	v_mfma_f32_16x16x32_bf16 v[36:39], v[164:167], v[224:227], v[36:39]
	v_mfma_f32_16x16x32_bf16 v[28:31], v[172:175], v[224:227], v[28:31]
	v_mfma_f32_16x16x32_bf16 v[20:23], v[164:167], v[232:235], v[20:23]
	v_mfma_f32_16x16x32_bf16 v[12:15], v[172:175], v[232:235], v[12:15]
	v_mfma_f32_16x16x32_bf16 v[48:51], v[176:179], v[204:207], v[48:51]
	v_mfma_f32_16x16x32_bf16 v[40:43], v[196:199], v[204:207], v[40:43]
	v_mfma_f32_16x16x32_bf16 v[32:35], v[176:179], v[212:215], v[32:35]
	v_mfma_f32_16x16x32_bf16 v[24:27], v[196:199], v[212:215], v[24:27]
	v_mfma_f32_16x16x32_bf16 v[16:19], v[176:179], v[220:223], v[16:19]
	v_mfma_f32_16x16x32_bf16 v[8:11], v[196:199], v[220:223], v[8:11]
	v_mfma_f32_16x16x32_bf16 v[4:7], v[176:179], v[228:231], v[4:7]
	v_mfma_f32_16x16x32_bf16 v[0:3], v[196:199], v[228:231], v[0:3]
	v_mfma_f32_16x16x32_bf16 v[48:51], v[192:195], v[208:211], v[48:51]
	v_mfma_f32_16x16x32_bf16 v[40:43], v[200:203], v[208:211], v[40:43]
	v_mfma_f32_16x16x32_bf16 v[32:35], v[192:195], v[216:219], v[32:35]
	v_mfma_f32_16x16x32_bf16 v[24:27], v[200:203], v[216:219], v[24:27]
	v_mfma_f32_16x16x32_bf16 v[16:19], v[192:195], v[224:227], v[16:19]
	v_mfma_f32_16x16x32_bf16 v[8:11], v[200:203], v[224:227], v[8:11]
	v_mfma_f32_16x16x32_bf16 v[4:7], v[192:195], v[232:235], v[4:7]
	v_mfma_f32_16x16x32_bf16 v[0:3], v[200:203], v[232:235], v[0:3]
	s_barrier
	s_add_i32 s39, 0, 0x18000
	s_add_i32 s44, 0, 0x1c000
	v_add_u32_e32 v172, s39, v142
	v_add_u32_e32 v200, s44, v142
	ds_read_b128 v[160:163], v172
	ds_read_b128 v[164:167], v172 offset:1024
	ds_read_b128 v[168:171], v172 offset:2048
	ds_read_b128 v[172:175], v172 offset:3072
	ds_read_b128 v[176:179], v200
	ds_read_b128 v[192:195], v200 offset:1024
	ds_read_b128 v[196:199], v200 offset:2048
	ds_read_b128 v[200:203], v200 offset:3072
	s_add_u32 s36, s36, 0x80000
	s_addc_u32 s37, s37, 0
	s_mov_b32 m0, s3
	v_lshl_add_u64 v[240:241], s[36:37], 0, v[132:133]
	ds_read_b128 v[204:207], v143 offset:32768
	ds_read_b128 v[208:211], v143 offset:33792
	ds_read_b128 v[212:215], v143 offset:34816
	ds_read_b128 v[216:219], v143 offset:35840
	ds_read_b128 v[220:223], v143 offset:36864
	ds_read_b128 v[224:227], v143 offset:37888
	ds_read_b128 v[228:231], v143 offset:38912
	ds_read_b128 v[232:235], v143 offset:39936
	global_load_lds_dwordx4 v[240:241], off
	v_lshl_add_u64 v[240:241], s[36:37], 0, v[130:131]
	s_mov_b32 m0, s4
	s_nop 0
	global_load_lds_dwordx4 v[240:241], off
	s_waitcnt vmcnt(8)
	s_waitcnt lgkmcnt(0)
	s_barrier
	s_waitcnt lgkmcnt(0)
	v_mfma_f32_16x16x32_bf16 v[124:127], v[160:163], v[204:207], v[124:127]
	v_mfma_f32_16x16x32_bf16 v[120:123], v[168:171], v[204:207], v[120:123]
	v_mfma_f32_16x16x32_bf16 v[116:119], v[160:163], v[212:215], v[116:119]
	v_mfma_f32_16x16x32_bf16 v[108:111], v[168:171], v[212:215], v[108:111]
	v_mfma_f32_16x16x32_bf16 v[100:103], v[160:163], v[220:223], v[100:103]
	v_mfma_f32_16x16x32_bf16 v[92:95], v[168:171], v[220:223], v[92:95]
	v_mfma_f32_16x16x32_bf16 v[84:87], v[160:163], v[228:231], v[84:87]
	v_mfma_f32_16x16x32_bf16 v[76:79], v[168:171], v[228:231], v[76:79]
	v_mfma_f32_16x16x32_bf16 v[124:127], v[164:167], v[208:211], v[124:127]
	v_mfma_f32_16x16x32_bf16 v[120:123], v[172:175], v[208:211], v[120:123]
	v_mfma_f32_16x16x32_bf16 v[116:119], v[164:167], v[216:219], v[116:119]
	v_mfma_f32_16x16x32_bf16 v[108:111], v[172:175], v[216:219], v[108:111]
	v_mfma_f32_16x16x32_bf16 v[100:103], v[164:167], v[224:227], v[100:103]
	v_mfma_f32_16x16x32_bf16 v[92:95], v[172:175], v[224:227], v[92:95]
	v_mfma_f32_16x16x32_bf16 v[84:87], v[164:167], v[232:235], v[84:87]
	v_mfma_f32_16x16x32_bf16 v[76:79], v[172:175], v[232:235], v[76:79]
	v_mfma_f32_16x16x32_bf16 v[112:115], v[176:179], v[204:207], v[112:115]
	v_mfma_f32_16x16x32_bf16 v[104:107], v[196:199], v[204:207], v[104:107]
	v_mfma_f32_16x16x32_bf16 v[96:99], v[176:179], v[212:215], v[96:99]
	v_mfma_f32_16x16x32_bf16 v[88:91], v[196:199], v[212:215], v[88:91]
	v_mfma_f32_16x16x32_bf16 v[80:83], v[176:179], v[220:223], v[80:83]
	v_mfma_f32_16x16x32_bf16 v[72:75], v[196:199], v[220:223], v[72:75]
	v_mfma_f32_16x16x32_bf16 v[68:71], v[176:179], v[228:231], v[68:71]
	v_mfma_f32_16x16x32_bf16 v[64:67], v[196:199], v[228:231], v[64:67]
	v_mfma_f32_16x16x32_bf16 v[112:115], v[192:195], v[208:211], v[112:115]
	v_mfma_f32_16x16x32_bf16 v[104:107], v[200:203], v[208:211], v[104:107]
	v_mfma_f32_16x16x32_bf16 v[96:99], v[192:195], v[216:219], v[96:99]
	v_mfma_f32_16x16x32_bf16 v[88:91], v[200:203], v[216:219], v[88:91]
	v_mfma_f32_16x16x32_bf16 v[80:83], v[192:195], v[224:227], v[80:83]
	v_mfma_f32_16x16x32_bf16 v[72:75], v[200:203], v[224:227], v[72:75]
	v_mfma_f32_16x16x32_bf16 v[68:71], v[192:195], v[232:235], v[68:71]
	v_mfma_f32_16x16x32_bf16 v[64:67], v[200:203], v[232:235], v[64:67]
	s_barrier
; #define PG8_STAGE(bufoff, gbase, voff) do { _Pragma("unroll") for (int _i = 0; _i < 2; ++_i) \
;         __builtin_amdgcn_global_load_lds((const unsigned*)((const char*)(gbase) + (voff)[_i]), (LAS unsigned*)(lds + (bufoff) + ldsw + _i * 8192), 16, 0, 0); } while (0)
; #define PG8_LDA(dst, b, h) do { _Pragma("unroll") for (int m = 0; m < 4; ++m) _Pragma("unroll") for (int k = 0; k < 2; ++k) dst[m][k] = *(const LAS bf16x8*)(lds + PG8_SA(b, h) + aoff + m * 2048 + k * 1024); } while (0)
; #define PG8_MMA(ai, bj, At, Bt) do { __builtin_amdgcn_s_setprio(1); _Pragma("unroll") for (int m = 0; m < 4; ++m) _Pragma("unroll") for (int n = 0; n < 2; ++n) _Pragma("unroll") for (int k = 0; k < 2; ++k) \
;         acc[ai][bj][m][n] = __builtin_amdgcn_mfma_f32_16x16x32_bf16(Bt[n][k], At[m][k], acc[ai][bj][m][n], 0, 0, 0); __builtin_amdgcn_s_setprio(0); } while (0)
; #define PG8_WAIT_V(n) asm volatile("s_waitcnt vmcnt(" #n ")" ::: "memory")
; #define PG8_WAIT_L(n) asm volatile("s_waitcnt lgkmcnt(" #n ")" ::: "memory")
; #define PG8_BAR __builtin_amdgcn_s_barrier()
; #define PG8_SCHED __builtin_amdgcn_sched_barrier(0)
; template <class Epi, class Map>
; __device__ __forceinline__ void gemm_phase(LAS unsigned char* lds, const Gemm g, const Sched<Map>& S, const Epi& E) {
;     ...
;             PG8_LDA(At, 1, 1); PG8_STAGE(PG8_SB(1, 0), b3, voffB); PG8_STAGE(PG8_SB(1, 1), b3 + hstepB, voffB); PG8_STAGE(PG8_SA(1, 0), a3, voffA);
;             PG8_WAIT_V(8); PG8_WAIT_L(0); PG8_BAR; PG8_MMA(1, 0, At, B0); PG8_MMA(1, 1, At, B1); PG8_BAR; PG8_SCHED;
;         }
;         if (wr == 0) PG8_BAR;
	s_add_i32 s36, s39, s0
	v_lshl_add_u64 v[138:139], v[138:139], 0, s[82:83]
	s_mov_b32 m0, s36
	ds_read_b128 v[204:207], v143 offset:49152
	ds_read_b128 v[208:211], v143 offset:50176
	ds_read_b128 v[212:215], v143 offset:51200
	ds_read_b128 v[216:219], v143 offset:52224
	ds_read_b128 v[220:223], v143 offset:53248
	ds_read_b128 v[224:227], v143 offset:54272
	ds_read_b128 v[228:231], v143 offset:55296
	ds_read_b128 v[232:235], v143 offset:56320
	global_load_lds_dwordx4 v[138:139], off
	s_add_i32 m0, s36, 0x2000
	s_add_u32 s34, s34, 0x80080
	v_lshl_add_u64 v[138:139], v[180:181], 0, s[82:83]
	s_addc_u32 s35, s35, 0
	s_add_i32 s36, s44, s0
	global_load_lds_dwordx4 v[138:139], off
	v_lshl_add_u64 v[138:139], s[34:35], 0, v[144:145]
	s_mov_b32 m0, s36
	s_nop 0
	global_load_lds_dwordx4 v[138:139], off
	v_lshl_add_u64 v[138:139], s[34:35], 0, v[128:129]
	s_add_i32 m0, s36, 0x2000
	s_nop 0
	global_load_lds_dwordx4 v[138:139], off
	v_lshl_add_u64 v[138:139], v[236:237], 0, s[82:83]
	s_mov_b32 m0, s6
	s_nop 0
	global_load_lds_dwordx4 v[138:139], off
	v_lshl_add_u64 v[138:139], v[238:239], 0, s[82:83]
	s_mov_b32 m0, s7
	s_nop 0
	global_load_lds_dwordx4 v[138:139], off
	s_waitcnt vmcnt(8)
	s_waitcnt lgkmcnt(0)
	s_barrier
	s_waitcnt lgkmcnt(0)
	v_mfma_f32_16x16x32_bf16 v[60:63], v[160:163], v[204:207], v[60:63]
	v_mfma_f32_16x16x32_bf16 v[56:59], v[168:171], v[204:207], v[56:59]
	v_mfma_f32_16x16x32_bf16 v[52:55], v[160:163], v[212:215], v[52:55]
	v_mfma_f32_16x16x32_bf16 v[44:47], v[168:171], v[212:215], v[44:47]
	v_mfma_f32_16x16x32_bf16 v[36:39], v[160:163], v[220:223], v[36:39]
	v_mfma_f32_16x16x32_bf16 v[28:31], v[168:171], v[220:223], v[28:31]
	v_mfma_f32_16x16x32_bf16 v[20:23], v[160:163], v[228:231], v[20:23]
	v_mfma_f32_16x16x32_bf16 v[12:15], v[168:171], v[228:231], v[12:15]
	v_mfma_f32_16x16x32_bf16 v[60:63], v[164:167], v[208:211], v[60:63]
	v_mfma_f32_16x16x32_bf16 v[56:59], v[172:175], v[208:211], v[56:59]
	v_mfma_f32_16x16x32_bf16 v[52:55], v[164:167], v[216:219], v[52:55]
	v_mfma_f32_16x16x32_bf16 v[44:47], v[172:175], v[216:219], v[44:47]
	v_mfma_f32_16x16x32_bf16 v[36:39], v[164:167], v[224:227], v[36:39]
	v_mfma_f32_16x16x32_bf16 v[28:31], v[172:175], v[224:227], v[28:31]
	v_mfma_f32_16x16x32_bf16 v[20:23], v[164:167], v[232:235], v[20:23]
	v_mfma_f32_16x16x32_bf16 v[12:15], v[172:175], v[232:235], v[12:15]
	v_mfma_f32_16x16x32_bf16 v[48:51], v[176:179], v[204:207], v[48:51]
	v_mfma_f32_16x16x32_bf16 v[40:43], v[196:199], v[204:207], v[40:43]
	v_mfma_f32_16x16x32_bf16 v[32:35], v[176:179], v[212:215], v[32:35]
	v_mfma_f32_16x16x32_bf16 v[24:27], v[196:199], v[212:215], v[24:27]
	v_mfma_f32_16x16x32_bf16 v[16:19], v[176:179], v[220:223], v[16:19]
	v_mfma_f32_16x16x32_bf16 v[8:11], v[196:199], v[220:223], v[8:11]
	v_mfma_f32_16x16x32_bf16 v[4:7], v[176:179], v[228:231], v[4:7]
	v_mfma_f32_16x16x32_bf16 v[0:3], v[196:199], v[228:231], v[0:3]
	v_mfma_f32_16x16x32_bf16 v[48:51], v[192:195], v[208:211], v[48:51]
	v_mfma_f32_16x16x32_bf16 v[40:43], v[200:203], v[208:211], v[40:43]
	v_mfma_f32_16x16x32_bf16 v[32:35], v[192:195], v[216:219], v[32:35]
	v_mfma_f32_16x16x32_bf16 v[24:27], v[200:203], v[216:219], v[24:27]
	v_mfma_f32_16x16x32_bf16 v[16:19], v[192:195], v[224:227], v[16:19]
	v_mfma_f32_16x16x32_bf16 v[8:11], v[200:203], v[224:227], v[8:11]
	v_mfma_f32_16x16x32_bf16 v[4:7], v[192:195], v[232:235], v[4:7]
	v_mfma_f32_16x16x32_bf16 v[0:3], v[200:203], v[232:235], v[0:3]
	s_barrier
	s_add_i32 s38, s38, 2
	s_add_u32 s30, s30, 0x100
	s_addc_u32 s31, s31, 0
	s_add_u32 s21, s21, 0x100
	s_addc_u32 s33, s33, 0
	s_cmp_gt_u32 s38, 29
	s_cbranch_scc0 .LBB0_587
	s_and_b64 vcc, exec, s[18:19]
	s_cbranch_vccz .LBB0_590
	s_barrier

; #define PG8_STAGE(bufoff, gbase, voff) do { _Pragma("unroll") for (int _i = 0; _i < 2; ++_i) \
;         __builtin_amdgcn_global_load_lds((const unsigned*)((const char*)(gbase) + (voff)[_i]), (LAS unsigned*)(lds + (bufoff) + ldsw + _i * 8192), 16, 0, 0); } while (0)
; #define PG8_LDA(dst, b, h) do { _Pragma("unroll") for (int m = 0; m < 4; ++m) _Pragma("unroll") for (int k = 0; k < 2; ++k) dst[m][k] = *(const LAS bf16x8*)(lds + PG8_SA(b, h) + aoff + m * 2048 + k * 1024); } while (0)
; #define PG8_LDB(dst, b, h) do { _Pragma("unroll") for (int n = 0; n < 2; ++n) _Pragma("unroll") for (int k = 0; k < 2; ++k) dst[n][k] = *(const LAS bf16x8*)(lds + PG8_SB(b, h) + boff + n * 2048 + k * 1024); } while (0)
; #define PG8_MMA(ai, bj, At, Bt) do { __builtin_amdgcn_s_setprio(1); _Pragma("unroll") for (int m = 0; m < 4; ++m) _Pragma("unroll") for (int n = 0; n < 2; ++n) _Pragma("unroll") for (int k = 0; k < 2; ++k) \
;         acc[ai][bj][m][n] = __builtin_amdgcn_mfma_f32_16x16x32_bf16(Bt[n][k], At[m][k], acc[ai][bj][m][n], 0, 0, 0); __builtin_amdgcn_s_setprio(0); } while (0)
; #define PG8_WAIT_V(n) asm volatile("s_waitcnt vmcnt(" #n ")" ::: "memory")
; #define PG8_WAIT_L(n) asm volatile("s_waitcnt lgkmcnt(" #n ")" ::: "memory")
; #define PG8_BAR __builtin_amdgcn_s_barrier()
; #define PG8_SCHED __builtin_amdgcn_sched_barrier(0)
; template <class Epi, class Map>
; __device__ __forceinline__ void gemm_phase(LAS unsigned char* lds, const Gemm g, const Sched<Map>& S, const Epi& E) {
;     ...
;         for (int t = 0; t < nt; t += 2) {
;             const bool last = (t == nt - 2);
;             const char* a1 = cA + (size_t)(t + 1) * kstep;
;             const char* a2 = last ? nA : cA + (size_t)(t + 2) * kstep; const char* b2 = last ? nB : cB + (size_t)(t + 2) * kstep;
;             const char* a3 = a2 + kstep; const char* b3 = b2 + kstep;
;             PG8_LDB(B0, 0, 0); PG8_LDB(B1, 0, 1); PG8_SCHED; PG8_LDA(At, 0, 0); PG8_STAGE(PG8_SA(1, 1), a1 + hstepA, voffA);
;             PG8_WAIT_V(8); PG8_WAIT_L(0); PG8_BAR; PG8_MMA(0, 0, At, B0); PG8_MMA(0, 1, At, B1); PG8_BAR; PG8_SCHED;
;             PG8_LDA(At, 0, 1); PG8_STAGE(PG8_SB(0, 0), b2, voffB); PG8_STAGE(PG8_SB(0, 1), b2 + hstepB, voffB); PG8_STAGE(PG8_SA(0, 0), a2, voffA);
.LBB0_659:
	s_add_u32 s50, s30, s44
	s_addc_u32 s51, s31, s45
	s_add_u32 s48, s50, 0x100
	s_addc_u32 s49, s51, 0
	s_and_b64 s[46:47], s[36:37], exec
	s_cselect_b32 s47, s15, s49
	s_cselect_b32 s46, s33, s48
	s_add_u32 s44, s28, s44
	s_addc_u32 s45, s29, s45
	s_add_u32 s44, s44, 0x100
	s_addc_u32 s45, s45, 0
	s_add_i32 s62, 0, 0x10000
	s_and_b64 s[36:37], s[36:37], exec
	s_cselect_b32 s49, s38, s45
	s_cselect_b32 s48, s39, s44
	s_add_i32 s37, 0, 0x14000
	s_add_u32 s52, s50, 0x20080
	s_addc_u32 s53, s51, 0
	s_add_i32 s66, s62, s0
	s_add_i32 m0, s1, 0xc000
	s_add_i32 s63, s1, 0xe000
	s_add_i32 s58, s66, 0x2000
	v_add_u32_e32 v142, s62, v140
	s_add_u32 s50, s48, 0x10000
	ds_read_b128 v[134:137], v142
	ds_read_b128 v[160:163], v142 offset:1024
	ds_read_b128 v[164:167], v142 offset:2048
	ds_read_b128 v[168:171], v142 offset:3072
	v_add_u32_e32 v142, s37, v140
	s_addc_u32 s51, s49, 0
	s_add_i32 s65, s37, s0
	ds_read_b128 v[172:175], v142
	ds_read_b128 v[176:179], v142 offset:1024
	ds_read_b128 v[192:195], v142 offset:2048
	ds_read_b128 v[196:199], v142 offset:3072
	s_add_i32 s59, s65, 0x2000
	s_add_i32 s57, 0, 0x18000
	s_add_i32 s56, 0, 0x1c000
	s_add_u32 s44, s46, 0x20000
	s_addc_u32 s45, s47, 0
	s_add_i32 s55, s57, s0
	s_add_i32 s54, s55, 0x2000
	s_add_u32 s36, s48, 0x10080
	s_addc_u32 s37, s49, 0
	s_add_i32 s68, s56, s0
	s_add_i32 s67, s68, 0x2000
	v_lshl_add_u64 v[142:143], s[52:53], 0, v[132:133]
	ds_read_b128 v[200:203], v141
	ds_read_b128 v[204:207], v141 offset:1024
	ds_read_b128 v[208:211], v141 offset:2048
	ds_read_b128 v[212:215], v141 offset:3072
	ds_read_b128 v[216:219], v141 offset:4096
	ds_read_b128 v[220:223], v141 offset:5120
	ds_read_b128 v[224:227], v141 offset:6144
	ds_read_b128 v[228:231], v141 offset:7168
	global_load_lds_dwordx4 v[142:143], off
	v_lshl_add_u64 v[142:143], s[52:53], 0, v[130:131]
	s_mov_b32 m0, s63
	s_nop 0
	global_load_lds_dwordx4 v[142:143], off
	s_waitcnt vmcnt(8)
	s_waitcnt lgkmcnt(0)
	s_barrier
	s_waitcnt lgkmcnt(0)
	v_mfma_f32_16x16x32_bf16 v[124:127], v[134:137], v[200:203], v[124:127]
	v_mfma_f32_16x16x32_bf16 v[120:123], v[164:167], v[200:203], v[120:123]
	v_mfma_f32_16x16x32_bf16 v[116:119], v[134:137], v[208:211], v[116:119]
	v_mfma_f32_16x16x32_bf16 v[112:115], v[164:167], v[208:211], v[112:115]
	v_mfma_f32_16x16x32_bf16 v[108:111], v[134:137], v[216:219], v[108:111]
	v_mfma_f32_16x16x32_bf16 v[104:107], v[164:167], v[216:219], v[104:107]
	v_mfma_f32_16x16x32_bf16 v[100:103], v[134:137], v[224:227], v[100:103]
	v_mfma_f32_16x16x32_bf16 v[96:99], v[164:167], v[224:227], v[96:99]
	v_mfma_f32_16x16x32_bf16 v[124:127], v[160:163], v[204:207], v[124:127]
	v_mfma_f32_16x16x32_bf16 v[120:123], v[168:171], v[204:207], v[120:123]
	v_mfma_f32_16x16x32_bf16 v[116:119], v[160:163], v[212:215], v[116:119]
	v_mfma_f32_16x16x32_bf16 v[112:115], v[168:171], v[212:215], v[112:115]
	v_mfma_f32_16x16x32_bf16 v[108:111], v[160:163], v[220:223], v[108:111]
	v_mfma_f32_16x16x32_bf16 v[104:107], v[168:171], v[220:223], v[104:107]
	v_mfma_f32_16x16x32_bf16 v[100:103], v[160:163], v[228:231], v[100:103]
	v_mfma_f32_16x16x32_bf16 v[96:99], v[168:171], v[228:231], v[96:99]
	v_mfma_f32_16x16x32_bf16 v[60:63], v[172:175], v[200:203], v[60:63]
	v_mfma_f32_16x16x32_bf16 v[56:59], v[192:195], v[200:203], v[56:59]
	v_mfma_f32_16x16x32_bf16 v[52:55], v[172:175], v[208:211], v[52:55]
	v_mfma_f32_16x16x32_bf16 v[48:51], v[192:195], v[208:211], v[48:51]
	v_mfma_f32_16x16x32_bf16 v[44:47], v[172:175], v[216:219], v[44:47]
	v_mfma_f32_16x16x32_bf16 v[40:43], v[192:195], v[216:219], v[40:43]
	v_mfma_f32_16x16x32_bf16 v[36:39], v[172:175], v[224:227], v[36:39]
	v_mfma_f32_16x16x32_bf16 v[32:35], v[192:195], v[224:227], v[32:35]
	v_mfma_f32_16x16x32_bf16 v[60:63], v[176:179], v[204:207], v[60:63]
	v_mfma_f32_16x16x32_bf16 v[56:59], v[196:199], v[204:207], v[56:59]
	v_mfma_f32_16x16x32_bf16 v[52:55], v[176:179], v[212:215], v[52:55]
	v_mfma_f32_16x16x32_bf16 v[48:51], v[196:199], v[212:215], v[48:51]
	v_mfma_f32_16x16x32_bf16 v[44:47], v[176:179], v[220:223], v[44:47]
	v_mfma_f32_16x16x32_bf16 v[40:43], v[196:199], v[220:223], v[40:43]
	v_mfma_f32_16x16x32_bf16 v[36:39], v[176:179], v[228:231], v[36:39]
	v_mfma_f32_16x16x32_bf16 v[32:35], v[196:199], v[228:231], v[32:35]
	s_barrier
	s_mov_b32 m0, s66
	v_lshl_add_u64 v[142:143], s[48:49], 0, v[144:145]
	ds_read_b128 v[200:203], v141 offset:16384
	ds_read_b128 v[204:207], v141 offset:17408
	ds_read_b128 v[208:211], v141 offset:18432
	ds_read_b128 v[212:215], v141 offset:19456
	ds_read_b128 v[216:219], v141 offset:20480
	ds_read_b128 v[220:223], v141 offset:21504
	ds_read_b128 v[224:227], v141 offset:22528
	ds_read_b128 v[228:231], v141 offset:23552
	global_load_lds_dwordx4 v[142:143], off
	v_lshl_add_u64 v[180:181], s[48:49], 0, v[128:129]
	s_mov_b32 m0, s58
	v_lshl_add_u64 v[232:233], s[50:51], 0, v[144:145]
	global_load_lds_dwordx4 v[180:181], off
	s_mov_b32 m0, s65
	v_lshl_add_u64 v[234:235], s[46:47], 0, v[130:131]
	global_load_lds_dwordx4 v[232:233], off
	v_lshl_add_u64 v[232:233], s[50:51], 0, v[128:129]
	s_mov_b32 m0, s59
	s_nop 0
	global_load_lds_dwordx4 v[232:233], off
	v_lshl_add_u64 v[232:233], s[46:47], 0, v[132:133]
	s_mov_b32 m0, s1
	s_nop 0
	global_load_lds_dwordx4 v[232:233], off
	s_mov_b32 m0, s2
	s_nop 0
	global_load_lds_dwordx4 v[234:235], off
	s_waitcnt vmcnt(8)
	s_waitcnt lgkmcnt(0)
	s_barrier
; #define PG8_STAGE(bufoff, gbase, voff) do { _Pragma("unroll") for (int _i = 0; _i < 2; ++_i) \
;         __builtin_amdgcn_global_load_lds((const unsigned*)((const char*)(gbase) + (voff)[_i]), (LAS unsigned*)(lds + (bufoff) + ldsw + _i * 8192), 16, 0, 0); } while (0)
; #define PG8_LDA(dst, b, h) do { _Pragma("unroll") for (int m = 0; m < 4; ++m) _Pragma("unroll") for (int k = 0; k < 2; ++k) dst[m][k] = *(const LAS bf16x8*)(lds + PG8_SA(b, h) + aoff + m * 2048 + k * 1024); } while (0)
; #define PG8_LDB(dst, b, h) do { _Pragma("unroll") for (int n = 0; n < 2; ++n) _Pragma("unroll") for (int k = 0; k < 2; ++k) dst[n][k] = *(const LAS bf16x8*)(lds + PG8_SB(b, h) + boff + n * 2048 + k * 1024); } while (0)
; #define PG8_MMA(ai, bj, At, Bt) do { __builtin_amdgcn_s_setprio(1); _Pragma("unroll") for (int m = 0; m < 4; ++m) _Pragma("unroll") for (int n = 0; n < 2; ++n) _Pragma("unroll") for (int k = 0; k < 2; ++k) \
;         acc[ai][bj][m][n] = __builtin_amdgcn_mfma_f32_16x16x32_bf16(Bt[n][k], At[m][k], acc[ai][bj][m][n], 0, 0, 0); __builtin_amdgcn_s_setprio(0); } while (0)
; #define PG8_WAIT_V(n) asm volatile("s_waitcnt vmcnt(" #n ")" ::: "memory")
; #define PG8_WAIT_L(n) asm volatile("s_waitcnt lgkmcnt(" #n ")" ::: "memory")
; #define PG8_BAR __builtin_amdgcn_s_barrier()
; #define PG8_SCHED __builtin_amdgcn_sched_barrier(0)
; template <class Epi, class Map>
; __device__ __forceinline__ void gemm_phase(LAS unsigned char* lds, const Gemm g, const Sched<Map>& S, const Epi& E) {
;     ...
;             PG8_WAIT_V(8); PG8_WAIT_L(0); PG8_BAR; PG8_MMA(1, 0, At, B0); PG8_MMA(1, 1, At, B1); PG8_BAR; PG8_SCHED;
;             PG8_LDB(B0, 1, 0); PG8_LDB(B1, 1, 1); PG8_SCHED; PG8_LDA(At, 1, 0); PG8_STAGE(PG8_SA(0, 1), a2 + hstepA, voffA);
;             PG8_WAIT_V(8); PG8_WAIT_L(0); PG8_BAR; PG8_MMA(0, 0, At, B0); PG8_MMA(0, 1, At, B1); PG8_BAR; PG8_SCHED;
	s_waitcnt lgkmcnt(0)
	v_mfma_f32_16x16x32_bf16 v[92:95], v[134:137], v[200:203], v[92:95]
	v_mfma_f32_16x16x32_bf16 v[88:91], v[164:167], v[200:203], v[88:91]
	v_mfma_f32_16x16x32_bf16 v[84:87], v[134:137], v[208:211], v[84:87]
	v_mfma_f32_16x16x32_bf16 v[80:83], v[164:167], v[208:211], v[80:83]
	v_mfma_f32_16x16x32_bf16 v[76:79], v[134:137], v[216:219], v[76:79]
	v_mfma_f32_16x16x32_bf16 v[72:75], v[164:167], v[216:219], v[72:75]
	v_mfma_f32_16x16x32_bf16 v[68:71], v[134:137], v[224:227], v[68:71]
	v_mfma_f32_16x16x32_bf16 v[64:67], v[164:167], v[224:227], v[64:67]
	v_mfma_f32_16x16x32_bf16 v[92:95], v[160:163], v[204:207], v[92:95]
	v_mfma_f32_16x16x32_bf16 v[88:91], v[168:171], v[204:207], v[88:91]
	v_mfma_f32_16x16x32_bf16 v[84:87], v[160:163], v[212:215], v[84:87]
	v_mfma_f32_16x16x32_bf16 v[80:83], v[168:171], v[212:215], v[80:83]
	v_mfma_f32_16x16x32_bf16 v[76:79], v[160:163], v[220:223], v[76:79]
	v_mfma_f32_16x16x32_bf16 v[72:75], v[168:171], v[220:223], v[72:75]
	v_mfma_f32_16x16x32_bf16 v[68:71], v[160:163], v[228:231], v[68:71]
	v_mfma_f32_16x16x32_bf16 v[64:67], v[168:171], v[228:231], v[64:67]
	v_mfma_f32_16x16x32_bf16 v[28:31], v[172:175], v[200:203], v[28:31]
	v_mfma_f32_16x16x32_bf16 v[24:27], v[192:195], v[200:203], v[24:27]
	v_mfma_f32_16x16x32_bf16 v[20:23], v[172:175], v[208:211], v[20:23]
	v_mfma_f32_16x16x32_bf16 v[16:19], v[192:195], v[208:211], v[16:19]
	v_mfma_f32_16x16x32_bf16 v[12:15], v[172:175], v[216:219], v[12:15]
	v_mfma_f32_16x16x32_bf16 v[8:11], v[192:195], v[216:219], v[8:11]
	v_mfma_f32_16x16x32_bf16 v[4:7], v[172:175], v[224:227], v[4:7]
	v_mfma_f32_16x16x32_bf16 v[0:3], v[192:195], v[224:227], v[0:3]
	v_mfma_f32_16x16x32_bf16 v[28:31], v[176:179], v[204:207], v[28:31]
	v_mfma_f32_16x16x32_bf16 v[24:27], v[196:199], v[204:207], v[24:27]
	v_mfma_f32_16x16x32_bf16 v[20:23], v[176:179], v[212:215], v[20:23]
	v_mfma_f32_16x16x32_bf16 v[16:19], v[196:199], v[212:215], v[16:19]
	v_mfma_f32_16x16x32_bf16 v[12:15], v[176:179], v[220:223], v[12:15]
	v_mfma_f32_16x16x32_bf16 v[8:11], v[196:199], v[220:223], v[8:11]
	v_mfma_f32_16x16x32_bf16 v[4:7], v[176:179], v[228:231], v[4:7]
	v_mfma_f32_16x16x32_bf16 v[0:3], v[196:199], v[228:231], v[0:3]
	s_barrier
	v_add_u32_e32 v168, s57, v140
	v_add_u32_e32 v196, s56, v140
	ds_read_b128 v[134:137], v168
	ds_read_b128 v[160:163], v168 offset:1024
	ds_read_b128 v[164:167], v168 offset:2048
	ds_read_b128 v[168:171], v168 offset:3072
	ds_read_b128 v[172:175], v196
	ds_read_b128 v[176:179], v196 offset:1024
	ds_read_b128 v[192:195], v196 offset:2048
	ds_read_b128 v[196:199], v196 offset:3072
	s_mov_b32 m0, s3
	v_lshl_add_u64 v[236:237], s[44:45], 0, v[132:133]
	ds_read_b128 v[200:203], v141 offset:32768
	ds_read_b128 v[204:207], v141 offset:33792
	ds_read_b128 v[208:211], v141 offset:34816
	ds_read_b128 v[212:215], v141 offset:35840
	ds_read_b128 v[216:219], v141 offset:36864
	ds_read_b128 v[220:223], v141 offset:37888
	ds_read_b128 v[224:227], v141 offset:38912
	ds_read_b128 v[228:231], v141 offset:39936
	global_load_lds_dwordx4 v[236:237], off
	v_lshl_add_u64 v[236:237], s[44:45], 0, v[130:131]
	s_mov_b32 m0, s4
	s_nop 0
	global_load_lds_dwordx4 v[236:237], off
	s_waitcnt vmcnt(8)
	s_waitcnt lgkmcnt(0)
	s_barrier
	s_waitcnt lgkmcnt(0)
	v_mfma_f32_16x16x32_bf16 v[124:127], v[134:137], v[200:203], v[124:127]
	v_mfma_f32_16x16x32_bf16 v[120:123], v[164:167], v[200:203], v[120:123]
	v_mfma_f32_16x16x32_bf16 v[116:119], v[134:137], v[208:211], v[116:119]
	v_mfma_f32_16x16x32_bf16 v[112:115], v[164:167], v[208:211], v[112:115]
	v_mfma_f32_16x16x32_bf16 v[108:111], v[134:137], v[216:219], v[108:111]
	v_mfma_f32_16x16x32_bf16 v[104:107], v[164:167], v[216:219], v[104:107]
	v_mfma_f32_16x16x32_bf16 v[100:103], v[134:137], v[224:227], v[100:103]
	v_mfma_f32_16x16x32_bf16 v[96:99], v[164:167], v[224:227], v[96:99]
	v_mfma_f32_16x16x32_bf16 v[124:127], v[160:163], v[204:207], v[124:127]
	v_mfma_f32_16x16x32_bf16 v[120:123], v[168:171], v[204:207], v[120:123]
	v_mfma_f32_16x16x32_bf16 v[116:119], v[160:163], v[212:215], v[116:119]
	v_mfma_f32_16x16x32_bf16 v[112:115], v[168:171], v[212:215], v[112:115]
	v_mfma_f32_16x16x32_bf16 v[108:111], v[160:163], v[220:223], v[108:111]
	v_mfma_f32_16x16x32_bf16 v[104:107], v[168:171], v[220:223], v[104:107]
	v_mfma_f32_16x16x32_bf16 v[100:103], v[160:163], v[228:231], v[100:103]
	v_mfma_f32_16x16x32_bf16 v[96:99], v[168:171], v[228:231], v[96:99]
	v_mfma_f32_16x16x32_bf16 v[60:63], v[172:175], v[200:203], v[60:63]
	v_mfma_f32_16x16x32_bf16 v[56:59], v[192:195], v[200:203], v[56:59]
	v_mfma_f32_16x16x32_bf16 v[52:55], v[172:175], v[208:211], v[52:55]
	v_mfma_f32_16x16x32_bf16 v[48:51], v[192:195], v[208:211], v[48:51]
	v_mfma_f32_16x16x32_bf16 v[44:47], v[172:175], v[216:219], v[44:47]
	v_mfma_f32_16x16x32_bf16 v[40:43], v[192:195], v[216:219], v[40:43]
	v_mfma_f32_16x16x32_bf16 v[36:39], v[172:175], v[224:227], v[36:39]
	v_mfma_f32_16x16x32_bf16 v[32:35], v[192:195], v[224:227], v[32:35]
	v_mfma_f32_16x16x32_bf16 v[60:63], v[176:179], v[204:207], v[60:63]
	v_mfma_f32_16x16x32_bf16 v[56:59], v[196:199], v[204:207], v[56:59]
	v_mfma_f32_16x16x32_bf16 v[52:55], v[176:179], v[212:215], v[52:55]
	v_mfma_f32_16x16x32_bf16 v[48:51], v[196:199], v[212:215], v[48:51]
	v_mfma_f32_16x16x32_bf16 v[44:47], v[176:179], v[220:223], v[44:47]
	v_mfma_f32_16x16x32_bf16 v[40:43], v[196:199], v[220:223], v[40:43]
	v_mfma_f32_16x16x32_bf16 v[36:39], v[176:179], v[228:231], v[36:39]
	v_mfma_f32_16x16x32_bf16 v[32:35], v[196:199], v[228:231], v[32:35]
	s_barrier
; #define PG8_STAGE(bufoff, gbase, voff) do { _Pragma("unroll") for (int _i = 0; _i < 2; ++_i) \
;         __builtin_amdgcn_global_load_lds((const unsigned*)((const char*)(gbase) + (voff)[_i]), (LAS unsigned*)(lds + (bufoff) + ldsw + _i * 8192), 16, 0, 0); } while (0)
; #define PG8_LDA(dst, b, h) do { _Pragma("unroll") for (int m = 0; m < 4; ++m) _Pragma("unroll") for (int k = 0; k < 2; ++k) dst[m][k] = *(const LAS bf16x8*)(lds + PG8_SA(b, h) + aoff + m * 2048 + k * 1024); } while (0)
; #define PG8_MMA(ai, bj, At, Bt) do { __builtin_amdgcn_s_setprio(1); _Pragma("unroll") for (int m = 0; m < 4; ++m) _Pragma("unroll") for (int n = 0; n < 2; ++n) _Pragma("unroll") for (int k = 0; k < 2; ++k) \
;         acc[ai][bj][m][n] = __builtin_amdgcn_mfma_f32_16x16x32_bf16(Bt[n][k], At[m][k], acc[ai][bj][m][n], 0, 0, 0); __builtin_amdgcn_s_setprio(0); } while (0)
; #define PG8_WAIT_V(n) asm volatile("s_waitcnt vmcnt(" #n ")" ::: "memory")
; #define PG8_WAIT_L(n) asm volatile("s_waitcnt lgkmcnt(" #n ")" ::: "memory")
; #define PG8_BAR __builtin_amdgcn_s_barrier()
; #define PG8_SCHED __builtin_amdgcn_sched_barrier(0)
; template <class Epi, class Map>
; __device__ __forceinline__ void gemm_phase(LAS unsigned char* lds, const Gemm g, const Sched<Map>& S, const Epi& E) {
;     ...
;             PG8_LDA(At, 1, 1); PG8_STAGE(PG8_SB(1, 0), b3, voffB); PG8_STAGE(PG8_SB(1, 1), b3 + hstepB, voffB); PG8_STAGE(PG8_SA(1, 0), a3, voffA);
;             PG8_WAIT_V(8); PG8_WAIT_L(0); PG8_BAR; PG8_MMA(1, 0, At, B0); PG8_MMA(1, 1, At, B1); PG8_BAR; PG8_SCHED;
;         }
;         if (wr == 0) PG8_BAR;
;         E(acc, cur, wr, wc, fr, fq);
;         if (!has_next) break;
	s_mov_b32 m0, s55
	v_lshl_add_u64 v[142:143], v[142:143], 0, s[82:83]
	ds_read_b128 v[200:203], v141 offset:49152
	ds_read_b128 v[204:207], v141 offset:50176
	ds_read_b128 v[208:211], v141 offset:51200
	ds_read_b128 v[212:215], v141 offset:52224
	ds_read_b128 v[216:219], v141 offset:53248
	ds_read_b128 v[220:223], v141 offset:54272
	ds_read_b128 v[224:227], v141 offset:55296
	ds_read_b128 v[228:231], v141 offset:56320
	global_load_lds_dwordx4 v[142:143], off
	v_lshl_add_u64 v[142:143], v[180:181], 0, s[82:83]
	s_mov_b32 m0, s54
	s_nop 0
	global_load_lds_dwordx4 v[142:143], off
	v_lshl_add_u64 v[142:143], s[36:37], 0, v[144:145]
	s_mov_b32 m0, s68
	s_nop 0
	global_load_lds_dwordx4 v[142:143], off
	v_lshl_add_u64 v[142:143], s[36:37], 0, v[128:129]
	s_mov_b32 m0, s67
	s_nop 0
	global_load_lds_dwordx4 v[142:143], off
	v_lshl_add_u64 v[142:143], v[232:233], 0, s[82:83]
	s_mov_b32 m0, s7
	s_nop 0
	global_load_lds_dwordx4 v[142:143], off
	v_lshl_add_u64 v[142:143], v[234:235], 0, s[82:83]
	s_mov_b32 m0, s8
	s_nop 0
	global_load_lds_dwordx4 v[142:143], off
	s_waitcnt vmcnt(8)
	s_waitcnt lgkmcnt(0)
	s_barrier
	s_waitcnt lgkmcnt(0)
	v_mfma_f32_16x16x32_bf16 v[92:95], v[134:137], v[200:203], v[92:95]
	v_mfma_f32_16x16x32_bf16 v[88:91], v[164:167], v[200:203], v[88:91]
	v_mfma_f32_16x16x32_bf16 v[84:87], v[134:137], v[208:211], v[84:87]
	v_mfma_f32_16x16x32_bf16 v[80:83], v[164:167], v[208:211], v[80:83]
	v_mfma_f32_16x16x32_bf16 v[76:79], v[134:137], v[216:219], v[76:79]
	v_mfma_f32_16x16x32_bf16 v[72:75], v[164:167], v[216:219], v[72:75]
	v_mfma_f32_16x16x32_bf16 v[68:71], v[134:137], v[224:227], v[68:71]
	v_mfma_f32_16x16x32_bf16 v[64:67], v[164:167], v[224:227], v[64:67]
	v_mfma_f32_16x16x32_bf16 v[92:95], v[160:163], v[204:207], v[92:95]
	v_mfma_f32_16x16x32_bf16 v[88:91], v[168:171], v[204:207], v[88:91]
	v_mfma_f32_16x16x32_bf16 v[84:87], v[160:163], v[212:215], v[84:87]
	v_mfma_f32_16x16x32_bf16 v[80:83], v[168:171], v[212:215], v[80:83]
	v_mfma_f32_16x16x32_bf16 v[76:79], v[160:163], v[220:223], v[76:79]
	v_mfma_f32_16x16x32_bf16 v[72:75], v[168:171], v[220:223], v[72:75]
	v_mfma_f32_16x16x32_bf16 v[68:71], v[160:163], v[228:231], v[68:71]
	v_mfma_f32_16x16x32_bf16 v[64:67], v[168:171], v[228:231], v[64:67]
	v_mfma_f32_16x16x32_bf16 v[28:31], v[172:175], v[200:203], v[28:31]
	v_mfma_f32_16x16x32_bf16 v[24:27], v[192:195], v[200:203], v[24:27]
	v_mfma_f32_16x16x32_bf16 v[20:23], v[172:175], v[208:211], v[20:23]
	v_mfma_f32_16x16x32_bf16 v[16:19], v[192:195], v[208:211], v[16:19]
	v_mfma_f32_16x16x32_bf16 v[12:15], v[172:175], v[216:219], v[12:15]
	v_mfma_f32_16x16x32_bf16 v[8:11], v[192:195], v[216:219], v[8:11]
	v_mfma_f32_16x16x32_bf16 v[4:7], v[172:175], v[224:227], v[4:7]
	v_mfma_f32_16x16x32_bf16 v[0:3], v[192:195], v[224:227], v[0:3]
	v_mfma_f32_16x16x32_bf16 v[28:31], v[176:179], v[204:207], v[28:31]
	v_mfma_f32_16x16x32_bf16 v[24:27], v[196:199], v[204:207], v[24:27]
	v_mfma_f32_16x16x32_bf16 v[20:23], v[176:179], v[212:215], v[20:23]
	v_mfma_f32_16x16x32_bf16 v[16:19], v[196:199], v[212:215], v[16:19]
	v_mfma_f32_16x16x32_bf16 v[12:15], v[176:179], v[220:223], v[12:15]
	v_mfma_f32_16x16x32_bf16 v[8:11], v[196:199], v[220:223], v[8:11]
	v_mfma_f32_16x16x32_bf16 v[4:7], v[176:179], v[228:231], v[4:7]
	v_mfma_f32_16x16x32_bf16 v[0:3], v[196:199], v[228:231], v[0:3]
	s_barrier
	s_andn2_b64 vcc, exec, s[34:35]
	s_mov_b64 s[36:37], -1
	s_mov_b64 s[34:35], 0
	s_mov_b64 s[44:45], 0x100
	s_cbranch_vccz .LBB0_659
	s_and_b64 vcc, exec, s[18:19]
	s_cbranch_vccz .LBB0_662
	s_barrier

; #define PG8_STAGE(bufoff, gbase, voff) do { _Pragma("unroll") for (int _i = 0; _i < 2; ++_i) \
;         __builtin_amdgcn_global_load_lds((const unsigned*)((const char*)(gbase) + (voff)[_i]), (LAS unsigned*)(lds + (bufoff) + ldsw + _i * 8192), 16, 0, 0); } while (0)
; #define PG8_LDA(dst, b, h) do { _Pragma("unroll") for (int m = 0; m < 4; ++m) _Pragma("unroll") for (int k = 0; k < 2; ++k) dst[m][k] = *(const LAS bf16x8*)(lds + PG8_SA(b, h) + aoff + m * 2048 + k * 1024); } while (0)
; #define PG8_LDB(dst, b, h) do { _Pragma("unroll") for (int n = 0; n < 2; ++n) _Pragma("unroll") for (int k = 0; k < 2; ++k) dst[n][k] = *(const LAS bf16x8*)(lds + PG8_SB(b, h) + boff + n * 2048 + k * 1024); } while (0)
; #define PG8_MMA(ai, bj, At, Bt) do { __builtin_amdgcn_s_setprio(1); _Pragma("unroll") for (int m = 0; m < 4; ++m) _Pragma("unroll") for (int n = 0; n < 2; ++n) _Pragma("unroll") for (int k = 0; k < 2; ++k) \
;         acc[ai][bj][m][n] = __builtin_amdgcn_mfma_f32_16x16x32_bf16(Bt[n][k], At[m][k], acc[ai][bj][m][n], 0, 0, 0); __builtin_amdgcn_s_setprio(0); } while (0)
; #define PG8_WAIT_V(n) asm volatile("s_waitcnt vmcnt(" #n ")" ::: "memory")
; #define PG8_WAIT_L(n) asm volatile("s_waitcnt lgkmcnt(" #n ")" ::: "memory")
; #define PG8_BAR __builtin_amdgcn_s_barrier()
; #define PG8_SCHED __builtin_amdgcn_sched_barrier(0)
; template <class Epi, class Map>
; __device__ __forceinline__ void gemm_phase(LAS unsigned char* lds, const Gemm g, const Sched<Map>& S, const Epi& E) {
;     ...
;         for (int t = 0; t < nt; t += 2) {
;             const bool last = (t == nt - 2);
;             const char* a1 = cA + (size_t)(t + 1) * kstep;
;             const char* a2 = last ? nA : cA + (size_t)(t + 2) * kstep; const char* b2 = last ? nB : cB + (size_t)(t + 2) * kstep;
;             const char* a3 = a2 + kstep; const char* b3 = b2 + kstep;
;             PG8_LDB(B0, 0, 0); PG8_LDB(B1, 0, 1); PG8_SCHED; PG8_LDA(At, 0, 0); PG8_STAGE(PG8_SA(1, 1), a1 + hstepA, voffA);
;             PG8_WAIT_V(8); PG8_WAIT_L(0); PG8_BAR; PG8_MMA(0, 0, At, B0); PG8_MMA(0, 1, At, B1); PG8_BAR; PG8_SCHED;
;             PG8_LDA(At, 0, 1); PG8_STAGE(PG8_SB(0, 0), b2, voffB); PG8_STAGE(PG8_SB(0, 1), b2 + hstepB, voffB); PG8_STAGE(PG8_SA(0, 0), a2, voffA);
.LBB0_679:
	s_add_u32 s21, s34, s46
	s_addc_u32 s33, s35, s47
	s_add_u32 s48, s21, 0x100
	s_addc_u32 s49, s33, 0
	s_and_b64 s[38:39], s[44:45], exec
	s_cselect_b32 s49, s12, s49
	s_cselect_b32 s48, s13, s48
	s_add_u32 s38, s30, s46
	s_addc_u32 s39, s31, s47
	s_add_u32 s46, s38, 0x100
	s_addc_u32 s47, s39, 0
	s_add_i32 s62, 0, 0x10000
	s_and_b64 s[38:39], s[44:45], exec
	s_cselect_b32 s51, s14, s47
	s_cselect_b32 s50, s15, s46
	s_add_i32 s45, 0, 0x14000
	s_add_u32 s54, s21, 0x20080
	s_addc_u32 s55, s33, 0
	s_add_i32 s59, s62, s0
	s_add_i32 m0, s1, 0xc000
	s_add_i32 s63, s1, 0xe000
	s_add_i32 s56, s59, 0x2000
	v_add_u32_e32 v134, s62, v138
	s_add_u32 s52, s50, 0x10000
	ds_read_b128 v[140:143], v134
	ds_read_b128 v[160:163], v134 offset:1024
	ds_read_b128 v[164:167], v134 offset:2048
	ds_read_b128 v[168:171], v134 offset:3072
	v_add_u32_e32 v134, s45, v138
	s_addc_u32 s53, s51, 0
	s_add_i32 s58, s45, s0
	ds_read_b128 v[172:175], v134
	ds_read_b128 v[176:179], v134 offset:1024
	ds_read_b128 v[192:195], v134 offset:2048
	ds_read_b128 v[196:199], v134 offset:3072
	s_add_i32 s57, s58, 0x2000
	s_add_i32 s39, 0, 0x18000
	s_add_i32 s38, 0, 0x1c000
	s_add_u32 s46, s48, 0x20000
	s_addc_u32 s47, s49, 0
	s_add_i32 s33, s39, s0
	s_add_i32 s21, s33, 0x2000
	s_add_u32 s44, s50, 0x10080
	s_addc_u32 s45, s51, 0
	s_add_i32 s66, s38, s0
	s_add_i32 s65, s66, 0x2000
	v_lshl_add_u64 v[134:135], s[54:55], 0, v[132:133]
	ds_read_b128 v[200:203], v139
	ds_read_b128 v[204:207], v139 offset:1024
	ds_read_b128 v[208:211], v139 offset:2048
	ds_read_b128 v[212:215], v139 offset:3072
	ds_read_b128 v[216:219], v139 offset:4096
	ds_read_b128 v[220:223], v139 offset:5120
	ds_read_b128 v[224:227], v139 offset:6144
	ds_read_b128 v[228:231], v139 offset:7168
	global_load_lds_dwordx4 v[134:135], off
	v_lshl_add_u64 v[134:135], s[54:55], 0, v[130:131]
	s_mov_b32 m0, s63
	s_nop 0
	global_load_lds_dwordx4 v[134:135], off
	s_waitcnt vmcnt(8)
	s_waitcnt lgkmcnt(0)
	s_barrier
	s_waitcnt lgkmcnt(0)
	v_mfma_f32_16x16x32_bf16 v[124:127], v[140:143], v[200:203], v[124:127]
	v_mfma_f32_16x16x32_bf16 v[120:123], v[164:167], v[200:203], v[120:123]
	v_mfma_f32_16x16x32_bf16 v[116:119], v[140:143], v[208:211], v[116:119]
	v_mfma_f32_16x16x32_bf16 v[108:111], v[164:167], v[208:211], v[108:111]
	v_mfma_f32_16x16x32_bf16 v[100:103], v[140:143], v[216:219], v[100:103]
	v_mfma_f32_16x16x32_bf16 v[92:95], v[164:167], v[216:219], v[92:95]
	v_mfma_f32_16x16x32_bf16 v[84:87], v[140:143], v[224:227], v[84:87]
	v_mfma_f32_16x16x32_bf16 v[76:79], v[164:167], v[224:227], v[76:79]
	v_mfma_f32_16x16x32_bf16 v[124:127], v[160:163], v[204:207], v[124:127]
	v_mfma_f32_16x16x32_bf16 v[120:123], v[168:171], v[204:207], v[120:123]
	v_mfma_f32_16x16x32_bf16 v[116:119], v[160:163], v[212:215], v[116:119]
	v_mfma_f32_16x16x32_bf16 v[108:111], v[168:171], v[212:215], v[108:111]
	v_mfma_f32_16x16x32_bf16 v[100:103], v[160:163], v[220:223], v[100:103]
	v_mfma_f32_16x16x32_bf16 v[92:95], v[168:171], v[220:223], v[92:95]
	v_mfma_f32_16x16x32_bf16 v[84:87], v[160:163], v[228:231], v[84:87]
	v_mfma_f32_16x16x32_bf16 v[76:79], v[168:171], v[228:231], v[76:79]
	v_mfma_f32_16x16x32_bf16 v[112:115], v[172:175], v[200:203], v[112:115]
	v_mfma_f32_16x16x32_bf16 v[104:107], v[192:195], v[200:203], v[104:107]
	v_mfma_f32_16x16x32_bf16 v[96:99], v[172:175], v[208:211], v[96:99]
	v_mfma_f32_16x16x32_bf16 v[88:91], v[192:195], v[208:211], v[88:91]
	v_mfma_f32_16x16x32_bf16 v[80:83], v[172:175], v[216:219], v[80:83]
	v_mfma_f32_16x16x32_bf16 v[72:75], v[192:195], v[216:219], v[72:75]
	v_mfma_f32_16x16x32_bf16 v[68:71], v[172:175], v[224:227], v[68:71]
	v_mfma_f32_16x16x32_bf16 v[64:67], v[192:195], v[224:227], v[64:67]
	v_mfma_f32_16x16x32_bf16 v[112:115], v[176:179], v[204:207], v[112:115]
	v_mfma_f32_16x16x32_bf16 v[104:107], v[196:199], v[204:207], v[104:107]
	v_mfma_f32_16x16x32_bf16 v[96:99], v[176:179], v[212:215], v[96:99]
	v_mfma_f32_16x16x32_bf16 v[88:91], v[196:199], v[212:215], v[88:91]
	v_mfma_f32_16x16x32_bf16 v[80:83], v[176:179], v[220:223], v[80:83]
	v_mfma_f32_16x16x32_bf16 v[72:75], v[196:199], v[220:223], v[72:75]
	v_mfma_f32_16x16x32_bf16 v[68:71], v[176:179], v[228:231], v[68:71]
	v_mfma_f32_16x16x32_bf16 v[64:67], v[196:199], v[228:231], v[64:67]
	s_barrier
	s_mov_b32 m0, s59
	v_lshl_add_u64 v[134:135], s[50:51], 0, v[144:145]
	ds_read_b128 v[200:203], v139 offset:16384
	ds_read_b128 v[204:207], v139 offset:17408
	ds_read_b128 v[208:211], v139 offset:18432
	ds_read_b128 v[212:215], v139 offset:19456
	ds_read_b128 v[216:219], v139 offset:20480
	ds_read_b128 v[220:223], v139 offset:21504
	ds_read_b128 v[224:227], v139 offset:22528
	ds_read_b128 v[228:231], v139 offset:23552
	global_load_lds_dwordx4 v[134:135], off
	v_lshl_add_u64 v[180:181], s[50:51], 0, v[128:129]
	s_mov_b32 m0, s56
	v_lshl_add_u64 v[232:233], s[52:53], 0, v[144:145]
	global_load_lds_dwordx4 v[180:181], off
	s_mov_b32 m0, s58
	v_lshl_add_u64 v[234:235], s[48:49], 0, v[130:131]
	global_load_lds_dwordx4 v[232:233], off
	v_lshl_add_u64 v[232:233], s[52:53], 0, v[128:129]
	s_mov_b32 m0, s57
	s_nop 0
	global_load_lds_dwordx4 v[232:233], off
	v_lshl_add_u64 v[232:233], s[48:49], 0, v[132:133]
	s_mov_b32 m0, s1
	s_nop 0
	global_load_lds_dwordx4 v[232:233], off
	s_mov_b32 m0, s2
	s_nop 0
	global_load_lds_dwordx4 v[234:235], off
	s_waitcnt vmcnt(8)
	s_waitcnt lgkmcnt(0)
	s_barrier
; #define PG8_STAGE(bufoff, gbase, voff) do { _Pragma("unroll") for (int _i = 0; _i < 2; ++_i) \
;         __builtin_amdgcn_global_load_lds((const unsigned*)((const char*)(gbase) + (voff)[_i]), (LAS unsigned*)(lds + (bufoff) + ldsw + _i * 8192), 16, 0, 0); } while (0)
; #define PG8_LDA(dst, b, h) do { _Pragma("unroll") for (int m = 0; m < 4; ++m) _Pragma("unroll") for (int k = 0; k < 2; ++k) dst[m][k] = *(const LAS bf16x8*)(lds + PG8_SA(b, h) + aoff + m * 2048 + k * 1024); } while (0)
; #define PG8_LDB(dst, b, h) do { _Pragma("unroll") for (int n = 0; n < 2; ++n) _Pragma("unroll") for (int k = 0; k < 2; ++k) dst[n][k] = *(const LAS bf16x8*)(lds + PG8_SB(b, h) + boff + n * 2048 + k * 1024); } while (0)
; #define PG8_MMA(ai, bj, At, Bt) do { __builtin_amdgcn_s_setprio(1); _Pragma("unroll") for (int m = 0; m < 4; ++m) _Pragma("unroll") for (int n = 0; n < 2; ++n) _Pragma("unroll") for (int k = 0; k < 2; ++k) \
;         acc[ai][bj][m][n] = __builtin_amdgcn_mfma_f32_16x16x32_bf16(Bt[n][k], At[m][k], acc[ai][bj][m][n], 0, 0, 0); __builtin_amdgcn_s_setprio(0); } while (0)
; #define PG8_WAIT_V(n) asm volatile("s_waitcnt vmcnt(" #n ")" ::: "memory")
; #define PG8_WAIT_L(n) asm volatile("s_waitcnt lgkmcnt(" #n ")" ::: "memory")
; #define PG8_BAR __builtin_amdgcn_s_barrier()
; #define PG8_SCHED __builtin_amdgcn_sched_barrier(0)
; template <class Epi, class Map>
; __device__ __forceinline__ void gemm_phase(LAS unsigned char* lds, const Gemm g, const Sched<Map>& S, const Epi& E) {
;     ...
;             PG8_WAIT_V(8); PG8_WAIT_L(0); PG8_BAR; PG8_MMA(1, 0, At, B0); PG8_MMA(1, 1, At, B1); PG8_BAR; PG8_SCHED;
;             PG8_LDB(B0, 1, 0); PG8_LDB(B1, 1, 1); PG8_SCHED; PG8_LDA(At, 1, 0); PG8_STAGE(PG8_SA(0, 1), a2 + hstepA, voffA);
;             PG8_WAIT_V(8); PG8_WAIT_L(0); PG8_BAR; PG8_MMA(0, 0, At, B0); PG8_MMA(0, 1, At, B1); PG8_BAR; PG8_SCHED;
	s_waitcnt lgkmcnt(0)
	v_mfma_f32_16x16x32_bf16 v[60:63], v[140:143], v[200:203], v[60:63]
	v_mfma_f32_16x16x32_bf16 v[56:59], v[164:167], v[200:203], v[56:59]
	v_mfma_f32_16x16x32_bf16 v[52:55], v[140:143], v[208:211], v[52:55]
	v_mfma_f32_16x16x32_bf16 v[44:47], v[164:167], v[208:211], v[44:47]
	v_mfma_f32_16x16x32_bf16 v[36:39], v[140:143], v[216:219], v[36:39]
	v_mfma_f32_16x16x32_bf16 v[28:31], v[164:167], v[216:219], v[28:31]
	v_mfma_f32_16x16x32_bf16 v[20:23], v[140:143], v[224:227], v[20:23]
	v_mfma_f32_16x16x32_bf16 v[12:15], v[164:167], v[224:227], v[12:15]
	v_mfma_f32_16x16x32_bf16 v[60:63], v[160:163], v[204:207], v[60:63]
	v_mfma_f32_16x16x32_bf16 v[56:59], v[168:171], v[204:207], v[56:59]
	v_mfma_f32_16x16x32_bf16 v[52:55], v[160:163], v[212:215], v[52:55]
	v_mfma_f32_16x16x32_bf16 v[44:47], v[168:171], v[212:215], v[44:47]
	v_mfma_f32_16x16x32_bf16 v[36:39], v[160:163], v[220:223], v[36:39]
	v_mfma_f32_16x16x32_bf16 v[28:31], v[168:171], v[220:223], v[28:31]
	v_mfma_f32_16x16x32_bf16 v[20:23], v[160:163], v[228:231], v[20:23]
	v_mfma_f32_16x16x32_bf16 v[12:15], v[168:171], v[228:231], v[12:15]
	v_mfma_f32_16x16x32_bf16 v[48:51], v[172:175], v[200:203], v[48:51]
	v_mfma_f32_16x16x32_bf16 v[40:43], v[192:195], v[200:203], v[40:43]
	v_mfma_f32_16x16x32_bf16 v[32:35], v[172:175], v[208:211], v[32:35]
	v_mfma_f32_16x16x32_bf16 v[24:27], v[192:195], v[208:211], v[24:27]
	v_mfma_f32_16x16x32_bf16 v[16:19], v[172:175], v[216:219], v[16:19]
	v_mfma_f32_16x16x32_bf16 v[8:11], v[192:195], v[216:219], v[8:11]
	v_mfma_f32_16x16x32_bf16 v[4:7], v[172:175], v[224:227], v[4:7]
	v_mfma_f32_16x16x32_bf16 v[0:3], v[192:195], v[224:227], v[0:3]
	v_mfma_f32_16x16x32_bf16 v[48:51], v[176:179], v[204:207], v[48:51]
	v_mfma_f32_16x16x32_bf16 v[40:43], v[196:199], v[204:207], v[40:43]
	v_mfma_f32_16x16x32_bf16 v[32:35], v[176:179], v[212:215], v[32:35]
	v_mfma_f32_16x16x32_bf16 v[24:27], v[196:199], v[212:215], v[24:27]
	v_mfma_f32_16x16x32_bf16 v[16:19], v[176:179], v[220:223], v[16:19]
	v_mfma_f32_16x16x32_bf16 v[8:11], v[196:199], v[220:223], v[8:11]
	v_mfma_f32_16x16x32_bf16 v[4:7], v[176:179], v[228:231], v[4:7]
	v_mfma_f32_16x16x32_bf16 v[0:3], v[196:199], v[228:231], v[0:3]
	s_barrier
	v_add_u32_e32 v168, s39, v138
	v_add_u32_e32 v196, s38, v138
	ds_read_b128 v[140:143], v168
	ds_read_b128 v[160:163], v168 offset:1024
	ds_read_b128 v[164:167], v168 offset:2048
	ds_read_b128 v[168:171], v168 offset:3072
	ds_read_b128 v[172:175], v196
	ds_read_b128 v[176:179], v196 offset:1024
	ds_read_b128 v[192:195], v196 offset:2048
	ds_read_b128 v[196:199], v196 offset:3072
	s_mov_b32 m0, s3
	v_lshl_add_u64 v[236:237], s[46:47], 0, v[132:133]
	ds_read_b128 v[200:203], v139 offset:32768
	ds_read_b128 v[204:207], v139 offset:33792
	ds_read_b128 v[208:211], v139 offset:34816
	ds_read_b128 v[212:215], v139 offset:35840
	ds_read_b128 v[216:219], v139 offset:36864
	ds_read_b128 v[220:223], v139 offset:37888
	ds_read_b128 v[224:227], v139 offset:38912
	ds_read_b128 v[228:231], v139 offset:39936
	global_load_lds_dwordx4 v[236:237], off
	v_lshl_add_u64 v[236:237], s[46:47], 0, v[130:131]
	s_mov_b32 m0, s4
	s_nop 0
	global_load_lds_dwordx4 v[236:237], off
	s_waitcnt vmcnt(8)
	s_waitcnt lgkmcnt(0)
	s_barrier
	s_waitcnt lgkmcnt(0)
	v_mfma_f32_16x16x32_bf16 v[124:127], v[140:143], v[200:203], v[124:127]
	v_mfma_f32_16x16x32_bf16 v[120:123], v[164:167], v[200:203], v[120:123]
	v_mfma_f32_16x16x32_bf16 v[116:119], v[140:143], v[208:211], v[116:119]
	v_mfma_f32_16x16x32_bf16 v[108:111], v[164:167], v[208:211], v[108:111]
	v_mfma_f32_16x16x32_bf16 v[100:103], v[140:143], v[216:219], v[100:103]
	v_mfma_f32_16x16x32_bf16 v[92:95], v[164:167], v[216:219], v[92:95]
	v_mfma_f32_16x16x32_bf16 v[84:87], v[140:143], v[224:227], v[84:87]
	v_mfma_f32_16x16x32_bf16 v[76:79], v[164:167], v[224:227], v[76:79]
	v_mfma_f32_16x16x32_bf16 v[124:127], v[160:163], v[204:207], v[124:127]
	v_mfma_f32_16x16x32_bf16 v[120:123], v[168:171], v[204:207], v[120:123]
	v_mfma_f32_16x16x32_bf16 v[116:119], v[160:163], v[212:215], v[116:119]
	v_mfma_f32_16x16x32_bf16 v[108:111], v[168:171], v[212:215], v[108:111]
	v_mfma_f32_16x16x32_bf16 v[100:103], v[160:163], v[220:223], v[100:103]
	v_mfma_f32_16x16x32_bf16 v[92:95], v[168:171], v[220:223], v[92:95]
	v_mfma_f32_16x16x32_bf16 v[84:87], v[160:163], v[228:231], v[84:87]
	v_mfma_f32_16x16x32_bf16 v[76:79], v[168:171], v[228:231], v[76:79]
	v_mfma_f32_16x16x32_bf16 v[112:115], v[172:175], v[200:203], v[112:115]
	v_mfma_f32_16x16x32_bf16 v[104:107], v[192:195], v[200:203], v[104:107]
	v_mfma_f32_16x16x32_bf16 v[96:99], v[172:175], v[208:211], v[96:99]
	v_mfma_f32_16x16x32_bf16 v[88:91], v[192:195], v[208:211], v[88:91]
	v_mfma_f32_16x16x32_bf16 v[80:83], v[172:175], v[216:219], v[80:83]
	v_mfma_f32_16x16x32_bf16 v[72:75], v[192:195], v[216:219], v[72:75]
	v_mfma_f32_16x16x32_bf16 v[68:71], v[172:175], v[224:227], v[68:71]
	v_mfma_f32_16x16x32_bf16 v[64:67], v[192:195], v[224:227], v[64:67]
	v_mfma_f32_16x16x32_bf16 v[112:115], v[176:179], v[204:207], v[112:115]
	v_mfma_f32_16x16x32_bf16 v[104:107], v[196:199], v[204:207], v[104:107]
	v_mfma_f32_16x16x32_bf16 v[96:99], v[176:179], v[212:215], v[96:99]
	v_mfma_f32_16x16x32_bf16 v[88:91], v[196:199], v[212:215], v[88:91]
	v_mfma_f32_16x16x32_bf16 v[80:83], v[176:179], v[220:223], v[80:83]
	v_mfma_f32_16x16x32_bf16 v[72:75], v[196:199], v[220:223], v[72:75]
	v_mfma_f32_16x16x32_bf16 v[68:71], v[176:179], v[228:231], v[68:71]
	v_mfma_f32_16x16x32_bf16 v[64:67], v[196:199], v[228:231], v[64:67]
	s_barrier
; #define PG8_STAGE(bufoff, gbase, voff) do { _Pragma("unroll") for (int _i = 0; _i < 2; ++_i) \
;         __builtin_amdgcn_global_load_lds((const unsigned*)((const char*)(gbase) + (voff)[_i]), (LAS unsigned*)(lds + (bufoff) + ldsw + _i * 8192), 16, 0, 0); } while (0)
; #define PG8_LDA(dst, b, h) do { _Pragma("unroll") for (int m = 0; m < 4; ++m) _Pragma("unroll") for (int k = 0; k < 2; ++k) dst[m][k] = *(const LAS bf16x8*)(lds + PG8_SA(b, h) + aoff + m * 2048 + k * 1024); } while (0)
; #define PG8_MMA(ai, bj, At, Bt) do { __builtin_amdgcn_s_setprio(1); _Pragma("unroll") for (int m = 0; m < 4; ++m) _Pragma("unroll") for (int n = 0; n < 2; ++n) _Pragma("unroll") for (int k = 0; k < 2; ++k) \
;         acc[ai][bj][m][n] = __builtin_amdgcn_mfma_f32_16x16x32_bf16(Bt[n][k], At[m][k], acc[ai][bj][m][n], 0, 0, 0); __builtin_amdgcn_s_setprio(0); } while (0)
; #define PG8_WAIT_V(n) asm volatile("s_waitcnt vmcnt(" #n ")" ::: "memory")
; #define PG8_WAIT_L(n) asm volatile("s_waitcnt lgkmcnt(" #n ")" ::: "memory")
; #define PG8_BAR __builtin_amdgcn_s_barrier()
; #define PG8_SCHED __builtin_amdgcn_sched_barrier(0)
; template <class Epi, class Map>
; __device__ __forceinline__ void gemm_phase(LAS unsigned char* lds, const Gemm g, const Sched<Map>& S, const Epi& E) {
;     ...
;             PG8_LDA(At, 1, 1); PG8_STAGE(PG8_SB(1, 0), b3, voffB); PG8_STAGE(PG8_SB(1, 1), b3 + hstepB, voffB); PG8_STAGE(PG8_SA(1, 0), a3, voffA);
;             PG8_WAIT_V(8); PG8_WAIT_L(0); PG8_BAR; PG8_MMA(1, 0, At, B0); PG8_MMA(1, 1, At, B1); PG8_BAR; PG8_SCHED;
;         }
;         if (wr == 0) PG8_BAR;
;         E(acc, cur, wr, wc, fr, fq);
;         if (!has_next) break;
	s_mov_b32 m0, s33
	v_lshl_add_u64 v[134:135], v[134:135], 0, s[82:83]
	ds_read_b128 v[200:203], v139 offset:49152
	ds_read_b128 v[204:207], v139 offset:50176
	ds_read_b128 v[208:211], v139 offset:51200
	ds_read_b128 v[212:215], v139 offset:52224
	ds_read_b128 v[216:219], v139 offset:53248
	ds_read_b128 v[220:223], v139 offset:54272
	ds_read_b128 v[224:227], v139 offset:55296
	ds_read_b128 v[228:231], v139 offset:56320
	global_load_lds_dwordx4 v[134:135], off
	v_lshl_add_u64 v[134:135], v[180:181], 0, s[82:83]
	s_mov_b32 m0, s21
	s_nop 0
	global_load_lds_dwordx4 v[134:135], off
	v_lshl_add_u64 v[134:135], s[44:45], 0, v[144:145]
	s_mov_b32 m0, s66
	s_nop 0
	global_load_lds_dwordx4 v[134:135], off
	v_lshl_add_u64 v[134:135], s[44:45], 0, v[128:129]
	s_mov_b32 m0, s65
	s_nop 0
	global_load_lds_dwordx4 v[134:135], off
	v_lshl_add_u64 v[134:135], v[232:233], 0, s[82:83]
	s_mov_b32 m0, s6
	s_nop 0
	global_load_lds_dwordx4 v[134:135], off
	v_lshl_add_u64 v[134:135], v[234:235], 0, s[82:83]
	s_mov_b32 m0, s7
	s_nop 0
	global_load_lds_dwordx4 v[134:135], off
	s_waitcnt vmcnt(8)
	s_waitcnt lgkmcnt(0)
	s_barrier
	s_waitcnt lgkmcnt(0)
	v_mfma_f32_16x16x32_bf16 v[60:63], v[140:143], v[200:203], v[60:63]
	v_mfma_f32_16x16x32_bf16 v[56:59], v[164:167], v[200:203], v[56:59]
	v_mfma_f32_16x16x32_bf16 v[52:55], v[140:143], v[208:211], v[52:55]
	v_mfma_f32_16x16x32_bf16 v[44:47], v[164:167], v[208:211], v[44:47]
	v_mfma_f32_16x16x32_bf16 v[36:39], v[140:143], v[216:219], v[36:39]
	v_mfma_f32_16x16x32_bf16 v[28:31], v[164:167], v[216:219], v[28:31]
	v_mfma_f32_16x16x32_bf16 v[20:23], v[140:143], v[224:227], v[20:23]
	v_mfma_f32_16x16x32_bf16 v[12:15], v[164:167], v[224:227], v[12:15]
	v_mfma_f32_16x16x32_bf16 v[60:63], v[160:163], v[204:207], v[60:63]
	v_mfma_f32_16x16x32_bf16 v[56:59], v[168:171], v[204:207], v[56:59]
	v_mfma_f32_16x16x32_bf16 v[52:55], v[160:163], v[212:215], v[52:55]
	v_mfma_f32_16x16x32_bf16 v[44:47], v[168:171], v[212:215], v[44:47]
	v_mfma_f32_16x16x32_bf16 v[36:39], v[160:163], v[220:223], v[36:39]
	v_mfma_f32_16x16x32_bf16 v[28:31], v[168:171], v[220:223], v[28:31]
	v_mfma_f32_16x16x32_bf16 v[20:23], v[160:163], v[228:231], v[20:23]
	v_mfma_f32_16x16x32_bf16 v[12:15], v[168:171], v[228:231], v[12:15]
	v_mfma_f32_16x16x32_bf16 v[48:51], v[172:175], v[200:203], v[48:51]
	v_mfma_f32_16x16x32_bf16 v[40:43], v[192:195], v[200:203], v[40:43]
	v_mfma_f32_16x16x32_bf16 v[32:35], v[172:175], v[208:211], v[32:35]
	v_mfma_f32_16x16x32_bf16 v[24:27], v[192:195], v[208:211], v[24:27]
	v_mfma_f32_16x16x32_bf16 v[16:19], v[172:175], v[216:219], v[16:19]
	v_mfma_f32_16x16x32_bf16 v[8:11], v[192:195], v[216:219], v[8:11]
	v_mfma_f32_16x16x32_bf16 v[4:7], v[172:175], v[224:227], v[4:7]
	v_mfma_f32_16x16x32_bf16 v[0:3], v[192:195], v[224:227], v[0:3]
	v_mfma_f32_16x16x32_bf16 v[48:51], v[176:179], v[204:207], v[48:51]
	v_mfma_f32_16x16x32_bf16 v[40:43], v[196:199], v[204:207], v[40:43]
	v_mfma_f32_16x16x32_bf16 v[32:35], v[176:179], v[212:215], v[32:35]
	v_mfma_f32_16x16x32_bf16 v[24:27], v[196:199], v[212:215], v[24:27]
	v_mfma_f32_16x16x32_bf16 v[16:19], v[176:179], v[220:223], v[16:19]
	v_mfma_f32_16x16x32_bf16 v[8:11], v[196:199], v[220:223], v[8:11]
	v_mfma_f32_16x16x32_bf16 v[4:7], v[176:179], v[228:231], v[4:7]
	v_mfma_f32_16x16x32_bf16 v[0:3], v[196:199], v[228:231], v[0:3]
	s_barrier
	s_andn2_b64 vcc, exec, s[36:37]
	s_mov_b64 s[44:45], -1
	s_mov_b64 s[36:37], 0
	s_mov_b64 s[46:47], 0x100
	s_cbranch_vccz .LBB0_679
	s_and_b64 vcc, exec, s[18:19]
	s_cbranch_vccz .LBB0_682
	s_barrier

; #define PG8_STAGE(bufoff, gbase, voff) do { _Pragma("unroll") for (int _i = 0; _i < 2; ++_i) \
;         __builtin_amdgcn_global_load_lds((const unsigned*)((const char*)(gbase) + (voff)[_i]), (LAS unsigned*)(lds + (bufoff) + ldsw + _i * 8192), 16, 0, 0); } while (0)
; #define PG8_LDA(dst, b, h) do { _Pragma("unroll") for (int m = 0; m < 4; ++m) _Pragma("unroll") for (int k = 0; k < 2; ++k) dst[m][k] = *(const LAS bf16x8*)(lds + PG8_SA(b, h) + aoff + m * 2048 + k * 1024); } while (0)
; #define PG8_LDB(dst, b, h) do { _Pragma("unroll") for (int n = 0; n < 2; ++n) _Pragma("unroll") for (int k = 0; k < 2; ++k) dst[n][k] = *(const LAS bf16x8*)(lds + PG8_SB(b, h) + boff + n * 2048 + k * 1024); } while (0)
; #define PG8_MMA(ai, bj, At, Bt) do { __builtin_amdgcn_s_setprio(1); _Pragma("unroll") for (int m = 0; m < 4; ++m) _Pragma("unroll") for (int n = 0; n < 2; ++n) _Pragma("unroll") for (int k = 0; k < 2; ++k) \
;         acc[ai][bj][m][n] = __builtin_amdgcn_mfma_f32_16x16x32_bf16(Bt[n][k], At[m][k], acc[ai][bj][m][n], 0, 0, 0); __builtin_amdgcn_s_setprio(0); } while (0)
; #define PG8_WAIT_V(n) asm volatile("s_waitcnt vmcnt(" #n ")" ::: "memory")
; #define PG8_WAIT_L(n) asm volatile("s_waitcnt lgkmcnt(" #n ")" ::: "memory")
; #define PG8_BAR __builtin_amdgcn_s_barrier()
; #define PG8_SCHED __builtin_amdgcn_sched_barrier(0)
; template <class Epi, class Map>
; __device__ __forceinline__ void gemm_phase(LAS unsigned char* lds, const Gemm g, const Sched<Map>& S, const Epi& E) {
;     ...
;         for (int t = 0; t < nt; t += 2) {
;             const bool last = (t == nt - 2);
;             const char* a1 = cA + (size_t)(t + 1) * kstep;
;             const char* a2 = last ? nA : cA + (size_t)(t + 2) * kstep; const char* b2 = last ? nB : cB + (size_t)(t + 2) * kstep;
;             const char* a3 = a2 + kstep; const char* b3 = b2 + kstep;
;             PG8_LDB(B0, 0, 0); PG8_LDB(B1, 0, 1); PG8_SCHED; PG8_LDA(At, 0, 0); PG8_STAGE(PG8_SA(1, 1), a1 + hstepA, voffA);
;             PG8_WAIT_V(8); PG8_WAIT_L(0); PG8_BAR; PG8_MMA(0, 0, At, B0); PG8_MMA(0, 1, At, B1); PG8_BAR; PG8_SCHED;
;             PG8_LDA(At, 0, 1); PG8_STAGE(PG8_SB(0, 0), b2, voffB); PG8_STAGE(PG8_SB(0, 1), b2 + hstepB, voffB); PG8_STAGE(PG8_SA(0, 0), a2, voffA);
.LBB0_808:
	s_add_u32 s36, s34, 0xfffe0080
	s_addc_u32 s37, s35, -1
	s_add_i32 s48, 0, 0x10000
	s_cmp_eq_u32 s47, 4
	s_cselect_b32 s45, s21, s37
	s_cselect_b32 s44, s25, s36
	v_add_u32_e32 v161, s48, v159
	s_cselect_b32 s37, s33, s46
	s_cselect_b32 s36, s38, s39
	s_add_i32 s50, 0, 0x14000
	ds_read_b128 v[138:141], v161
	ds_read_b128 v[162:165], v161 offset:1024
	ds_read_b128 v[166:169], v161 offset:2048
	ds_read_b128 v[170:173], v161 offset:3072
	v_add_u32_e32 v161, s50, v159
	ds_read_b128 v[174:177], v161
	ds_read_b128 v[178:181], v161 offset:1024
	ds_read_b128 v[192:195], v161 offset:2048
	ds_read_b128 v[196:199], v161 offset:3072
	v_lshl_add_u64 v[232:233], s[34:35], 0, v[134:135]
	s_add_i32 m0, s1, 0xc000
	ds_read_b128 v[200:203], v160
	ds_read_b128 v[204:207], v160 offset:1024
	ds_read_b128 v[208:211], v160 offset:2048
	ds_read_b128 v[212:215], v160 offset:3072
	ds_read_b128 v[216:219], v160 offset:4096
	ds_read_b128 v[220:223], v160 offset:5120
	ds_read_b128 v[224:227], v160 offset:6144
	ds_read_b128 v[228:231], v160 offset:7168
	global_load_lds_dwordx4 v[232:233], off
	v_lshl_add_u64 v[232:233], s[34:35], 0, v[136:137]
	s_add_i32 m0, s1, 0xe000
	s_nop 0
	global_load_lds_dwordx4 v[232:233], off
	s_waitcnt vmcnt(8)
	s_waitcnt lgkmcnt(0)
	s_barrier
	s_waitcnt lgkmcnt(0)
	v_mfma_f32_16x16x32_bf16 v[124:127], v[138:141], v[200:203], v[124:127]
	v_mfma_f32_16x16x32_bf16 v[120:123], v[166:169], v[200:203], v[120:123]
	v_mfma_f32_16x16x32_bf16 v[116:119], v[138:141], v[208:211], v[116:119]
	v_mfma_f32_16x16x32_bf16 v[112:115], v[166:169], v[208:211], v[112:115]
	v_mfma_f32_16x16x32_bf16 v[108:111], v[138:141], v[216:219], v[108:111]
	v_mfma_f32_16x16x32_bf16 v[104:107], v[166:169], v[216:219], v[104:107]
	v_mfma_f32_16x16x32_bf16 v[100:103], v[138:141], v[224:227], v[100:103]
	v_mfma_f32_16x16x32_bf16 v[96:99], v[166:169], v[224:227], v[96:99]
	v_mfma_f32_16x16x32_bf16 v[124:127], v[162:165], v[204:207], v[124:127]
	v_mfma_f32_16x16x32_bf16 v[120:123], v[170:173], v[204:207], v[120:123]
	v_mfma_f32_16x16x32_bf16 v[116:119], v[162:165], v[212:215], v[116:119]
	v_mfma_f32_16x16x32_bf16 v[112:115], v[170:173], v[212:215], v[112:115]
	v_mfma_f32_16x16x32_bf16 v[108:111], v[162:165], v[220:223], v[108:111]
	v_mfma_f32_16x16x32_bf16 v[104:107], v[170:173], v[220:223], v[104:107]
	v_mfma_f32_16x16x32_bf16 v[100:103], v[162:165], v[228:231], v[100:103]
	v_mfma_f32_16x16x32_bf16 v[96:99], v[170:173], v[228:231], v[96:99]
	v_mfma_f32_16x16x32_bf16 v[92:95], v[174:177], v[200:203], v[92:95]
	v_mfma_f32_16x16x32_bf16 v[88:91], v[192:195], v[200:203], v[88:91]
	v_mfma_f32_16x16x32_bf16 v[84:87], v[174:177], v[208:211], v[84:87]
	v_mfma_f32_16x16x32_bf16 v[80:83], v[192:195], v[208:211], v[80:83]
	v_mfma_f32_16x16x32_bf16 v[76:79], v[174:177], v[216:219], v[76:79]
	v_mfma_f32_16x16x32_bf16 v[72:75], v[192:195], v[216:219], v[72:75]
	v_mfma_f32_16x16x32_bf16 v[68:71], v[174:177], v[224:227], v[68:71]
	v_mfma_f32_16x16x32_bf16 v[64:67], v[192:195], v[224:227], v[64:67]
	v_mfma_f32_16x16x32_bf16 v[92:95], v[178:181], v[204:207], v[92:95]
	v_mfma_f32_16x16x32_bf16 v[88:91], v[196:199], v[204:207], v[88:91]
	v_mfma_f32_16x16x32_bf16 v[84:87], v[178:181], v[212:215], v[84:87]
	v_mfma_f32_16x16x32_bf16 v[80:83], v[196:199], v[212:215], v[80:83]
	v_mfma_f32_16x16x32_bf16 v[76:79], v[178:181], v[220:223], v[76:79]
	v_mfma_f32_16x16x32_bf16 v[72:75], v[196:199], v[220:223], v[72:75]
	v_mfma_f32_16x16x32_bf16 v[68:71], v[178:181], v[228:231], v[68:71]
	v_mfma_f32_16x16x32_bf16 v[64:67], v[196:199], v[228:231], v[64:67]
	s_barrier
	s_add_i32 s48, s48, s0
	v_lshl_add_u64 v[232:233], s[36:37], 0, v[144:145]
	s_mov_b32 m0, s48
	ds_read_b128 v[200:203], v160 offset:16384
	ds_read_b128 v[204:207], v160 offset:17408
	ds_read_b128 v[208:211], v160 offset:18432
	ds_read_b128 v[212:215], v160 offset:19456
	ds_read_b128 v[216:219], v160 offset:20480
	ds_read_b128 v[220:223], v160 offset:21504
	ds_read_b128 v[224:227], v160 offset:22528
	ds_read_b128 v[228:231], v160 offset:23552
	global_load_lds_dwordx4 v[232:233], off
	s_add_i32 m0, s48, 0x2000
	s_add_u32 s48, s36, 0x20000
	v_lshl_add_u64 v[234:235], s[36:37], 0, v[128:129]
	s_addc_u32 s49, s37, 0
	s_add_i32 s50, s50, s0
	global_load_lds_dwordx4 v[234:235], off
	v_lshl_add_u64 v[236:237], s[48:49], 0, v[144:145]
	s_mov_b32 m0, s50
	v_lshl_add_u64 v[238:239], s[44:45], 0, v[130:131]
	global_load_lds_dwordx4 v[236:237], off
	v_lshl_add_u64 v[236:237], s[48:49], 0, v[128:129]
	s_add_i32 m0, s50, 0x2000
	s_nop 0
	global_load_lds_dwordx4 v[236:237], off
	v_lshl_add_u64 v[236:237], s[44:45], 0, v[132:133]
	s_mov_b32 m0, s1
	s_nop 0
	global_load_lds_dwordx4 v[236:237], off
	s_mov_b32 m0, s2
	s_nop 0
	global_load_lds_dwordx4 v[238:239], off
	s_waitcnt vmcnt(8)
	s_waitcnt lgkmcnt(0)
	s_barrier
; #define PG8_STAGE(bufoff, gbase, voff) do { _Pragma("unroll") for (int _i = 0; _i < 2; ++_i) \
;         __builtin_amdgcn_global_load_lds((const unsigned*)((const char*)(gbase) + (voff)[_i]), (LAS unsigned*)(lds + (bufoff) + ldsw + _i * 8192), 16, 0, 0); } while (0)
; #define PG8_LDA(dst, b, h) do { _Pragma("unroll") for (int m = 0; m < 4; ++m) _Pragma("unroll") for (int k = 0; k < 2; ++k) dst[m][k] = *(const LAS bf16x8*)(lds + PG8_SA(b, h) + aoff + m * 2048 + k * 1024); } while (0)
; #define PG8_LDB(dst, b, h) do { _Pragma("unroll") for (int n = 0; n < 2; ++n) _Pragma("unroll") for (int k = 0; k < 2; ++k) dst[n][k] = *(const LAS bf16x8*)(lds + PG8_SB(b, h) + boff + n * 2048 + k * 1024); } while (0)
; #define PG8_MMA(ai, bj, At, Bt) do { __builtin_amdgcn_s_setprio(1); _Pragma("unroll") for (int m = 0; m < 4; ++m) _Pragma("unroll") for (int n = 0; n < 2; ++n) _Pragma("unroll") for (int k = 0; k < 2; ++k) \
;         acc[ai][bj][m][n] = __builtin_amdgcn_mfma_f32_16x16x32_bf16(Bt[n][k], At[m][k], acc[ai][bj][m][n], 0, 0, 0); __builtin_amdgcn_s_setprio(0); } while (0)
; #define PG8_WAIT_V(n) asm volatile("s_waitcnt vmcnt(" #n ")" ::: "memory")
; #define PG8_WAIT_L(n) asm volatile("s_waitcnt lgkmcnt(" #n ")" ::: "memory")
; #define PG8_BAR __builtin_amdgcn_s_barrier()
; #define PG8_SCHED __builtin_amdgcn_sched_barrier(0)
; template <class Epi, class Map>
; __device__ __forceinline__ void gemm_phase(LAS unsigned char* lds, const Gemm g, const Sched<Map>& S, const Epi& E) {
;     ...
;             PG8_WAIT_V(8); PG8_WAIT_L(0); PG8_BAR; PG8_MMA(1, 0, At, B0); PG8_MMA(1, 1, At, B1); PG8_BAR; PG8_SCHED;
;             PG8_LDB(B0, 1, 0); PG8_LDB(B1, 1, 1); PG8_SCHED; PG8_LDA(At, 1, 0); PG8_STAGE(PG8_SA(0, 1), a2 + hstepA, voffA);
;             PG8_WAIT_V(8); PG8_WAIT_L(0); PG8_BAR; PG8_MMA(0, 0, At, B0); PG8_MMA(0, 1, At, B1); PG8_BAR; PG8_SCHED;
	s_waitcnt lgkmcnt(0)
	v_mfma_f32_16x16x32_bf16 v[60:63], v[138:141], v[200:203], v[60:63]
	v_mfma_f32_16x16x32_bf16 v[56:59], v[166:169], v[200:203], v[56:59]
	v_mfma_f32_16x16x32_bf16 v[52:55], v[138:141], v[208:211], v[52:55]
	v_mfma_f32_16x16x32_bf16 v[48:51], v[166:169], v[208:211], v[48:51]
	v_mfma_f32_16x16x32_bf16 v[44:47], v[138:141], v[216:219], v[44:47]
	v_mfma_f32_16x16x32_bf16 v[40:43], v[166:169], v[216:219], v[40:43]
	v_mfma_f32_16x16x32_bf16 v[36:39], v[138:141], v[224:227], v[36:39]
	v_mfma_f32_16x16x32_bf16 v[32:35], v[166:169], v[224:227], v[32:35]
	v_mfma_f32_16x16x32_bf16 v[60:63], v[162:165], v[204:207], v[60:63]
	v_mfma_f32_16x16x32_bf16 v[56:59], v[170:173], v[204:207], v[56:59]
	v_mfma_f32_16x16x32_bf16 v[52:55], v[162:165], v[212:215], v[52:55]
	v_mfma_f32_16x16x32_bf16 v[48:51], v[170:173], v[212:215], v[48:51]
	v_mfma_f32_16x16x32_bf16 v[44:47], v[162:165], v[220:223], v[44:47]
	v_mfma_f32_16x16x32_bf16 v[40:43], v[170:173], v[220:223], v[40:43]
	v_mfma_f32_16x16x32_bf16 v[36:39], v[162:165], v[228:231], v[36:39]
	v_mfma_f32_16x16x32_bf16 v[32:35], v[170:173], v[228:231], v[32:35]
	v_mfma_f32_16x16x32_bf16 v[28:31], v[174:177], v[200:203], v[28:31]
	v_mfma_f32_16x16x32_bf16 v[24:27], v[192:195], v[200:203], v[24:27]
	v_mfma_f32_16x16x32_bf16 v[20:23], v[174:177], v[208:211], v[20:23]
	v_mfma_f32_16x16x32_bf16 v[16:19], v[192:195], v[208:211], v[16:19]
	v_mfma_f32_16x16x32_bf16 v[12:15], v[174:177], v[216:219], v[12:15]
	v_mfma_f32_16x16x32_bf16 v[8:11], v[192:195], v[216:219], v[8:11]
	v_mfma_f32_16x16x32_bf16 v[4:7], v[174:177], v[224:227], v[4:7]
	v_mfma_f32_16x16x32_bf16 v[0:3], v[192:195], v[224:227], v[0:3]
	v_mfma_f32_16x16x32_bf16 v[28:31], v[178:181], v[204:207], v[28:31]
	v_mfma_f32_16x16x32_bf16 v[24:27], v[196:199], v[204:207], v[24:27]
	v_mfma_f32_16x16x32_bf16 v[20:23], v[178:181], v[212:215], v[20:23]
	v_mfma_f32_16x16x32_bf16 v[16:19], v[196:199], v[212:215], v[16:19]
	v_mfma_f32_16x16x32_bf16 v[12:15], v[178:181], v[220:223], v[12:15]
	v_mfma_f32_16x16x32_bf16 v[8:11], v[196:199], v[220:223], v[8:11]
	v_mfma_f32_16x16x32_bf16 v[4:7], v[178:181], v[228:231], v[4:7]
	v_mfma_f32_16x16x32_bf16 v[0:3], v[196:199], v[228:231], v[0:3]
	s_barrier
	s_add_i32 s48, 0, 0x18000
	v_add_u32_e32 v161, s48, v159
	s_add_i32 s49, 0, 0x1c000
	ds_read_b128 v[138:141], v161
	ds_read_b128 v[162:165], v161 offset:1024
	ds_read_b128 v[166:169], v161 offset:2048
	ds_read_b128 v[170:173], v161 offset:3072
	v_add_u32_e32 v161, s49, v159
	ds_read_b128 v[174:177], v161
	ds_read_b128 v[178:181], v161 offset:1024
	ds_read_b128 v[192:195], v161 offset:2048
	ds_read_b128 v[196:199], v161 offset:3072
	s_add_u32 s44, s44, 0x20000
	s_addc_u32 s45, s45, 0
	s_mov_b32 m0, s3
	v_lshl_add_u64 v[240:241], s[44:45], 0, v[132:133]
	ds_read_b128 v[200:203], v160 offset:32768
	ds_read_b128 v[204:207], v160 offset:33792
	ds_read_b128 v[208:211], v160 offset:34816
	ds_read_b128 v[212:215], v160 offset:35840
	ds_read_b128 v[216:219], v160 offset:36864
	ds_read_b128 v[220:223], v160 offset:37888
	ds_read_b128 v[224:227], v160 offset:38912
	ds_read_b128 v[228:231], v160 offset:39936
	global_load_lds_dwordx4 v[240:241], off
	v_lshl_add_u64 v[240:241], s[44:45], 0, v[130:131]
	s_mov_b32 m0, s4
	s_nop 0
	global_load_lds_dwordx4 v[240:241], off
	s_waitcnt vmcnt(8)
	s_waitcnt lgkmcnt(0)
	s_barrier
	s_waitcnt lgkmcnt(0)
	v_mfma_f32_16x16x32_bf16 v[124:127], v[138:141], v[200:203], v[124:127]
	v_mfma_f32_16x16x32_bf16 v[120:123], v[166:169], v[200:203], v[120:123]
	v_mfma_f32_16x16x32_bf16 v[116:119], v[138:141], v[208:211], v[116:119]
	v_mfma_f32_16x16x32_bf16 v[112:115], v[166:169], v[208:211], v[112:115]
	v_mfma_f32_16x16x32_bf16 v[108:111], v[138:141], v[216:219], v[108:111]
	v_mfma_f32_16x16x32_bf16 v[104:107], v[166:169], v[216:219], v[104:107]
	v_mfma_f32_16x16x32_bf16 v[100:103], v[138:141], v[224:227], v[100:103]
	v_mfma_f32_16x16x32_bf16 v[96:99], v[166:169], v[224:227], v[96:99]
	v_mfma_f32_16x16x32_bf16 v[124:127], v[162:165], v[204:207], v[124:127]
	v_mfma_f32_16x16x32_bf16 v[120:123], v[170:173], v[204:207], v[120:123]
	v_mfma_f32_16x16x32_bf16 v[116:119], v[162:165], v[212:215], v[116:119]
	v_mfma_f32_16x16x32_bf16 v[112:115], v[170:173], v[212:215], v[112:115]
	v_mfma_f32_16x16x32_bf16 v[108:111], v[162:165], v[220:223], v[108:111]
	v_mfma_f32_16x16x32_bf16 v[104:107], v[170:173], v[220:223], v[104:107]
	v_mfma_f32_16x16x32_bf16 v[100:103], v[162:165], v[228:231], v[100:103]
	v_mfma_f32_16x16x32_bf16 v[96:99], v[170:173], v[228:231], v[96:99]
	v_mfma_f32_16x16x32_bf16 v[92:95], v[174:177], v[200:203], v[92:95]
	v_mfma_f32_16x16x32_bf16 v[88:91], v[192:195], v[200:203], v[88:91]
	v_mfma_f32_16x16x32_bf16 v[84:87], v[174:177], v[208:211], v[84:87]
	v_mfma_f32_16x16x32_bf16 v[80:83], v[192:195], v[208:211], v[80:83]
	v_mfma_f32_16x16x32_bf16 v[76:79], v[174:177], v[216:219], v[76:79]
	v_mfma_f32_16x16x32_bf16 v[72:75], v[192:195], v[216:219], v[72:75]
	v_mfma_f32_16x16x32_bf16 v[68:71], v[174:177], v[224:227], v[68:71]
	v_mfma_f32_16x16x32_bf16 v[64:67], v[192:195], v[224:227], v[64:67]
	v_mfma_f32_16x16x32_bf16 v[92:95], v[178:181], v[204:207], v[92:95]
	v_mfma_f32_16x16x32_bf16 v[88:91], v[196:199], v[204:207], v[88:91]
	v_mfma_f32_16x16x32_bf16 v[84:87], v[178:181], v[212:215], v[84:87]
	v_mfma_f32_16x16x32_bf16 v[80:83], v[196:199], v[212:215], v[80:83]
	v_mfma_f32_16x16x32_bf16 v[76:79], v[178:181], v[220:223], v[76:79]
	v_mfma_f32_16x16x32_bf16 v[72:75], v[196:199], v[220:223], v[72:75]
	v_mfma_f32_16x16x32_bf16 v[68:71], v[178:181], v[228:231], v[68:71]
	v_mfma_f32_16x16x32_bf16 v[64:67], v[196:199], v[228:231], v[64:67]
	s_barrier
; #define PG8_STAGE(bufoff, gbase, voff) do { _Pragma("unroll") for (int _i = 0; _i < 2; ++_i) \
;         __builtin_amdgcn_global_load_lds((const unsigned*)((const char*)(gbase) + (voff)[_i]), (LAS unsigned*)(lds + (bufoff) + ldsw + _i * 8192), 16, 0, 0); } while (0)
; #define PG8_LDA(dst, b, h) do { _Pragma("unroll") for (int m = 0; m < 4; ++m) _Pragma("unroll") for (int k = 0; k < 2; ++k) dst[m][k] = *(const LAS bf16x8*)(lds + PG8_SA(b, h) + aoff + m * 2048 + k * 1024); } while (0)
; #define PG8_MMA(ai, bj, At, Bt) do { __builtin_amdgcn_s_setprio(1); _Pragma("unroll") for (int m = 0; m < 4; ++m) _Pragma("unroll") for (int n = 0; n < 2; ++n) _Pragma("unroll") for (int k = 0; k < 2; ++k) \
;         acc[ai][bj][m][n] = __builtin_amdgcn_mfma_f32_16x16x32_bf16(Bt[n][k], At[m][k], acc[ai][bj][m][n], 0, 0, 0); __builtin_amdgcn_s_setprio(0); } while (0)
; #define PG8_WAIT_V(n) asm volatile("s_waitcnt vmcnt(" #n ")" ::: "memory")
; #define PG8_WAIT_L(n) asm volatile("s_waitcnt lgkmcnt(" #n ")" ::: "memory")
; #define PG8_BAR __builtin_amdgcn_s_barrier()
; #define PG8_SCHED __builtin_amdgcn_sched_barrier(0)
; template <class Epi, class Map>
; __device__ __forceinline__ void gemm_phase(LAS unsigned char* lds, const Gemm g, const Sched<Map>& S, const Epi& E) {
;     ...
;             PG8_LDA(At, 1, 1); PG8_STAGE(PG8_SB(1, 0), b3, voffB); PG8_STAGE(PG8_SB(1, 1), b3 + hstepB, voffB); PG8_STAGE(PG8_SA(1, 0), a3, voffA);
;             PG8_WAIT_V(8); PG8_WAIT_L(0); PG8_BAR; PG8_MMA(1, 0, At, B0); PG8_MMA(1, 1, At, B1); PG8_BAR; PG8_SCHED;
;         }
;         if (wr == 0) PG8_BAR;
;         E(acc, cur, wr, wc, fr, fq);
;         if (!has_next) break;
	s_add_i32 s44, s48, s0
	v_lshl_add_u64 v[232:233], v[232:233], 0, s[82:83]
	s_mov_b32 m0, s44
	ds_read_b128 v[200:203], v160 offset:49152
	ds_read_b128 v[204:207], v160 offset:50176
	ds_read_b128 v[208:211], v160 offset:51200
	ds_read_b128 v[212:215], v160 offset:52224
	ds_read_b128 v[216:219], v160 offset:53248
	ds_read_b128 v[220:223], v160 offset:54272
	ds_read_b128 v[224:227], v160 offset:55296
	ds_read_b128 v[228:231], v160 offset:56320
	global_load_lds_dwordx4 v[232:233], off
	s_add_i32 m0, s44, 0x2000
	s_add_u32 s36, s36, 0x20080
	v_lshl_add_u64 v[232:233], v[234:235], 0, s[82:83]
	s_addc_u32 s37, s37, 0
	s_add_i32 s44, s49, s0
	global_load_lds_dwordx4 v[232:233], off
	v_lshl_add_u64 v[232:233], s[36:37], 0, v[144:145]
	s_mov_b32 m0, s44
	s_nop 0
	global_load_lds_dwordx4 v[232:233], off
	v_lshl_add_u64 v[232:233], s[36:37], 0, v[128:129]
	s_add_i32 m0, s44, 0x2000
	s_nop 0
	global_load_lds_dwordx4 v[232:233], off
	v_lshl_add_u64 v[232:233], v[236:237], 0, s[82:83]
	s_mov_b32 m0, s6
	s_nop 0
	global_load_lds_dwordx4 v[232:233], off
	v_lshl_add_u64 v[232:233], v[238:239], 0, s[82:83]
	s_mov_b32 m0, s7
	s_nop 0
	global_load_lds_dwordx4 v[232:233], off
	s_waitcnt vmcnt(8)
	s_waitcnt lgkmcnt(0)
	s_barrier
	s_waitcnt lgkmcnt(0)
	v_mfma_f32_16x16x32_bf16 v[60:63], v[138:141], v[200:203], v[60:63]
	v_mfma_f32_16x16x32_bf16 v[56:59], v[166:169], v[200:203], v[56:59]
	v_mfma_f32_16x16x32_bf16 v[52:55], v[138:141], v[208:211], v[52:55]
	v_mfma_f32_16x16x32_bf16 v[48:51], v[166:169], v[208:211], v[48:51]
	v_mfma_f32_16x16x32_bf16 v[44:47], v[138:141], v[216:219], v[44:47]
	v_mfma_f32_16x16x32_bf16 v[40:43], v[166:169], v[216:219], v[40:43]
	v_mfma_f32_16x16x32_bf16 v[36:39], v[138:141], v[224:227], v[36:39]
	v_mfma_f32_16x16x32_bf16 v[32:35], v[166:169], v[224:227], v[32:35]
	v_mfma_f32_16x16x32_bf16 v[60:63], v[162:165], v[204:207], v[60:63]
	v_mfma_f32_16x16x32_bf16 v[56:59], v[170:173], v[204:207], v[56:59]
	v_mfma_f32_16x16x32_bf16 v[52:55], v[162:165], v[212:215], v[52:55]
	v_mfma_f32_16x16x32_bf16 v[48:51], v[170:173], v[212:215], v[48:51]
	v_mfma_f32_16x16x32_bf16 v[44:47], v[162:165], v[220:223], v[44:47]
	v_mfma_f32_16x16x32_bf16 v[40:43], v[170:173], v[220:223], v[40:43]
	v_mfma_f32_16x16x32_bf16 v[36:39], v[162:165], v[228:231], v[36:39]
	v_mfma_f32_16x16x32_bf16 v[32:35], v[170:173], v[228:231], v[32:35]
	v_mfma_f32_16x16x32_bf16 v[28:31], v[174:177], v[200:203], v[28:31]
	v_mfma_f32_16x16x32_bf16 v[24:27], v[192:195], v[200:203], v[24:27]
	v_mfma_f32_16x16x32_bf16 v[20:23], v[174:177], v[208:211], v[20:23]
	v_mfma_f32_16x16x32_bf16 v[16:19], v[192:195], v[208:211], v[16:19]
	v_mfma_f32_16x16x32_bf16 v[12:15], v[174:177], v[216:219], v[12:15]
	v_mfma_f32_16x16x32_bf16 v[8:11], v[192:195], v[216:219], v[8:11]
	v_mfma_f32_16x16x32_bf16 v[4:7], v[174:177], v[224:227], v[4:7]
	v_mfma_f32_16x16x32_bf16 v[0:3], v[192:195], v[224:227], v[0:3]
	v_mfma_f32_16x16x32_bf16 v[28:31], v[178:181], v[204:207], v[28:31]
	v_mfma_f32_16x16x32_bf16 v[24:27], v[196:199], v[204:207], v[24:27]
	v_mfma_f32_16x16x32_bf16 v[20:23], v[178:181], v[212:215], v[20:23]
	v_mfma_f32_16x16x32_bf16 v[16:19], v[196:199], v[212:215], v[16:19]
	v_mfma_f32_16x16x32_bf16 v[12:15], v[178:181], v[220:223], v[12:15]
	v_mfma_f32_16x16x32_bf16 v[8:11], v[196:199], v[220:223], v[8:11]
	v_mfma_f32_16x16x32_bf16 v[4:7], v[178:181], v[228:231], v[4:7]
	v_mfma_f32_16x16x32_bf16 v[0:3], v[196:199], v[228:231], v[0:3]
	s_barrier
	s_add_i32 s47, s47, 2
	s_add_u32 s34, s34, 0x100
	s_addc_u32 s35, s35, 0
	s_add_u32 s39, s39, 0x100
	s_addc_u32 s46, s46, 0
	s_cmp_gt_u32 s47, 5
	s_cbranch_scc0 .LBB0_808
	s_and_b64 vcc, exec, s[18:19]
	s_cbranch_vccz .LBB0_811
	s_barrier

; #define PG8_STAGE(bufoff, gbase, voff) do { _Pragma("unroll") for (int _i = 0; _i < 2; ++_i) \
;         __builtin_amdgcn_global_load_lds((const unsigned*)((const char*)(gbase) + (voff)[_i]), (LAS unsigned*)(lds + (bufoff) + ldsw + _i * 8192), 16, 0, 0); } while (0)
; #define PG8_LDA(dst, b, h) do { _Pragma("unroll") for (int m = 0; m < 4; ++m) _Pragma("unroll") for (int k = 0; k < 2; ++k) dst[m][k] = *(const LAS bf16x8*)(lds + PG8_SA(b, h) + aoff + m * 2048 + k * 1024); } while (0)
; #define PG8_LDB(dst, b, h) do { _Pragma("unroll") for (int n = 0; n < 2; ++n) _Pragma("unroll") for (int k = 0; k < 2; ++k) dst[n][k] = *(const LAS bf16x8*)(lds + PG8_SB(b, h) + boff + n * 2048 + k * 1024); } while (0)
; #define PG8_MMA(ai, bj, At, Bt) do { __builtin_amdgcn_s_setprio(1); _Pragma("unroll") for (int m = 0; m < 4; ++m) _Pragma("unroll") for (int n = 0; n < 2; ++n) _Pragma("unroll") for (int k = 0; k < 2; ++k) \
;         acc[ai][bj][m][n] = __builtin_amdgcn_mfma_f32_16x16x32_bf16(Bt[n][k], At[m][k], acc[ai][bj][m][n], 0, 0, 0); __builtin_amdgcn_s_setprio(0); } while (0)
; #define PG8_WAIT_V(n) asm volatile("s_waitcnt vmcnt(" #n ")" ::: "memory")
; #define PG8_WAIT_L(n) asm volatile("s_waitcnt lgkmcnt(" #n ")" ::: "memory")
; #define PG8_BAR __builtin_amdgcn_s_barrier()
; #define PG8_SCHED __builtin_amdgcn_sched_barrier(0)
; template <class Epi, class Map>
; __device__ __forceinline__ void gemm_phase(LAS unsigned char* lds, const Gemm g, const Sched<Map>& S, const Epi& E) {
;     ...
;         for (int t = 0; t < nt; t += 2) {
;             const bool last = (t == nt - 2);
;             const char* a1 = cA + (size_t)(t + 1) * kstep;
;             const char* a2 = last ? nA : cA + (size_t)(t + 2) * kstep; const char* b2 = last ? nB : cB + (size_t)(t + 2) * kstep;
;             const char* a3 = a2 + kstep; const char* b3 = b2 + kstep;
;             PG8_LDB(B0, 0, 0); PG8_LDB(B1, 0, 1); PG8_SCHED; PG8_LDA(At, 0, 0); PG8_STAGE(PG8_SA(1, 1), a1 + hstepA, voffA);
;             PG8_WAIT_V(8); PG8_WAIT_L(0); PG8_BAR; PG8_MMA(0, 0, At, B0); PG8_MMA(0, 1, At, B1); PG8_BAR; PG8_SCHED;
;             PG8_LDA(At, 0, 1); PG8_STAGE(PG8_SB(0, 0), b2, voffB); PG8_STAGE(PG8_SB(0, 1), b2 + hstepB, voffB); PG8_STAGE(PG8_SA(0, 0), a2, voffA);
.LBB0_880:
	s_add_u32 s9, s18, 0xfff80080
	s_addc_u32 s10, s19, -1
	s_add_i32 s11, 0, 0x10000
	s_cmp_eq_u32 s8, 28
	s_cselect_b32 s25, s2, s10
	s_cselect_b32 s24, s3, s9
	s_cselect_b32 s21, s4, s7
	s_cselect_b32 s20, s5, s6
	s_add_i32 s9, 0, 0x14000
	v_add_u32_e32 v166, s11, v173
	v_add_u32_e32 v170, s9, v173
	ds_read_b128 v[124:127], v166
	ds_read_b128 v[132:135], v166 offset:1024
	ds_read_b128 v[162:165], v166 offset:2048
	ds_read_b128 v[166:169], v166 offset:3072
	ds_read_b128 v[176:179], v170
	ds_read_b128 v[192:195], v170 offset:1024
	ds_read_b128 v[196:199], v170 offset:2048
	ds_read_b128 v[200:203], v170 offset:3072
	v_lshl_add_u64 v[170:171], s[18:19], 0, v[142:143]
	s_add_i32 m0, s29, 0xc000
	ds_read_b128 v[204:207], v174
	ds_read_b128 v[208:211], v174 offset:1024
	ds_read_b128 v[212:215], v174 offset:2048
	ds_read_b128 v[216:219], v174 offset:3072
	ds_read_b128 v[220:223], v174 offset:4096
	ds_read_b128 v[224:227], v174 offset:5120
	ds_read_b128 v[228:231], v174 offset:6144
	ds_read_b128 v[232:235], v174 offset:7168
	global_load_lds_dwordx4 v[170:171], off
	v_lshl_add_u64 v[170:171], s[18:19], 0, v[160:161]
	s_add_i32 m0, s29, 0xe000
	s_nop 0
	global_load_lds_dwordx4 v[170:171], off
	s_waitcnt vmcnt(8)
	s_waitcnt lgkmcnt(0)
	s_barrier
	s_waitcnt lgkmcnt(0)
	v_mfma_f32_16x16x32_bf16 v[128:131], v[124:127], v[204:207], v[128:131]
	v_mfma_f32_16x16x32_bf16 v[120:123], v[162:165], v[204:207], v[120:123]
	v_mfma_f32_16x16x32_bf16 v[108:111], v[124:127], v[212:215], v[108:111]
	v_mfma_f32_16x16x32_bf16 v[104:107], v[162:165], v[212:215], v[104:107]
	v_mfma_f32_16x16x32_bf16 v[92:95], v[124:127], v[220:223], v[92:95]
	v_mfma_f32_16x16x32_bf16 v[88:91], v[162:165], v[220:223], v[88:91]
	v_mfma_f32_16x16x32_bf16 v[76:79], v[124:127], v[228:231], v[76:79]
	v_mfma_f32_16x16x32_bf16 v[72:75], v[162:165], v[228:231], v[72:75]
	v_mfma_f32_16x16x32_bf16 v[128:131], v[132:135], v[208:211], v[128:131]
	v_mfma_f32_16x16x32_bf16 v[120:123], v[166:169], v[208:211], v[120:123]
	v_mfma_f32_16x16x32_bf16 v[108:111], v[132:135], v[216:219], v[108:111]
	v_mfma_f32_16x16x32_bf16 v[104:107], v[166:169], v[216:219], v[104:107]
	v_mfma_f32_16x16x32_bf16 v[92:95], v[132:135], v[224:227], v[92:95]
	v_mfma_f32_16x16x32_bf16 v[88:91], v[166:169], v[224:227], v[88:91]
	v_mfma_f32_16x16x32_bf16 v[76:79], v[132:135], v[232:235], v[76:79]
	v_mfma_f32_16x16x32_bf16 v[72:75], v[166:169], v[232:235], v[72:75]
	v_mfma_f32_16x16x32_bf16 v[116:119], v[176:179], v[204:207], v[116:119]
	v_mfma_f32_16x16x32_bf16 v[112:115], v[196:199], v[204:207], v[112:115]
	v_mfma_f32_16x16x32_bf16 v[100:103], v[176:179], v[212:215], v[100:103]
	v_mfma_f32_16x16x32_bf16 v[96:99], v[196:199], v[212:215], v[96:99]
	v_mfma_f32_16x16x32_bf16 v[84:87], v[176:179], v[220:223], v[84:87]
	v_mfma_f32_16x16x32_bf16 v[80:83], v[196:199], v[220:223], v[80:83]
	v_mfma_f32_16x16x32_bf16 v[68:71], v[176:179], v[228:231], v[68:71]
	v_mfma_f32_16x16x32_bf16 v[64:67], v[196:199], v[228:231], v[64:67]
	v_mfma_f32_16x16x32_bf16 v[116:119], v[192:195], v[208:211], v[116:119]
	v_mfma_f32_16x16x32_bf16 v[112:115], v[200:203], v[208:211], v[112:115]
	v_mfma_f32_16x16x32_bf16 v[100:103], v[192:195], v[216:219], v[100:103]
	v_mfma_f32_16x16x32_bf16 v[96:99], v[200:203], v[216:219], v[96:99]
	v_mfma_f32_16x16x32_bf16 v[84:87], v[192:195], v[224:227], v[84:87]
	v_mfma_f32_16x16x32_bf16 v[80:83], v[200:203], v[224:227], v[80:83]
	v_mfma_f32_16x16x32_bf16 v[68:71], v[192:195], v[232:235], v[68:71]
	v_mfma_f32_16x16x32_bf16 v[64:67], v[200:203], v[232:235], v[64:67]
	s_barrier
	s_add_i32 s10, s11, s28
	v_lshl_add_u64 v[170:171], s[20:21], 0, v[144:145]
	s_mov_b32 m0, s10
	ds_read_b128 v[204:207], v174 offset:16384
	ds_read_b128 v[208:211], v174 offset:17408
	ds_read_b128 v[212:215], v174 offset:18432
	ds_read_b128 v[216:219], v174 offset:19456
	ds_read_b128 v[220:223], v174 offset:20480
	ds_read_b128 v[224:227], v174 offset:21504
	ds_read_b128 v[228:231], v174 offset:22528
	ds_read_b128 v[232:235], v174 offset:23552
	global_load_lds_dwordx4 v[170:171], off
	s_add_i32 m0, s10, 0x2000
	s_add_u32 s10, s20, 0x80000
	v_lshl_add_u64 v[180:181], s[20:21], 0, v[136:137]
	s_addc_u32 s11, s21, 0
	s_add_i32 s9, s9, s28
	global_load_lds_dwordx4 v[180:181], off
	v_lshl_add_u64 v[236:237], s[10:11], 0, v[144:145]
	s_mov_b32 m0, s9
	v_lshl_add_u64 v[238:239], s[24:25], 0, v[138:139]
	global_load_lds_dwordx4 v[236:237], off
	v_lshl_add_u64 v[236:237], s[10:11], 0, v[136:137]
	s_add_i32 m0, s9, 0x2000
	s_nop 0
	global_load_lds_dwordx4 v[236:237], off
	v_lshl_add_u64 v[236:237], s[24:25], 0, v[140:141]
	s_mov_b32 m0, s29
	s_nop 0
	global_load_lds_dwordx4 v[236:237], off
	s_mov_b32 m0, s30
	s_nop 0
	global_load_lds_dwordx4 v[238:239], off
	s_waitcnt vmcnt(8)
	s_waitcnt lgkmcnt(0)
	s_barrier
; #define PG8_STAGE(bufoff, gbase, voff) do { _Pragma("unroll") for (int _i = 0; _i < 2; ++_i) \
;         __builtin_amdgcn_global_load_lds((const unsigned*)((const char*)(gbase) + (voff)[_i]), (LAS unsigned*)(lds + (bufoff) + ldsw + _i * 8192), 16, 0, 0); } while (0)
; #define PG8_LDA(dst, b, h) do { _Pragma("unroll") for (int m = 0; m < 4; ++m) _Pragma("unroll") for (int k = 0; k < 2; ++k) dst[m][k] = *(const LAS bf16x8*)(lds + PG8_SA(b, h) + aoff + m * 2048 + k * 1024); } while (0)
; #define PG8_LDB(dst, b, h) do { _Pragma("unroll") for (int n = 0; n < 2; ++n) _Pragma("unroll") for (int k = 0; k < 2; ++k) dst[n][k] = *(const LAS bf16x8*)(lds + PG8_SB(b, h) + boff + n * 2048 + k * 1024); } while (0)
; #define PG8_MMA(ai, bj, At, Bt) do { __builtin_amdgcn_s_setprio(1); _Pragma("unroll") for (int m = 0; m < 4; ++m) _Pragma("unroll") for (int n = 0; n < 2; ++n) _Pragma("unroll") for (int k = 0; k < 2; ++k) \
;         acc[ai][bj][m][n] = __builtin_amdgcn_mfma_f32_16x16x32_bf16(Bt[n][k], At[m][k], acc[ai][bj][m][n], 0, 0, 0); __builtin_amdgcn_s_setprio(0); } while (0)
; #define PG8_WAIT_V(n) asm volatile("s_waitcnt vmcnt(" #n ")" ::: "memory")
; #define PG8_WAIT_L(n) asm volatile("s_waitcnt lgkmcnt(" #n ")" ::: "memory")
; #define PG8_BAR __builtin_amdgcn_s_barrier()
; #define PG8_SCHED __builtin_amdgcn_sched_barrier(0)
; template <class Epi, class Map>
; __device__ __forceinline__ void gemm_phase(LAS unsigned char* lds, const Gemm g, const Sched<Map>& S, const Epi& E) {
;     ...
;             PG8_WAIT_V(8); PG8_WAIT_L(0); PG8_BAR; PG8_MMA(1, 0, At, B0); PG8_MMA(1, 1, At, B1); PG8_BAR; PG8_SCHED;
;             PG8_LDB(B0, 1, 0); PG8_LDB(B1, 1, 1); PG8_SCHED; PG8_LDA(At, 1, 0); PG8_STAGE(PG8_SA(0, 1), a2 + hstepA, voffA);
;             PG8_WAIT_V(8); PG8_WAIT_L(0); PG8_BAR; PG8_MMA(0, 0, At, B0); PG8_MMA(0, 1, At, B1); PG8_BAR; PG8_SCHED;
	s_waitcnt lgkmcnt(0)
	v_mfma_f32_16x16x32_bf16 v[60:63], v[124:127], v[204:207], v[60:63]
	v_mfma_f32_16x16x32_bf16 v[56:59], v[162:165], v[204:207], v[56:59]
	v_mfma_f32_16x16x32_bf16 v[44:47], v[124:127], v[212:215], v[44:47]
	v_mfma_f32_16x16x32_bf16 v[40:43], v[162:165], v[212:215], v[40:43]
	v_mfma_f32_16x16x32_bf16 v[28:31], v[124:127], v[220:223], v[28:31]
	v_mfma_f32_16x16x32_bf16 v[24:27], v[162:165], v[220:223], v[24:27]
	v_mfma_f32_16x16x32_bf16 v[12:15], v[124:127], v[228:231], v[12:15]
	v_mfma_f32_16x16x32_bf16 v[8:11], v[162:165], v[228:231], v[8:11]
	v_mfma_f32_16x16x32_bf16 v[60:63], v[132:135], v[208:211], v[60:63]
	v_mfma_f32_16x16x32_bf16 v[56:59], v[166:169], v[208:211], v[56:59]
	v_mfma_f32_16x16x32_bf16 v[44:47], v[132:135], v[216:219], v[44:47]
	v_mfma_f32_16x16x32_bf16 v[40:43], v[166:169], v[216:219], v[40:43]
	v_mfma_f32_16x16x32_bf16 v[28:31], v[132:135], v[224:227], v[28:31]
	v_mfma_f32_16x16x32_bf16 v[24:27], v[166:169], v[224:227], v[24:27]
	v_mfma_f32_16x16x32_bf16 v[12:15], v[132:135], v[232:235], v[12:15]
	v_mfma_f32_16x16x32_bf16 v[8:11], v[166:169], v[232:235], v[8:11]
	v_mfma_f32_16x16x32_bf16 v[52:55], v[176:179], v[204:207], v[52:55]
	v_mfma_f32_16x16x32_bf16 v[48:51], v[196:199], v[204:207], v[48:51]
	v_mfma_f32_16x16x32_bf16 v[36:39], v[176:179], v[212:215], v[36:39]
	v_mfma_f32_16x16x32_bf16 v[32:35], v[196:199], v[212:215], v[32:35]
	v_mfma_f32_16x16x32_bf16 v[20:23], v[176:179], v[220:223], v[20:23]
	v_mfma_f32_16x16x32_bf16 v[16:19], v[196:199], v[220:223], v[16:19]
	v_mfma_f32_16x16x32_bf16 v[4:7], v[176:179], v[228:231], v[4:7]
	v_mfma_f32_16x16x32_bf16 v[0:3], v[196:199], v[228:231], v[0:3]
	v_mfma_f32_16x16x32_bf16 v[52:55], v[192:195], v[208:211], v[52:55]
	v_mfma_f32_16x16x32_bf16 v[48:51], v[200:203], v[208:211], v[48:51]
	v_mfma_f32_16x16x32_bf16 v[36:39], v[192:195], v[216:219], v[36:39]
	v_mfma_f32_16x16x32_bf16 v[32:35], v[200:203], v[216:219], v[32:35]
	v_mfma_f32_16x16x32_bf16 v[20:23], v[192:195], v[224:227], v[20:23]
	v_mfma_f32_16x16x32_bf16 v[16:19], v[200:203], v[224:227], v[16:19]
	v_mfma_f32_16x16x32_bf16 v[4:7], v[192:195], v[232:235], v[4:7]
	v_mfma_f32_16x16x32_bf16 v[0:3], v[200:203], v[232:235], v[0:3]
	s_barrier
	s_add_i32 s9, 0, 0x18000
	s_add_i32 s12, 0, 0x1c000
	v_add_u32_e32 v166, s9, v173
	v_add_u32_e32 v175, s12, v173
	ds_read_b128 v[124:127], v166
	ds_read_b128 v[132:135], v166 offset:1024
	ds_read_b128 v[162:165], v166 offset:2048
	ds_read_b128 v[166:169], v166 offset:3072
	ds_read_b128 v[176:179], v175
	ds_read_b128 v[192:195], v175 offset:1024
	ds_read_b128 v[196:199], v175 offset:2048
	ds_read_b128 v[200:203], v175 offset:3072
	s_add_u32 s10, s24, 0x80000
	s_addc_u32 s11, s25, 0
	s_mov_b32 m0, s31
	v_lshl_add_u64 v[240:241], s[10:11], 0, v[140:141]
	ds_read_b128 v[204:207], v174 offset:32768
	ds_read_b128 v[208:211], v174 offset:33792
	ds_read_b128 v[212:215], v174 offset:34816
	ds_read_b128 v[216:219], v174 offset:35840
	ds_read_b128 v[220:223], v174 offset:36864
	ds_read_b128 v[224:227], v174 offset:37888
	ds_read_b128 v[228:231], v174 offset:38912
	ds_read_b128 v[232:235], v174 offset:39936
	global_load_lds_dwordx4 v[240:241], off
	v_lshl_add_u64 v[240:241], s[10:11], 0, v[138:139]
	s_mov_b32 m0, s34
	s_nop 0
	global_load_lds_dwordx4 v[240:241], off
	s_waitcnt vmcnt(8)
	s_waitcnt lgkmcnt(0)
	s_barrier
	s_waitcnt lgkmcnt(0)
	v_mfma_f32_16x16x32_bf16 v[128:131], v[124:127], v[204:207], v[128:131]
	v_mfma_f32_16x16x32_bf16 v[120:123], v[162:165], v[204:207], v[120:123]
	v_mfma_f32_16x16x32_bf16 v[108:111], v[124:127], v[212:215], v[108:111]
	v_mfma_f32_16x16x32_bf16 v[104:107], v[162:165], v[212:215], v[104:107]
	v_mfma_f32_16x16x32_bf16 v[92:95], v[124:127], v[220:223], v[92:95]
	v_mfma_f32_16x16x32_bf16 v[88:91], v[162:165], v[220:223], v[88:91]
	v_mfma_f32_16x16x32_bf16 v[76:79], v[124:127], v[228:231], v[76:79]
	v_mfma_f32_16x16x32_bf16 v[72:75], v[162:165], v[228:231], v[72:75]
	v_mfma_f32_16x16x32_bf16 v[128:131], v[132:135], v[208:211], v[128:131]
	v_mfma_f32_16x16x32_bf16 v[120:123], v[166:169], v[208:211], v[120:123]
	v_mfma_f32_16x16x32_bf16 v[108:111], v[132:135], v[216:219], v[108:111]
	v_mfma_f32_16x16x32_bf16 v[104:107], v[166:169], v[216:219], v[104:107]
	v_mfma_f32_16x16x32_bf16 v[92:95], v[132:135], v[224:227], v[92:95]
	v_mfma_f32_16x16x32_bf16 v[88:91], v[166:169], v[224:227], v[88:91]
	v_mfma_f32_16x16x32_bf16 v[76:79], v[132:135], v[232:235], v[76:79]
	v_mfma_f32_16x16x32_bf16 v[72:75], v[166:169], v[232:235], v[72:75]
	v_mfma_f32_16x16x32_bf16 v[116:119], v[176:179], v[204:207], v[116:119]
	v_mfma_f32_16x16x32_bf16 v[112:115], v[196:199], v[204:207], v[112:115]
	v_mfma_f32_16x16x32_bf16 v[100:103], v[176:179], v[212:215], v[100:103]
	v_mfma_f32_16x16x32_bf16 v[96:99], v[196:199], v[212:215], v[96:99]
	v_mfma_f32_16x16x32_bf16 v[84:87], v[176:179], v[220:223], v[84:87]
	v_mfma_f32_16x16x32_bf16 v[80:83], v[196:199], v[220:223], v[80:83]
	v_mfma_f32_16x16x32_bf16 v[68:71], v[176:179], v[228:231], v[68:71]
	v_mfma_f32_16x16x32_bf16 v[64:67], v[196:199], v[228:231], v[64:67]
	v_mfma_f32_16x16x32_bf16 v[116:119], v[192:195], v[208:211], v[116:119]
	v_mfma_f32_16x16x32_bf16 v[112:115], v[200:203], v[208:211], v[112:115]
	v_mfma_f32_16x16x32_bf16 v[100:103], v[192:195], v[216:219], v[100:103]
	v_mfma_f32_16x16x32_bf16 v[96:99], v[200:203], v[216:219], v[96:99]
	v_mfma_f32_16x16x32_bf16 v[84:87], v[192:195], v[224:227], v[84:87]
	v_mfma_f32_16x16x32_bf16 v[80:83], v[200:203], v[224:227], v[80:83]
	v_mfma_f32_16x16x32_bf16 v[68:71], v[192:195], v[232:235], v[68:71]
	v_mfma_f32_16x16x32_bf16 v[64:67], v[200:203], v[232:235], v[64:67]
	s_barrier
; #define PG8_STAGE(bufoff, gbase, voff) do { _Pragma("unroll") for (int _i = 0; _i < 2; ++_i) \
;         __builtin_amdgcn_global_load_lds((const unsigned*)((const char*)(gbase) + (voff)[_i]), (LAS unsigned*)(lds + (bufoff) + ldsw + _i * 8192), 16, 0, 0); } while (0)
; #define PG8_LDA(dst, b, h) do { _Pragma("unroll") for (int m = 0; m < 4; ++m) _Pragma("unroll") for (int k = 0; k < 2; ++k) dst[m][k] = *(const LAS bf16x8*)(lds + PG8_SA(b, h) + aoff + m * 2048 + k * 1024); } while (0)
; #define PG8_MMA(ai, bj, At, Bt) do { __builtin_amdgcn_s_setprio(1); _Pragma("unroll") for (int m = 0; m < 4; ++m) _Pragma("unroll") for (int n = 0; n < 2; ++n) _Pragma("unroll") for (int k = 0; k < 2; ++k) \
;         acc[ai][bj][m][n] = __builtin_amdgcn_mfma_f32_16x16x32_bf16(Bt[n][k], At[m][k], acc[ai][bj][m][n], 0, 0, 0); __builtin_amdgcn_s_setprio(0); } while (0)
; #define PG8_WAIT_V(n) asm volatile("s_waitcnt vmcnt(" #n ")" ::: "memory")
; #define PG8_WAIT_L(n) asm volatile("s_waitcnt lgkmcnt(" #n ")" ::: "memory")
; #define PG8_BAR __builtin_amdgcn_s_barrier()
; #define PG8_SCHED __builtin_amdgcn_sched_barrier(0)
; template <class Epi, class Map>
; __device__ __forceinline__ void gemm_phase(LAS unsigned char* lds, const Gemm g, const Sched<Map>& S, const Epi& E) {
;     ...
;             PG8_LDA(At, 1, 1); PG8_STAGE(PG8_SB(1, 0), b3, voffB); PG8_STAGE(PG8_SB(1, 1), b3 + hstepB, voffB); PG8_STAGE(PG8_SA(1, 0), a3, voffA);
;             PG8_WAIT_V(8); PG8_WAIT_L(0); PG8_BAR; PG8_MMA(1, 0, At, B0); PG8_MMA(1, 1, At, B1); PG8_BAR; PG8_SCHED;
;         }
;         if (wr == 0) PG8_BAR;
;         E(acc, cur, wr, wc, fr, fq);
;         if (!has_next) break;
	s_add_i32 s9, s9, s28
	v_lshl_add_u64 v[170:171], v[170:171], 0, s[82:83]
	s_mov_b32 m0, s9
	ds_read_b128 v[204:207], v174 offset:49152
	ds_read_b128 v[208:211], v174 offset:50176
	ds_read_b128 v[212:215], v174 offset:51200
	ds_read_b128 v[216:219], v174 offset:52224
	ds_read_b128 v[220:223], v174 offset:53248
	ds_read_b128 v[224:227], v174 offset:54272
	ds_read_b128 v[228:231], v174 offset:55296
	ds_read_b128 v[232:235], v174 offset:56320
	global_load_lds_dwordx4 v[170:171], off
	s_add_i32 m0, s9, 0x2000
	s_add_u32 s10, s20, 0x80080
	v_lshl_add_u64 v[170:171], v[180:181], 0, s[82:83]
	s_addc_u32 s11, s21, 0
	s_add_i32 s9, s12, s28
	global_load_lds_dwordx4 v[170:171], off
	v_lshl_add_u64 v[170:171], s[10:11], 0, v[144:145]
	s_mov_b32 m0, s9
	s_nop 0
	global_load_lds_dwordx4 v[170:171], off
	v_lshl_add_u64 v[170:171], s[10:11], 0, v[136:137]
	s_add_i32 m0, s9, 0x2000
	s_nop 0
	global_load_lds_dwordx4 v[170:171], off
	v_lshl_add_u64 v[170:171], v[236:237], 0, s[82:83]
	s_mov_b32 m0, s36
	s_nop 0
	global_load_lds_dwordx4 v[170:171], off
	v_lshl_add_u64 v[170:171], v[238:239], 0, s[82:83]
	s_mov_b32 m0, s37
	s_nop 0
	global_load_lds_dwordx4 v[170:171], off
	s_waitcnt vmcnt(8)
	s_waitcnt lgkmcnt(0)
	s_barrier
	s_waitcnt lgkmcnt(0)
	v_mfma_f32_16x16x32_bf16 v[60:63], v[124:127], v[204:207], v[60:63]
	v_mfma_f32_16x16x32_bf16 v[56:59], v[162:165], v[204:207], v[56:59]
	v_mfma_f32_16x16x32_bf16 v[44:47], v[124:127], v[212:215], v[44:47]
	v_mfma_f32_16x16x32_bf16 v[40:43], v[162:165], v[212:215], v[40:43]
	v_mfma_f32_16x16x32_bf16 v[28:31], v[124:127], v[220:223], v[28:31]
	v_mfma_f32_16x16x32_bf16 v[24:27], v[162:165], v[220:223], v[24:27]
	v_mfma_f32_16x16x32_bf16 v[12:15], v[124:127], v[228:231], v[12:15]
	v_mfma_f32_16x16x32_bf16 v[8:11], v[162:165], v[228:231], v[8:11]
	v_mfma_f32_16x16x32_bf16 v[60:63], v[132:135], v[208:211], v[60:63]
	v_mfma_f32_16x16x32_bf16 v[56:59], v[166:169], v[208:211], v[56:59]
	v_mfma_f32_16x16x32_bf16 v[44:47], v[132:135], v[216:219], v[44:47]
	v_mfma_f32_16x16x32_bf16 v[40:43], v[166:169], v[216:219], v[40:43]
	v_mfma_f32_16x16x32_bf16 v[28:31], v[132:135], v[224:227], v[28:31]
	v_mfma_f32_16x16x32_bf16 v[24:27], v[166:169], v[224:227], v[24:27]
	v_mfma_f32_16x16x32_bf16 v[12:15], v[132:135], v[232:235], v[12:15]
	v_mfma_f32_16x16x32_bf16 v[8:11], v[166:169], v[232:235], v[8:11]
	v_mfma_f32_16x16x32_bf16 v[52:55], v[176:179], v[204:207], v[52:55]
	v_mfma_f32_16x16x32_bf16 v[48:51], v[196:199], v[204:207], v[48:51]
	v_mfma_f32_16x16x32_bf16 v[36:39], v[176:179], v[212:215], v[36:39]
	v_mfma_f32_16x16x32_bf16 v[32:35], v[196:199], v[212:215], v[32:35]
	v_mfma_f32_16x16x32_bf16 v[20:23], v[176:179], v[220:223], v[20:23]
	v_mfma_f32_16x16x32_bf16 v[16:19], v[196:199], v[220:223], v[16:19]
	v_mfma_f32_16x16x32_bf16 v[4:7], v[176:179], v[228:231], v[4:7]
	v_mfma_f32_16x16x32_bf16 v[0:3], v[196:199], v[228:231], v[0:3]
	v_mfma_f32_16x16x32_bf16 v[52:55], v[192:195], v[208:211], v[52:55]
	v_mfma_f32_16x16x32_bf16 v[48:51], v[200:203], v[208:211], v[48:51]
	v_mfma_f32_16x16x32_bf16 v[36:39], v[192:195], v[216:219], v[36:39]
	v_mfma_f32_16x16x32_bf16 v[32:35], v[200:203], v[216:219], v[32:35]
	v_mfma_f32_16x16x32_bf16 v[20:23], v[192:195], v[224:227], v[20:23]
	v_mfma_f32_16x16x32_bf16 v[16:19], v[200:203], v[224:227], v[16:19]
	v_mfma_f32_16x16x32_bf16 v[4:7], v[192:195], v[232:235], v[4:7]
	v_mfma_f32_16x16x32_bf16 v[0:3], v[200:203], v[232:235], v[0:3]
	s_barrier
	s_add_i32 s8, s8, 2
	s_add_u32 s18, s18, 0x100
	s_addc_u32 s19, s19, 0
	s_add_u32 s6, s6, 0x100
	s_addc_u32 s7, s7, 0
	s_cmp_gt_u32 s8, 29
	s_cbranch_scc0 .LBB0_880
	s_and_b64 vcc, exec, s[44:45]
	s_cbranch_vccz .LBB0_883
	s_barrier

; #define PG8_STAGE(bufoff, gbase, voff) do { _Pragma("unroll") for (int _i = 0; _i < 2; ++_i) \
;         __builtin_amdgcn_global_load_lds((const unsigned*)((const char*)(gbase) + (voff)[_i]), (LAS unsigned*)(lds + (bufoff) + ldsw + _i * 8192), 16, 0, 0); } while (0)
; #define PG8_LDA(dst, b, h) do { _Pragma("unroll") for (int m = 0; m < 4; ++m) _Pragma("unroll") for (int k = 0; k < 2; ++k) dst[m][k] = *(const LAS bf16x8*)(lds + PG8_SA(b, h) + aoff + m * 2048 + k * 1024); } while (0)
; #define PG8_LDB(dst, b, h) do { _Pragma("unroll") for (int n = 0; n < 2; ++n) _Pragma("unroll") for (int k = 0; k < 2; ++k) dst[n][k] = *(const LAS bf16x8*)(lds + PG8_SB(b, h) + boff + n * 2048 + k * 1024); } while (0)
; #define PG8_MMA(ai, bj, At, Bt) do { __builtin_amdgcn_s_setprio(1); _Pragma("unroll") for (int m = 0; m < 4; ++m) _Pragma("unroll") for (int n = 0; n < 2; ++n) _Pragma("unroll") for (int k = 0; k < 2; ++k) \
;         acc[ai][bj][m][n] = __builtin_amdgcn_mfma_f32_16x16x32_bf16(Bt[n][k], At[m][k], acc[ai][bj][m][n], 0, 0, 0); __builtin_amdgcn_s_setprio(0); } while (0)
; #define PG8_WAIT_V(n) asm volatile("s_waitcnt vmcnt(" #n ")" ::: "memory")
; #define PG8_WAIT_L(n) asm volatile("s_waitcnt lgkmcnt(" #n ")" ::: "memory")
; #define PG8_BAR __builtin_amdgcn_s_barrier()
; #define PG8_SCHED __builtin_amdgcn_sched_barrier(0)
; template <class Epi, class Map>
; __device__ __forceinline__ void gemm_phase(LAS unsigned char* lds, const Gemm g, const Sched<Map>& S, const Epi& E) {
;     ...
;         for (int t = 0; t < nt; t += 2) {
;             const bool last = (t == nt - 2);
;             const char* a1 = cA + (size_t)(t + 1) * kstep;
;             const char* a2 = last ? nA : cA + (size_t)(t + 2) * kstep; const char* b2 = last ? nB : cB + (size_t)(t + 2) * kstep;
;             const char* a3 = a2 + kstep; const char* b3 = b2 + kstep;
;             PG8_LDB(B0, 0, 0); PG8_LDB(B1, 0, 1); PG8_SCHED; PG8_LDA(At, 0, 0); PG8_STAGE(PG8_SA(1, 1), a1 + hstepA, voffA);
;             PG8_WAIT_V(8); PG8_WAIT_L(0); PG8_BAR; PG8_MMA(0, 0, At, B0); PG8_MMA(0, 1, At, B1); PG8_BAR; PG8_SCHED;
;             PG8_LDA(At, 0, 1); PG8_STAGE(PG8_SB(0, 0), b2, voffB); PG8_STAGE(PG8_SB(0, 1), b2 + hstepB, voffB); PG8_STAGE(PG8_SA(0, 0), a2, voffA);
.LBB0_952:
	s_add_u32 s40, s36, 0xfff00080
	s_addc_u32 s41, s37, -1
	s_add_i32 s50, 0, 0x10000
	s_cmp_eq_u32 s49, 60
	s_cselect_b32 s43, s33, s41
	s_cselect_b32 s42, s44, s40
	s_cselect_b32 s41, s45, s48
	s_cselect_b32 s40, s46, s47
	s_add_i32 s52, 0, 0x14000
	v_add_u32_e32 v108, s50, v173
	v_add_u32_e32 v170, s52, v173
	ds_read_b128 v[64:67], v108
	ds_read_b128 v[68:71], v108 offset:1024
	ds_read_b128 v[72:75], v108 offset:2048
	ds_read_b128 v[108:111], v108 offset:3072
	ds_read_b128 v[166:169], v170
	ds_read_b128 v[176:179], v170 offset:1024
	ds_read_b128 v[192:195], v170 offset:2048
	ds_read_b128 v[196:199], v170 offset:3072
	v_lshl_add_u64 v[170:171], s[36:37], 0, v[162:163]
	s_add_i32 m0, s1, 0xc000
	ds_read_b128 v[200:203], v174
	ds_read_b128 v[204:207], v174 offset:1024
	ds_read_b128 v[208:211], v174 offset:2048
	ds_read_b128 v[212:215], v174 offset:3072
	ds_read_b128 v[216:219], v174 offset:4096
	ds_read_b128 v[220:223], v174 offset:5120
	ds_read_b128 v[224:227], v174 offset:6144
	ds_read_b128 v[228:231], v174 offset:7168
	global_load_lds_dwordx4 v[170:171], off
	v_lshl_add_u64 v[170:171], s[36:37], 0, v[164:165]
	s_add_i32 m0, s1, 0xe000
	s_nop 0
	global_load_lds_dwordx4 v[170:171], off
	s_waitcnt vmcnt(8)
	s_waitcnt lgkmcnt(0)
	s_barrier
	s_waitcnt lgkmcnt(0)
	v_mfma_f32_16x16x32_bf16 v[140:143], v[64:67], v[200:203], v[140:143]
	v_mfma_f32_16x16x32_bf16 v[136:139], v[72:75], v[200:203], v[136:139]
	v_mfma_f32_16x16x32_bf16 v[132:135], v[64:67], v[208:211], v[132:135]
	v_mfma_f32_16x16x32_bf16 v[128:131], v[72:75], v[208:211], v[128:131]
	v_mfma_f32_16x16x32_bf16 v[104:107], v[64:67], v[216:219], v[104:107]
	v_mfma_f32_16x16x32_bf16 v[100:103], v[72:75], v[216:219], v[100:103]
	v_mfma_f32_16x16x32_bf16 v[96:99], v[64:67], v[224:227], v[96:99]
	v_mfma_f32_16x16x32_bf16 v[92:95], v[72:75], v[224:227], v[92:95]
	v_mfma_f32_16x16x32_bf16 v[140:143], v[68:71], v[204:207], v[140:143]
	v_mfma_f32_16x16x32_bf16 v[136:139], v[108:111], v[204:207], v[136:139]
	v_mfma_f32_16x16x32_bf16 v[132:135], v[68:71], v[212:215], v[132:135]
	v_mfma_f32_16x16x32_bf16 v[128:131], v[108:111], v[212:215], v[128:131]
	v_mfma_f32_16x16x32_bf16 v[104:107], v[68:71], v[220:223], v[104:107]
	v_mfma_f32_16x16x32_bf16 v[100:103], v[108:111], v[220:223], v[100:103]
	v_mfma_f32_16x16x32_bf16 v[96:99], v[68:71], v[228:231], v[96:99]
	v_mfma_f32_16x16x32_bf16 v[92:95], v[108:111], v[228:231], v[92:95]
	v_mfma_f32_16x16x32_bf16 v[124:127], v[166:169], v[200:203], v[124:127]
	v_mfma_f32_16x16x32_bf16 v[120:123], v[192:195], v[200:203], v[120:123]
	v_mfma_f32_16x16x32_bf16 v[116:119], v[166:169], v[208:211], v[116:119]
	v_mfma_f32_16x16x32_bf16 v[112:115], v[192:195], v[208:211], v[112:115]
	v_mfma_f32_16x16x32_bf16 v[88:91], v[166:169], v[216:219], v[88:91]
	v_mfma_f32_16x16x32_bf16 v[84:87], v[192:195], v[216:219], v[84:87]
	v_mfma_f32_16x16x32_bf16 v[80:83], v[166:169], v[224:227], v[80:83]
	v_mfma_f32_16x16x32_bf16 v[76:79], v[192:195], v[224:227], v[76:79]
	v_mfma_f32_16x16x32_bf16 v[124:127], v[176:179], v[204:207], v[124:127]
	v_mfma_f32_16x16x32_bf16 v[120:123], v[196:199], v[204:207], v[120:123]
	v_mfma_f32_16x16x32_bf16 v[116:119], v[176:179], v[212:215], v[116:119]
	v_mfma_f32_16x16x32_bf16 v[112:115], v[196:199], v[212:215], v[112:115]
	v_mfma_f32_16x16x32_bf16 v[88:91], v[176:179], v[220:223], v[88:91]
	v_mfma_f32_16x16x32_bf16 v[84:87], v[196:199], v[220:223], v[84:87]
	v_mfma_f32_16x16x32_bf16 v[80:83], v[176:179], v[228:231], v[80:83]
	v_mfma_f32_16x16x32_bf16 v[76:79], v[196:199], v[228:231], v[76:79]
	s_barrier
	s_add_i32 s50, s50, s0
	v_lshl_add_u64 v[170:171], s[40:41], 0, v[144:145]
	s_mov_b32 m0, s50
	ds_read_b128 v[200:203], v174 offset:16384
	ds_read_b128 v[204:207], v174 offset:17408
	ds_read_b128 v[208:211], v174 offset:18432
	ds_read_b128 v[212:215], v174 offset:19456
	ds_read_b128 v[216:219], v174 offset:20480
	ds_read_b128 v[220:223], v174 offset:21504
	ds_read_b128 v[224:227], v174 offset:22528
	ds_read_b128 v[228:231], v174 offset:23552
	global_load_lds_dwordx4 v[170:171], off
	s_add_i32 m0, s50, 0x2000
	s_add_u32 s50, s40, 0x100000
	v_lshl_add_u64 v[180:181], s[40:41], 0, v[160:161]
	s_addc_u32 s51, s41, 0
	s_add_i32 s52, s52, s0
	global_load_lds_dwordx4 v[180:181], off
	v_lshl_add_u64 v[232:233], s[50:51], 0, v[144:145]
	s_mov_b32 m0, s52
	v_lshl_add_u64 v[234:235], s[42:43], 0, v[160:161]
	global_load_lds_dwordx4 v[232:233], off
	v_lshl_add_u64 v[232:233], s[50:51], 0, v[160:161]
	s_add_i32 m0, s52, 0x2000
	s_nop 0
	global_load_lds_dwordx4 v[232:233], off
	v_lshl_add_u64 v[232:233], s[42:43], 0, v[144:145]
	s_mov_b32 m0, s1
	s_nop 0
	global_load_lds_dwordx4 v[232:233], off
	s_mov_b32 m0, s2
	s_nop 0
	global_load_lds_dwordx4 v[234:235], off
	s_waitcnt vmcnt(8)
	s_waitcnt lgkmcnt(0)
	s_barrier
; #define PG8_STAGE(bufoff, gbase, voff) do { _Pragma("unroll") for (int _i = 0; _i < 2; ++_i) \
;         __builtin_amdgcn_global_load_lds((const unsigned*)((const char*)(gbase) + (voff)[_i]), (LAS unsigned*)(lds + (bufoff) + ldsw + _i * 8192), 16, 0, 0); } while (0)
; #define PG8_LDA(dst, b, h) do { _Pragma("unroll") for (int m = 0; m < 4; ++m) _Pragma("unroll") for (int k = 0; k < 2; ++k) dst[m][k] = *(const LAS bf16x8*)(lds + PG8_SA(b, h) + aoff + m * 2048 + k * 1024); } while (0)
; #define PG8_LDB(dst, b, h) do { _Pragma("unroll") for (int n = 0; n < 2; ++n) _Pragma("unroll") for (int k = 0; k < 2; ++k) dst[n][k] = *(const LAS bf16x8*)(lds + PG8_SB(b, h) + boff + n * 2048 + k * 1024); } while (0)
; #define PG8_MMA(ai, bj, At, Bt) do { __builtin_amdgcn_s_setprio(1); _Pragma("unroll") for (int m = 0; m < 4; ++m) _Pragma("unroll") for (int n = 0; n < 2; ++n) _Pragma("unroll") for (int k = 0; k < 2; ++k) \
;         acc[ai][bj][m][n] = __builtin_amdgcn_mfma_f32_16x16x32_bf16(Bt[n][k], At[m][k], acc[ai][bj][m][n], 0, 0, 0); __builtin_amdgcn_s_setprio(0); } while (0)
; #define PG8_WAIT_V(n) asm volatile("s_waitcnt vmcnt(" #n ")" ::: "memory")
; #define PG8_WAIT_L(n) asm volatile("s_waitcnt lgkmcnt(" #n ")" ::: "memory")
; #define PG8_BAR __builtin_amdgcn_s_barrier()
; #define PG8_SCHED __builtin_amdgcn_sched_barrier(0)
; template <class Epi, class Map>
; __device__ __forceinline__ void gemm_phase(LAS unsigned char* lds, const Gemm g, const Sched<Map>& S, const Epi& E) {
;     ...
;             PG8_WAIT_V(8); PG8_WAIT_L(0); PG8_BAR; PG8_MMA(1, 0, At, B0); PG8_MMA(1, 1, At, B1); PG8_BAR; PG8_SCHED;
;             PG8_LDB(B0, 1, 0); PG8_LDB(B1, 1, 1); PG8_SCHED; PG8_LDA(At, 1, 0); PG8_STAGE(PG8_SA(0, 1), a2 + hstepA, voffA);
;             PG8_WAIT_V(8); PG8_WAIT_L(0); PG8_BAR; PG8_MMA(0, 0, At, B0); PG8_MMA(0, 1, At, B1); PG8_BAR; PG8_SCHED;
	s_waitcnt lgkmcnt(0)
	v_mfma_f32_16x16x32_bf16 v[60:63], v[64:67], v[200:203], v[60:63]
	v_mfma_f32_16x16x32_bf16 v[56:59], v[72:75], v[200:203], v[56:59]
	v_mfma_f32_16x16x32_bf16 v[52:55], v[64:67], v[208:211], v[52:55]
	v_mfma_f32_16x16x32_bf16 v[48:51], v[72:75], v[208:211], v[48:51]
	v_mfma_f32_16x16x32_bf16 v[28:31], v[64:67], v[216:219], v[28:31]
	v_mfma_f32_16x16x32_bf16 v[24:27], v[72:75], v[216:219], v[24:27]
	v_mfma_f32_16x16x32_bf16 v[20:23], v[64:67], v[224:227], v[20:23]
	v_mfma_f32_16x16x32_bf16 v[8:11], v[72:75], v[224:227], v[8:11]
	v_mfma_f32_16x16x32_bf16 v[60:63], v[68:71], v[204:207], v[60:63]
	v_mfma_f32_16x16x32_bf16 v[56:59], v[108:111], v[204:207], v[56:59]
	v_mfma_f32_16x16x32_bf16 v[52:55], v[68:71], v[212:215], v[52:55]
	v_mfma_f32_16x16x32_bf16 v[48:51], v[108:111], v[212:215], v[48:51]
	v_mfma_f32_16x16x32_bf16 v[28:31], v[68:71], v[220:223], v[28:31]
	v_mfma_f32_16x16x32_bf16 v[24:27], v[108:111], v[220:223], v[24:27]
	v_mfma_f32_16x16x32_bf16 v[20:23], v[68:71], v[228:231], v[20:23]
	v_mfma_f32_16x16x32_bf16 v[8:11], v[108:111], v[228:231], v[8:11]
	v_mfma_f32_16x16x32_bf16 v[44:47], v[166:169], v[200:203], v[44:47]
	v_mfma_f32_16x16x32_bf16 v[40:43], v[192:195], v[200:203], v[40:43]
	v_mfma_f32_16x16x32_bf16 v[36:39], v[166:169], v[208:211], v[36:39]
	v_mfma_f32_16x16x32_bf16 v[32:35], v[192:195], v[208:211], v[32:35]
	v_mfma_f32_16x16x32_bf16 v[16:19], v[166:169], v[216:219], v[16:19]
	v_mfma_f32_16x16x32_bf16 v[12:15], v[192:195], v[216:219], v[12:15]
	v_mfma_f32_16x16x32_bf16 v[4:7], v[166:169], v[224:227], v[4:7]
	v_mfma_f32_16x16x32_bf16 v[0:3], v[192:195], v[224:227], v[0:3]
	v_mfma_f32_16x16x32_bf16 v[44:47], v[176:179], v[204:207], v[44:47]
	v_mfma_f32_16x16x32_bf16 v[40:43], v[196:199], v[204:207], v[40:43]
	v_mfma_f32_16x16x32_bf16 v[36:39], v[176:179], v[212:215], v[36:39]
	v_mfma_f32_16x16x32_bf16 v[32:35], v[196:199], v[212:215], v[32:35]
	v_mfma_f32_16x16x32_bf16 v[16:19], v[176:179], v[220:223], v[16:19]
	v_mfma_f32_16x16x32_bf16 v[12:15], v[196:199], v[220:223], v[12:15]
	v_mfma_f32_16x16x32_bf16 v[4:7], v[176:179], v[228:231], v[4:7]
	v_mfma_f32_16x16x32_bf16 v[0:3], v[196:199], v[228:231], v[0:3]
	s_barrier
	s_add_i32 s50, 0, 0x18000
	s_add_i32 s51, 0, 0x1c000
	v_add_u32_e32 v108, s50, v173
	v_add_u32_e32 v175, s51, v173
	ds_read_b128 v[64:67], v108
	ds_read_b128 v[68:71], v108 offset:1024
	ds_read_b128 v[72:75], v108 offset:2048
	ds_read_b128 v[108:111], v108 offset:3072
	ds_read_b128 v[166:169], v175
	ds_read_b128 v[176:179], v175 offset:1024
	ds_read_b128 v[192:195], v175 offset:2048
	ds_read_b128 v[196:199], v175 offset:3072
	s_add_u32 s42, s42, 0x100000
	s_addc_u32 s43, s43, 0
	s_mov_b32 m0, s3
	v_lshl_add_u64 v[236:237], s[42:43], 0, v[144:145]
	ds_read_b128 v[200:203], v174 offset:32768
	ds_read_b128 v[204:207], v174 offset:33792
	ds_read_b128 v[208:211], v174 offset:34816
	ds_read_b128 v[212:215], v174 offset:35840
	ds_read_b128 v[216:219], v174 offset:36864
	ds_read_b128 v[220:223], v174 offset:37888
	ds_read_b128 v[224:227], v174 offset:38912
	ds_read_b128 v[228:231], v174 offset:39936
	global_load_lds_dwordx4 v[236:237], off
	v_lshl_add_u64 v[236:237], s[42:43], 0, v[160:161]
	s_mov_b32 m0, s4
	s_nop 0
	global_load_lds_dwordx4 v[236:237], off
	s_waitcnt vmcnt(8)
	s_waitcnt lgkmcnt(0)
	s_barrier
	s_waitcnt lgkmcnt(0)
	v_mfma_f32_16x16x32_bf16 v[140:143], v[64:67], v[200:203], v[140:143]
	v_mfma_f32_16x16x32_bf16 v[136:139], v[72:75], v[200:203], v[136:139]
	v_mfma_f32_16x16x32_bf16 v[132:135], v[64:67], v[208:211], v[132:135]
	v_mfma_f32_16x16x32_bf16 v[128:131], v[72:75], v[208:211], v[128:131]
	v_mfma_f32_16x16x32_bf16 v[104:107], v[64:67], v[216:219], v[104:107]
	v_mfma_f32_16x16x32_bf16 v[100:103], v[72:75], v[216:219], v[100:103]
	v_mfma_f32_16x16x32_bf16 v[96:99], v[64:67], v[224:227], v[96:99]
	v_mfma_f32_16x16x32_bf16 v[92:95], v[72:75], v[224:227], v[92:95]
	v_mfma_f32_16x16x32_bf16 v[140:143], v[68:71], v[204:207], v[140:143]
	v_mfma_f32_16x16x32_bf16 v[136:139], v[108:111], v[204:207], v[136:139]
	v_mfma_f32_16x16x32_bf16 v[132:135], v[68:71], v[212:215], v[132:135]
	v_mfma_f32_16x16x32_bf16 v[128:131], v[108:111], v[212:215], v[128:131]
	v_mfma_f32_16x16x32_bf16 v[104:107], v[68:71], v[220:223], v[104:107]
	v_mfma_f32_16x16x32_bf16 v[100:103], v[108:111], v[220:223], v[100:103]
	v_mfma_f32_16x16x32_bf16 v[96:99], v[68:71], v[228:231], v[96:99]
	v_mfma_f32_16x16x32_bf16 v[92:95], v[108:111], v[228:231], v[92:95]
	v_mfma_f32_16x16x32_bf16 v[124:127], v[166:169], v[200:203], v[124:127]
	v_mfma_f32_16x16x32_bf16 v[120:123], v[192:195], v[200:203], v[120:123]
	v_mfma_f32_16x16x32_bf16 v[116:119], v[166:169], v[208:211], v[116:119]
	v_mfma_f32_16x16x32_bf16 v[112:115], v[192:195], v[208:211], v[112:115]
	v_mfma_f32_16x16x32_bf16 v[88:91], v[166:169], v[216:219], v[88:91]
	v_mfma_f32_16x16x32_bf16 v[84:87], v[192:195], v[216:219], v[84:87]
	v_mfma_f32_16x16x32_bf16 v[80:83], v[166:169], v[224:227], v[80:83]
	v_mfma_f32_16x16x32_bf16 v[76:79], v[192:195], v[224:227], v[76:79]
	v_mfma_f32_16x16x32_bf16 v[124:127], v[176:179], v[204:207], v[124:127]
	v_mfma_f32_16x16x32_bf16 v[120:123], v[196:199], v[204:207], v[120:123]
	v_mfma_f32_16x16x32_bf16 v[116:119], v[176:179], v[212:215], v[116:119]
	v_mfma_f32_16x16x32_bf16 v[112:115], v[196:199], v[212:215], v[112:115]
	v_mfma_f32_16x16x32_bf16 v[88:91], v[176:179], v[220:223], v[88:91]
	v_mfma_f32_16x16x32_bf16 v[84:87], v[196:199], v[220:223], v[84:87]
	v_mfma_f32_16x16x32_bf16 v[80:83], v[176:179], v[228:231], v[80:83]
	v_mfma_f32_16x16x32_bf16 v[76:79], v[196:199], v[228:231], v[76:79]
	s_barrier
; #define PG8_STAGE(bufoff, gbase, voff) do { _Pragma("unroll") for (int _i = 0; _i < 2; ++_i) \
;         __builtin_amdgcn_global_load_lds((const unsigned*)((const char*)(gbase) + (voff)[_i]), (LAS unsigned*)(lds + (bufoff) + ldsw + _i * 8192), 16, 0, 0); } while (0)
; #define PG8_LDA(dst, b, h) do { _Pragma("unroll") for (int m = 0; m < 4; ++m) _Pragma("unroll") for (int k = 0; k < 2; ++k) dst[m][k] = *(const LAS bf16x8*)(lds + PG8_SA(b, h) + aoff + m * 2048 + k * 1024); } while (0)
; #define PG8_MMA(ai, bj, At, Bt) do { __builtin_amdgcn_s_setprio(1); _Pragma("unroll") for (int m = 0; m < 4; ++m) _Pragma("unroll") for (int n = 0; n < 2; ++n) _Pragma("unroll") for (int k = 0; k < 2; ++k) \
;         acc[ai][bj][m][n] = __builtin_amdgcn_mfma_f32_16x16x32_bf16(Bt[n][k], At[m][k], acc[ai][bj][m][n], 0, 0, 0); __builtin_amdgcn_s_setprio(0); } while (0)
; #define PG8_WAIT_V(n) asm volatile("s_waitcnt vmcnt(" #n ")" ::: "memory")
; #define PG8_WAIT_L(n) asm volatile("s_waitcnt lgkmcnt(" #n ")" ::: "memory")
; #define PG8_BAR __builtin_amdgcn_s_barrier()
; #define PG8_SCHED __builtin_amdgcn_sched_barrier(0)
; template <class Epi, class Map>
; __device__ __forceinline__ void gemm_phase(LAS unsigned char* lds, const Gemm g, const Sched<Map>& S, const Epi& E) {
;     ...
;             PG8_LDA(At, 1, 1); PG8_STAGE(PG8_SB(1, 0), b3, voffB); PG8_STAGE(PG8_SB(1, 1), b3 + hstepB, voffB); PG8_STAGE(PG8_SA(1, 0), a3, voffA);
;             PG8_WAIT_V(8); PG8_WAIT_L(0); PG8_BAR; PG8_MMA(1, 0, At, B0); PG8_MMA(1, 1, At, B1); PG8_BAR; PG8_SCHED;
;         }
;         if (wr == 0) PG8_BAR;
;         E(acc, cur, wr, wc, fr, fq);
;         if (!has_next) break;
	s_add_i32 s42, s50, s0
	v_lshl_add_u64 v[170:171], v[170:171], 0, s[82:83]
	s_mov_b32 m0, s42
	ds_read_b128 v[200:203], v174 offset:49152
	ds_read_b128 v[204:207], v174 offset:50176
	ds_read_b128 v[208:211], v174 offset:51200
	ds_read_b128 v[212:215], v174 offset:52224
	ds_read_b128 v[216:219], v174 offset:53248
	ds_read_b128 v[220:223], v174 offset:54272
	ds_read_b128 v[224:227], v174 offset:55296
	ds_read_b128 v[228:231], v174 offset:56320
	global_load_lds_dwordx4 v[170:171], off
	s_add_i32 m0, s42, 0x2000
	s_add_u32 s40, s40, 0x100080
	v_lshl_add_u64 v[170:171], v[180:181], 0, s[82:83]
	s_addc_u32 s41, s41, 0
	s_add_i32 s42, s51, s0
	global_load_lds_dwordx4 v[170:171], off
	v_lshl_add_u64 v[170:171], s[40:41], 0, v[144:145]
	s_mov_b32 m0, s42
	s_nop 0
	global_load_lds_dwordx4 v[170:171], off
	v_lshl_add_u64 v[170:171], s[40:41], 0, v[160:161]
	s_add_i32 m0, s42, 0x2000
	s_nop 0
	global_load_lds_dwordx4 v[170:171], off
	v_lshl_add_u64 v[170:171], v[232:233], 0, s[82:83]
	s_mov_b32 m0, s7
	s_nop 0
	global_load_lds_dwordx4 v[170:171], off
	v_lshl_add_u64 v[170:171], v[234:235], 0, s[82:83]
	s_mov_b32 m0, s8
	s_nop 0
	global_load_lds_dwordx4 v[170:171], off
	s_waitcnt vmcnt(8)
	s_waitcnt lgkmcnt(0)
	s_barrier
	s_waitcnt lgkmcnt(0)
	v_mfma_f32_16x16x32_bf16 v[60:63], v[64:67], v[200:203], v[60:63]
	v_mfma_f32_16x16x32_bf16 v[56:59], v[72:75], v[200:203], v[56:59]
	v_mfma_f32_16x16x32_bf16 v[52:55], v[64:67], v[208:211], v[52:55]
	v_mfma_f32_16x16x32_bf16 v[48:51], v[72:75], v[208:211], v[48:51]
	v_mfma_f32_16x16x32_bf16 v[28:31], v[64:67], v[216:219], v[28:31]
	v_mfma_f32_16x16x32_bf16 v[24:27], v[72:75], v[216:219], v[24:27]
	v_mfma_f32_16x16x32_bf16 v[20:23], v[64:67], v[224:227], v[20:23]
	v_mfma_f32_16x16x32_bf16 v[8:11], v[72:75], v[224:227], v[8:11]
	v_mfma_f32_16x16x32_bf16 v[60:63], v[68:71], v[204:207], v[60:63]
	v_mfma_f32_16x16x32_bf16 v[56:59], v[108:111], v[204:207], v[56:59]
	v_mfma_f32_16x16x32_bf16 v[52:55], v[68:71], v[212:215], v[52:55]
	v_mfma_f32_16x16x32_bf16 v[48:51], v[108:111], v[212:215], v[48:51]
	v_mfma_f32_16x16x32_bf16 v[28:31], v[68:71], v[220:223], v[28:31]
	v_mfma_f32_16x16x32_bf16 v[24:27], v[108:111], v[220:223], v[24:27]
	v_mfma_f32_16x16x32_bf16 v[20:23], v[68:71], v[228:231], v[20:23]
	v_mfma_f32_16x16x32_bf16 v[8:11], v[108:111], v[228:231], v[8:11]
	v_mfma_f32_16x16x32_bf16 v[44:47], v[166:169], v[200:203], v[44:47]
	v_mfma_f32_16x16x32_bf16 v[40:43], v[192:195], v[200:203], v[40:43]
	v_mfma_f32_16x16x32_bf16 v[36:39], v[166:169], v[208:211], v[36:39]
	v_mfma_f32_16x16x32_bf16 v[32:35], v[192:195], v[208:211], v[32:35]
	v_mfma_f32_16x16x32_bf16 v[16:19], v[166:169], v[216:219], v[16:19]
	v_mfma_f32_16x16x32_bf16 v[12:15], v[192:195], v[216:219], v[12:15]
	v_mfma_f32_16x16x32_bf16 v[4:7], v[166:169], v[224:227], v[4:7]
	v_mfma_f32_16x16x32_bf16 v[0:3], v[192:195], v[224:227], v[0:3]
	v_mfma_f32_16x16x32_bf16 v[44:47], v[176:179], v[204:207], v[44:47]
	v_mfma_f32_16x16x32_bf16 v[40:43], v[196:199], v[204:207], v[40:43]
	v_mfma_f32_16x16x32_bf16 v[36:39], v[176:179], v[212:215], v[36:39]
	v_mfma_f32_16x16x32_bf16 v[32:35], v[196:199], v[212:215], v[32:35]
	v_mfma_f32_16x16x32_bf16 v[16:19], v[176:179], v[220:223], v[16:19]
	v_mfma_f32_16x16x32_bf16 v[12:15], v[196:199], v[220:223], v[12:15]
	v_mfma_f32_16x16x32_bf16 v[4:7], v[176:179], v[228:231], v[4:7]
	v_mfma_f32_16x16x32_bf16 v[0:3], v[196:199], v[228:231], v[0:3]
	s_barrier
	s_add_i32 s49, s49, 2
	s_add_u32 s36, s36, 0x100
	s_addc_u32 s37, s37, 0
	s_add_u32 s47, s47, 0x100
	s_addc_u32 s48, s48, 0
	s_cmp_gt_u32 s49, 61
	s_cbranch_scc0 .LBB0_952
	s_and_b64 vcc, exec, s[28:29]
	s_cbranch_vccz .LBB0_955
	s_barrier

; #define PG8_STAGE(bufoff, gbase, voff) do { _Pragma("unroll") for (int _i = 0; _i < 2; ++_i) \
;         __builtin_amdgcn_global_load_lds((const unsigned*)((const char*)(gbase) + (voff)[_i]), (LAS unsigned*)(lds + (bufoff) + ldsw + _i * 8192), 16, 0, 0); } while (0)
; #define PG8_LDA(dst, b, h) do { _Pragma("unroll") for (int m = 0; m < 4; ++m) _Pragma("unroll") for (int k = 0; k < 2; ++k) dst[m][k] = *(const LAS bf16x8*)(lds + PG8_SA(b, h) + aoff + m * 2048 + k * 1024); } while (0)
; #define PG8_LDB(dst, b, h) do { _Pragma("unroll") for (int n = 0; n < 2; ++n) _Pragma("unroll") for (int k = 0; k < 2; ++k) dst[n][k] = *(const LAS bf16x8*)(lds + PG8_SB(b, h) + boff + n * 2048 + k * 1024); } while (0)
; #define PG8_MMA(ai, bj, At, Bt) do { __builtin_amdgcn_s_setprio(1); _Pragma("unroll") for (int m = 0; m < 4; ++m) _Pragma("unroll") for (int n = 0; n < 2; ++n) _Pragma("unroll") for (int k = 0; k < 2; ++k) \
;         acc[ai][bj][m][n] = __builtin_amdgcn_mfma_f32_16x16x32_bf16(Bt[n][k], At[m][k], acc[ai][bj][m][n], 0, 0, 0); __builtin_amdgcn_s_setprio(0); } while (0)
; #define PG8_WAIT_V(n) asm volatile("s_waitcnt vmcnt(" #n ")" ::: "memory")
; #define PG8_WAIT_L(n) asm volatile("s_waitcnt lgkmcnt(" #n ")" ::: "memory")
; #define PG8_BAR __builtin_amdgcn_s_barrier()
; #define PG8_SCHED __builtin_amdgcn_sched_barrier(0)
; template <class Epi, class Map>
; __device__ __forceinline__ void gemm_phase(LAS unsigned char* lds, const Gemm g, const Sched<Map>& S, const Epi& E) {
;     ...
;         for (int t = 0; t < nt; t += 2) {
;             const bool last = (t == nt - 2);
;             const char* a1 = cA + (size_t)(t + 1) * kstep;
;             const char* a2 = last ? nA : cA + (size_t)(t + 2) * kstep; const char* b2 = last ? nB : cB + (size_t)(t + 2) * kstep;
;             const char* a3 = a2 + kstep; const char* b3 = b2 + kstep;
;             PG8_LDB(B0, 0, 0); PG8_LDB(B1, 0, 1); PG8_SCHED; PG8_LDA(At, 0, 0); PG8_STAGE(PG8_SA(1, 1), a1 + hstepA, voffA);
;             PG8_WAIT_V(8); PG8_WAIT_L(0); PG8_BAR; PG8_MMA(0, 0, At, B0); PG8_MMA(0, 1, At, B1); PG8_BAR; PG8_SCHED;
;             PG8_LDA(At, 0, 1); PG8_STAGE(PG8_SB(0, 0), b2, voffB); PG8_STAGE(PG8_SB(0, 1), b2 + hstepB, voffB); PG8_STAGE(PG8_SA(0, 0), a2, voffA);
.LBB0_1088:
	s_add_u32 s34, s30, 0xfff80080
	s_addc_u32 s35, s31, -1
	s_add_i32 s41, 0, 0x10000
	s_cmp_eq_u32 s40, 28
	s_cselect_b32 s37, s12, s35
	s_cselect_b32 s36, s13, s34
	v_add_u32_e32 v138, s41, v142
	s_cselect_b32 s35, s14, s33
	s_cselect_b32 s34, s15, s21
	s_add_i32 s46, 0, 0x14000
	ds_read_b128 v[160:163], v138
	ds_read_b128 v[164:167], v138 offset:1024
	ds_read_b128 v[168:171], v138 offset:2048
	ds_read_b128 v[172:175], v138 offset:3072
	v_add_u32_e32 v138, s46, v142
	ds_read_b128 v[176:179], v138
	ds_read_b128 v[192:195], v138 offset:1024
	ds_read_b128 v[196:199], v138 offset:2048
	ds_read_b128 v[200:203], v138 offset:3072
	v_lshl_add_u64 v[138:139], s[30:31], 0, v[134:135]
	s_add_i32 m0, s1, 0xc000
	ds_read_b128 v[204:207], v143
	ds_read_b128 v[208:211], v143 offset:1024
	ds_read_b128 v[212:215], v143 offset:2048
	ds_read_b128 v[216:219], v143 offset:3072
	ds_read_b128 v[220:223], v143 offset:4096
	ds_read_b128 v[224:227], v143 offset:5120
	ds_read_b128 v[228:231], v143 offset:6144
	ds_read_b128 v[232:235], v143 offset:7168
	global_load_lds_dwordx4 v[138:139], off
	v_lshl_add_u64 v[138:139], s[30:31], 0, v[136:137]
	s_add_i32 m0, s1, 0xe000
	s_nop 0
	global_load_lds_dwordx4 v[138:139], off
	s_waitcnt vmcnt(8)
	s_waitcnt lgkmcnt(0)
	s_barrier
	s_waitcnt lgkmcnt(0)
	v_mfma_f32_16x16x32_bf16 v[124:127], v[160:163], v[204:207], v[124:127]
	v_mfma_f32_16x16x32_bf16 v[120:123], v[168:171], v[204:207], v[120:123]
	v_mfma_f32_16x16x32_bf16 v[108:111], v[160:163], v[212:215], v[108:111]
	v_mfma_f32_16x16x32_bf16 v[104:107], v[168:171], v[212:215], v[104:107]
	v_mfma_f32_16x16x32_bf16 v[92:95], v[160:163], v[220:223], v[92:95]
	v_mfma_f32_16x16x32_bf16 v[88:91], v[168:171], v[220:223], v[88:91]
	v_mfma_f32_16x16x32_bf16 v[76:79], v[160:163], v[228:231], v[76:79]
	v_mfma_f32_16x16x32_bf16 v[72:75], v[168:171], v[228:231], v[72:75]
	v_mfma_f32_16x16x32_bf16 v[124:127], v[164:167], v[208:211], v[124:127]
	v_mfma_f32_16x16x32_bf16 v[120:123], v[172:175], v[208:211], v[120:123]
	v_mfma_f32_16x16x32_bf16 v[108:111], v[164:167], v[216:219], v[108:111]
	v_mfma_f32_16x16x32_bf16 v[104:107], v[172:175], v[216:219], v[104:107]
	v_mfma_f32_16x16x32_bf16 v[92:95], v[164:167], v[224:227], v[92:95]
	v_mfma_f32_16x16x32_bf16 v[88:91], v[172:175], v[224:227], v[88:91]
	v_mfma_f32_16x16x32_bf16 v[76:79], v[164:167], v[232:235], v[76:79]
	v_mfma_f32_16x16x32_bf16 v[72:75], v[172:175], v[232:235], v[72:75]
	v_mfma_f32_16x16x32_bf16 v[116:119], v[176:179], v[204:207], v[116:119]
	v_mfma_f32_16x16x32_bf16 v[112:115], v[196:199], v[204:207], v[112:115]
	v_mfma_f32_16x16x32_bf16 v[100:103], v[176:179], v[212:215], v[100:103]
	v_mfma_f32_16x16x32_bf16 v[96:99], v[196:199], v[212:215], v[96:99]
	v_mfma_f32_16x16x32_bf16 v[84:87], v[176:179], v[220:223], v[84:87]
	v_mfma_f32_16x16x32_bf16 v[80:83], v[196:199], v[220:223], v[80:83]
	v_mfma_f32_16x16x32_bf16 v[68:71], v[176:179], v[228:231], v[68:71]
	v_mfma_f32_16x16x32_bf16 v[64:67], v[196:199], v[228:231], v[64:67]
	v_mfma_f32_16x16x32_bf16 v[116:119], v[192:195], v[208:211], v[116:119]
	v_mfma_f32_16x16x32_bf16 v[112:115], v[200:203], v[208:211], v[112:115]
	v_mfma_f32_16x16x32_bf16 v[100:103], v[192:195], v[216:219], v[100:103]
	v_mfma_f32_16x16x32_bf16 v[96:99], v[200:203], v[216:219], v[96:99]
	v_mfma_f32_16x16x32_bf16 v[84:87], v[192:195], v[224:227], v[84:87]
	v_mfma_f32_16x16x32_bf16 v[80:83], v[200:203], v[224:227], v[80:83]
	v_mfma_f32_16x16x32_bf16 v[68:71], v[192:195], v[232:235], v[68:71]
	v_mfma_f32_16x16x32_bf16 v[64:67], v[200:203], v[232:235], v[64:67]
	s_barrier
	s_add_i32 s41, s41, s0
	v_lshl_add_u64 v[138:139], s[34:35], 0, v[144:145]
	s_mov_b32 m0, s41
	ds_read_b128 v[204:207], v143 offset:16384
	ds_read_b128 v[208:211], v143 offset:17408
	ds_read_b128 v[212:215], v143 offset:18432
	ds_read_b128 v[216:219], v143 offset:19456
	ds_read_b128 v[220:223], v143 offset:20480
	ds_read_b128 v[224:227], v143 offset:21504
	ds_read_b128 v[228:231], v143 offset:22528
	ds_read_b128 v[232:235], v143 offset:23552
	global_load_lds_dwordx4 v[138:139], off
	s_add_i32 m0, s41, 0x2000
	s_add_u32 s44, s34, 0x80000
	v_lshl_add_u64 v[180:181], s[34:35], 0, v[128:129]
	s_addc_u32 s45, s35, 0
	s_add_i32 s41, s46, s0
	global_load_lds_dwordx4 v[180:181], off
	v_lshl_add_u64 v[236:237], s[44:45], 0, v[144:145]
	s_mov_b32 m0, s41
	v_lshl_add_u64 v[238:239], s[36:37], 0, v[130:131]
	global_load_lds_dwordx4 v[236:237], off
	v_lshl_add_u64 v[236:237], s[44:45], 0, v[128:129]
	s_add_i32 m0, s41, 0x2000
	s_nop 0
	global_load_lds_dwordx4 v[236:237], off
	v_lshl_add_u64 v[236:237], s[36:37], 0, v[132:133]
	s_mov_b32 m0, s1
	s_nop 0
	global_load_lds_dwordx4 v[236:237], off
	s_mov_b32 m0, s2
	s_nop 0
	global_load_lds_dwordx4 v[238:239], off
	s_waitcnt vmcnt(8)
	s_waitcnt lgkmcnt(0)
	s_barrier
; #define PG8_STAGE(bufoff, gbase, voff) do { _Pragma("unroll") for (int _i = 0; _i < 2; ++_i) \
;         __builtin_amdgcn_global_load_lds((const unsigned*)((const char*)(gbase) + (voff)[_i]), (LAS unsigned*)(lds + (bufoff) + ldsw + _i * 8192), 16, 0, 0); } while (0)
; #define PG8_LDA(dst, b, h) do { _Pragma("unroll") for (int m = 0; m < 4; ++m) _Pragma("unroll") for (int k = 0; k < 2; ++k) dst[m][k] = *(const LAS bf16x8*)(lds + PG8_SA(b, h) + aoff + m * 2048 + k * 1024); } while (0)
; #define PG8_LDB(dst, b, h) do { _Pragma("unroll") for (int n = 0; n < 2; ++n) _Pragma("unroll") for (int k = 0; k < 2; ++k) dst[n][k] = *(const LAS bf16x8*)(lds + PG8_SB(b, h) + boff + n * 2048 + k * 1024); } while (0)
; #define PG8_MMA(ai, bj, At, Bt) do { __builtin_amdgcn_s_setprio(1); _Pragma("unroll") for (int m = 0; m < 4; ++m) _Pragma("unroll") for (int n = 0; n < 2; ++n) _Pragma("unroll") for (int k = 0; k < 2; ++k) \
;         acc[ai][bj][m][n] = __builtin_amdgcn_mfma_f32_16x16x32_bf16(Bt[n][k], At[m][k], acc[ai][bj][m][n], 0, 0, 0); __builtin_amdgcn_s_setprio(0); } while (0)
; #define PG8_WAIT_V(n) asm volatile("s_waitcnt vmcnt(" #n ")" ::: "memory")
; #define PG8_WAIT_L(n) asm volatile("s_waitcnt lgkmcnt(" #n ")" ::: "memory")
; #define PG8_BAR __builtin_amdgcn_s_barrier()
; #define PG8_SCHED __builtin_amdgcn_sched_barrier(0)
; template <class Epi, class Map>
; __device__ __forceinline__ void gemm_phase(LAS unsigned char* lds, const Gemm g, const Sched<Map>& S, const Epi& E) {
;     ...
;             PG8_WAIT_V(8); PG8_WAIT_L(0); PG8_BAR; PG8_MMA(1, 0, At, B0); PG8_MMA(1, 1, At, B1); PG8_BAR; PG8_SCHED;
;             PG8_LDB(B0, 1, 0); PG8_LDB(B1, 1, 1); PG8_SCHED; PG8_LDA(At, 1, 0); PG8_STAGE(PG8_SA(0, 1), a2 + hstepA, voffA);
;             PG8_WAIT_V(8); PG8_WAIT_L(0); PG8_BAR; PG8_MMA(0, 0, At, B0); PG8_MMA(0, 1, At, B1); PG8_BAR; PG8_SCHED;
	s_waitcnt lgkmcnt(0)
	v_mfma_f32_16x16x32_bf16 v[60:63], v[160:163], v[204:207], v[60:63]
	v_mfma_f32_16x16x32_bf16 v[56:59], v[168:171], v[204:207], v[56:59]
	v_mfma_f32_16x16x32_bf16 v[44:47], v[160:163], v[212:215], v[44:47]
	v_mfma_f32_16x16x32_bf16 v[40:43], v[168:171], v[212:215], v[40:43]
	v_mfma_f32_16x16x32_bf16 v[28:31], v[160:163], v[220:223], v[28:31]
	v_mfma_f32_16x16x32_bf16 v[24:27], v[168:171], v[220:223], v[24:27]
	v_mfma_f32_16x16x32_bf16 v[12:15], v[160:163], v[228:231], v[12:15]
	v_mfma_f32_16x16x32_bf16 v[8:11], v[168:171], v[228:231], v[8:11]
	v_mfma_f32_16x16x32_bf16 v[60:63], v[164:167], v[208:211], v[60:63]
	v_mfma_f32_16x16x32_bf16 v[56:59], v[172:175], v[208:211], v[56:59]
	v_mfma_f32_16x16x32_bf16 v[44:47], v[164:167], v[216:219], v[44:47]
	v_mfma_f32_16x16x32_bf16 v[40:43], v[172:175], v[216:219], v[40:43]
	v_mfma_f32_16x16x32_bf16 v[28:31], v[164:167], v[224:227], v[28:31]
	v_mfma_f32_16x16x32_bf16 v[24:27], v[172:175], v[224:227], v[24:27]
	v_mfma_f32_16x16x32_bf16 v[12:15], v[164:167], v[232:235], v[12:15]
	v_mfma_f32_16x16x32_bf16 v[8:11], v[172:175], v[232:235], v[8:11]
	v_mfma_f32_16x16x32_bf16 v[52:55], v[176:179], v[204:207], v[52:55]
	v_mfma_f32_16x16x32_bf16 v[48:51], v[196:199], v[204:207], v[48:51]
	v_mfma_f32_16x16x32_bf16 v[36:39], v[176:179], v[212:215], v[36:39]
	v_mfma_f32_16x16x32_bf16 v[32:35], v[196:199], v[212:215], v[32:35]
	v_mfma_f32_16x16x32_bf16 v[20:23], v[176:179], v[220:223], v[20:23]
	v_mfma_f32_16x16x32_bf16 v[16:19], v[196:199], v[220:223], v[16:19]
	v_mfma_f32_16x16x32_bf16 v[4:7], v[176:179], v[228:231], v[4:7]
	v_mfma_f32_16x16x32_bf16 v[0:3], v[196:199], v[228:231], v[0:3]
	v_mfma_f32_16x16x32_bf16 v[52:55], v[192:195], v[208:211], v[52:55]
	v_mfma_f32_16x16x32_bf16 v[48:51], v[200:203], v[208:211], v[48:51]
	v_mfma_f32_16x16x32_bf16 v[36:39], v[192:195], v[216:219], v[36:39]
	v_mfma_f32_16x16x32_bf16 v[32:35], v[200:203], v[216:219], v[32:35]
	v_mfma_f32_16x16x32_bf16 v[20:23], v[192:195], v[224:227], v[20:23]
	v_mfma_f32_16x16x32_bf16 v[16:19], v[200:203], v[224:227], v[16:19]
	v_mfma_f32_16x16x32_bf16 v[4:7], v[192:195], v[232:235], v[4:7]
	v_mfma_f32_16x16x32_bf16 v[0:3], v[200:203], v[232:235], v[0:3]
	s_barrier
	s_add_i32 s41, 0, 0x18000
	v_add_u32_e32 v159, s41, v142
	s_add_i32 s44, 0, 0x1c000
	ds_read_b128 v[160:163], v159
	ds_read_b128 v[164:167], v159 offset:1024
	ds_read_b128 v[168:171], v159 offset:2048
	ds_read_b128 v[172:175], v159 offset:3072
	v_add_u32_e32 v159, s44, v142
	ds_read_b128 v[176:179], v159
	ds_read_b128 v[192:195], v159 offset:1024
	ds_read_b128 v[196:199], v159 offset:2048
	ds_read_b128 v[200:203], v159 offset:3072
	s_add_u32 s36, s36, 0x80000
	s_addc_u32 s37, s37, 0
	s_mov_b32 m0, s3
	v_lshl_add_u64 v[240:241], s[36:37], 0, v[132:133]
	ds_read_b128 v[204:207], v143 offset:32768
	ds_read_b128 v[208:211], v143 offset:33792
	ds_read_b128 v[212:215], v143 offset:34816
	ds_read_b128 v[216:219], v143 offset:35840
	ds_read_b128 v[220:223], v143 offset:36864
	ds_read_b128 v[224:227], v143 offset:37888
	ds_read_b128 v[228:231], v143 offset:38912
	ds_read_b128 v[232:235], v143 offset:39936
	global_load_lds_dwordx4 v[240:241], off
	v_lshl_add_u64 v[240:241], s[36:37], 0, v[130:131]
	s_mov_b32 m0, s4
	s_nop 0
	global_load_lds_dwordx4 v[240:241], off
	s_waitcnt vmcnt(8)
	s_waitcnt lgkmcnt(0)
	s_barrier
	s_waitcnt lgkmcnt(0)
	v_mfma_f32_16x16x32_bf16 v[124:127], v[160:163], v[204:207], v[124:127]
	v_mfma_f32_16x16x32_bf16 v[120:123], v[168:171], v[204:207], v[120:123]
	v_mfma_f32_16x16x32_bf16 v[108:111], v[160:163], v[212:215], v[108:111]
	v_mfma_f32_16x16x32_bf16 v[104:107], v[168:171], v[212:215], v[104:107]
	v_mfma_f32_16x16x32_bf16 v[92:95], v[160:163], v[220:223], v[92:95]
	v_mfma_f32_16x16x32_bf16 v[88:91], v[168:171], v[220:223], v[88:91]
	v_mfma_f32_16x16x32_bf16 v[76:79], v[160:163], v[228:231], v[76:79]
	v_mfma_f32_16x16x32_bf16 v[72:75], v[168:171], v[228:231], v[72:75]
	v_mfma_f32_16x16x32_bf16 v[124:127], v[164:167], v[208:211], v[124:127]
	v_mfma_f32_16x16x32_bf16 v[120:123], v[172:175], v[208:211], v[120:123]
	v_mfma_f32_16x16x32_bf16 v[108:111], v[164:167], v[216:219], v[108:111]
	v_mfma_f32_16x16x32_bf16 v[104:107], v[172:175], v[216:219], v[104:107]
	v_mfma_f32_16x16x32_bf16 v[92:95], v[164:167], v[224:227], v[92:95]
	v_mfma_f32_16x16x32_bf16 v[88:91], v[172:175], v[224:227], v[88:91]
	v_mfma_f32_16x16x32_bf16 v[76:79], v[164:167], v[232:235], v[76:79]
	v_mfma_f32_16x16x32_bf16 v[72:75], v[172:175], v[232:235], v[72:75]
	v_mfma_f32_16x16x32_bf16 v[116:119], v[176:179], v[204:207], v[116:119]
	v_mfma_f32_16x16x32_bf16 v[112:115], v[196:199], v[204:207], v[112:115]
	v_mfma_f32_16x16x32_bf16 v[100:103], v[176:179], v[212:215], v[100:103]
	v_mfma_f32_16x16x32_bf16 v[96:99], v[196:199], v[212:215], v[96:99]
	v_mfma_f32_16x16x32_bf16 v[84:87], v[176:179], v[220:223], v[84:87]
	v_mfma_f32_16x16x32_bf16 v[80:83], v[196:199], v[220:223], v[80:83]
	v_mfma_f32_16x16x32_bf16 v[68:71], v[176:179], v[228:231], v[68:71]
	v_mfma_f32_16x16x32_bf16 v[64:67], v[196:199], v[228:231], v[64:67]
	v_mfma_f32_16x16x32_bf16 v[116:119], v[192:195], v[208:211], v[116:119]
	v_mfma_f32_16x16x32_bf16 v[112:115], v[200:203], v[208:211], v[112:115]
	v_mfma_f32_16x16x32_bf16 v[100:103], v[192:195], v[216:219], v[100:103]
	v_mfma_f32_16x16x32_bf16 v[96:99], v[200:203], v[216:219], v[96:99]
	v_mfma_f32_16x16x32_bf16 v[84:87], v[192:195], v[224:227], v[84:87]
	v_mfma_f32_16x16x32_bf16 v[80:83], v[200:203], v[224:227], v[80:83]
	v_mfma_f32_16x16x32_bf16 v[68:71], v[192:195], v[232:235], v[68:71]
	v_mfma_f32_16x16x32_bf16 v[64:67], v[200:203], v[232:235], v[64:67]
	s_barrier
; #define PG8_STAGE(bufoff, gbase, voff) do { _Pragma("unroll") for (int _i = 0; _i < 2; ++_i) \
;         __builtin_amdgcn_global_load_lds((const unsigned*)((const char*)(gbase) + (voff)[_i]), (LAS unsigned*)(lds + (bufoff) + ldsw + _i * 8192), 16, 0, 0); } while (0)
; #define PG8_LDA(dst, b, h) do { _Pragma("unroll") for (int m = 0; m < 4; ++m) _Pragma("unroll") for (int k = 0; k < 2; ++k) dst[m][k] = *(const LAS bf16x8*)(lds + PG8_SA(b, h) + aoff + m * 2048 + k * 1024); } while (0)
; #define PG8_MMA(ai, bj, At, Bt) do { __builtin_amdgcn_s_setprio(1); _Pragma("unroll") for (int m = 0; m < 4; ++m) _Pragma("unroll") for (int n = 0; n < 2; ++n) _Pragma("unroll") for (int k = 0; k < 2; ++k) \
;         acc[ai][bj][m][n] = __builtin_amdgcn_mfma_f32_16x16x32_bf16(Bt[n][k], At[m][k], acc[ai][bj][m][n], 0, 0, 0); __builtin_amdgcn_s_setprio(0); } while (0)
; #define PG8_WAIT_V(n) asm volatile("s_waitcnt vmcnt(" #n ")" ::: "memory")
; #define PG8_WAIT_L(n) asm volatile("s_waitcnt lgkmcnt(" #n ")" ::: "memory")
; #define PG8_BAR __builtin_amdgcn_s_barrier()
; #define PG8_SCHED __builtin_amdgcn_sched_barrier(0)
; template <class Epi, class Map>
; __device__ __forceinline__ void gemm_phase(LAS unsigned char* lds, const Gemm g, const Sched<Map>& S, const Epi& E) {
;     ...
;             PG8_LDA(At, 1, 1); PG8_STAGE(PG8_SB(1, 0), b3, voffB); PG8_STAGE(PG8_SB(1, 1), b3 + hstepB, voffB); PG8_STAGE(PG8_SA(1, 0), a3, voffA);
;             PG8_WAIT_V(8); PG8_WAIT_L(0); PG8_BAR; PG8_MMA(1, 0, At, B0); PG8_MMA(1, 1, At, B1); PG8_BAR; PG8_SCHED;
;         }
;         if (wr == 0) PG8_BAR;
	s_add_i32 s36, s41, s0
	v_lshl_add_u64 v[138:139], v[138:139], 0, s[82:83]
	s_mov_b32 m0, s36
	ds_read_b128 v[204:207], v143 offset:49152
	ds_read_b128 v[208:211], v143 offset:50176
	ds_read_b128 v[212:215], v143 offset:51200
	ds_read_b128 v[216:219], v143 offset:52224
	ds_read_b128 v[220:223], v143 offset:53248
	ds_read_b128 v[224:227], v143 offset:54272
	ds_read_b128 v[228:231], v143 offset:55296
	ds_read_b128 v[232:235], v143 offset:56320
	global_load_lds_dwordx4 v[138:139], off
	s_add_i32 m0, s36, 0x2000
	s_add_u32 s34, s34, 0x80080
	v_lshl_add_u64 v[138:139], v[180:181], 0, s[82:83]
	s_addc_u32 s35, s35, 0
	s_add_i32 s36, s44, s0
	global_load_lds_dwordx4 v[138:139], off
	v_lshl_add_u64 v[138:139], s[34:35], 0, v[144:145]
	s_mov_b32 m0, s36
	s_nop 0
	global_load_lds_dwordx4 v[138:139], off
	v_lshl_add_u64 v[138:139], s[34:35], 0, v[128:129]
	s_add_i32 m0, s36, 0x2000
	s_nop 0
	global_load_lds_dwordx4 v[138:139], off
	v_lshl_add_u64 v[138:139], v[236:237], 0, s[82:83]
	s_mov_b32 m0, s6
	s_nop 0
	global_load_lds_dwordx4 v[138:139], off
	v_lshl_add_u64 v[138:139], v[238:239], 0, s[82:83]
	s_mov_b32 m0, s7
	s_nop 0
	global_load_lds_dwordx4 v[138:139], off
	s_waitcnt vmcnt(8)
	s_waitcnt lgkmcnt(0)
	s_barrier
	s_waitcnt lgkmcnt(0)
	v_mfma_f32_16x16x32_bf16 v[60:63], v[160:163], v[204:207], v[60:63]
	v_mfma_f32_16x16x32_bf16 v[56:59], v[168:171], v[204:207], v[56:59]
	v_mfma_f32_16x16x32_bf16 v[44:47], v[160:163], v[212:215], v[44:47]
	v_mfma_f32_16x16x32_bf16 v[40:43], v[168:171], v[212:215], v[40:43]
	v_mfma_f32_16x16x32_bf16 v[28:31], v[160:163], v[220:223], v[28:31]
	v_mfma_f32_16x16x32_bf16 v[24:27], v[168:171], v[220:223], v[24:27]
	v_mfma_f32_16x16x32_bf16 v[12:15], v[160:163], v[228:231], v[12:15]
	v_mfma_f32_16x16x32_bf16 v[8:11], v[168:171], v[228:231], v[8:11]
	v_mfma_f32_16x16x32_bf16 v[60:63], v[164:167], v[208:211], v[60:63]
	v_mfma_f32_16x16x32_bf16 v[56:59], v[172:175], v[208:211], v[56:59]
	v_mfma_f32_16x16x32_bf16 v[44:47], v[164:167], v[216:219], v[44:47]
	v_mfma_f32_16x16x32_bf16 v[40:43], v[172:175], v[216:219], v[40:43]
	v_mfma_f32_16x16x32_bf16 v[28:31], v[164:167], v[224:227], v[28:31]
	v_mfma_f32_16x16x32_bf16 v[24:27], v[172:175], v[224:227], v[24:27]
	v_mfma_f32_16x16x32_bf16 v[12:15], v[164:167], v[232:235], v[12:15]
	v_mfma_f32_16x16x32_bf16 v[8:11], v[172:175], v[232:235], v[8:11]
	v_mfma_f32_16x16x32_bf16 v[52:55], v[176:179], v[204:207], v[52:55]
	v_mfma_f32_16x16x32_bf16 v[48:51], v[196:199], v[204:207], v[48:51]
	v_mfma_f32_16x16x32_bf16 v[36:39], v[176:179], v[212:215], v[36:39]
	v_mfma_f32_16x16x32_bf16 v[32:35], v[196:199], v[212:215], v[32:35]
	v_mfma_f32_16x16x32_bf16 v[20:23], v[176:179], v[220:223], v[20:23]
	v_mfma_f32_16x16x32_bf16 v[16:19], v[196:199], v[220:223], v[16:19]
	v_mfma_f32_16x16x32_bf16 v[4:7], v[176:179], v[228:231], v[4:7]
	v_mfma_f32_16x16x32_bf16 v[0:3], v[196:199], v[228:231], v[0:3]
	v_mfma_f32_16x16x32_bf16 v[52:55], v[192:195], v[208:211], v[52:55]
	v_mfma_f32_16x16x32_bf16 v[48:51], v[200:203], v[208:211], v[48:51]
	v_mfma_f32_16x16x32_bf16 v[36:39], v[192:195], v[216:219], v[36:39]
	v_mfma_f32_16x16x32_bf16 v[32:35], v[200:203], v[216:219], v[32:35]
	v_mfma_f32_16x16x32_bf16 v[20:23], v[192:195], v[224:227], v[20:23]
	v_mfma_f32_16x16x32_bf16 v[16:19], v[200:203], v[224:227], v[16:19]
	v_mfma_f32_16x16x32_bf16 v[4:7], v[192:195], v[232:235], v[4:7]
	v_mfma_f32_16x16x32_bf16 v[0:3], v[200:203], v[232:235], v[0:3]
	s_barrier
	s_add_i32 s40, s40, 2
	s_add_u32 s30, s30, 0x100
	s_addc_u32 s31, s31, 0
	s_add_u32 s21, s21, 0x100
	s_addc_u32 s33, s33, 0
	s_cmp_gt_u32 s40, 29
	s_cbranch_scc0 .LBB0_1088
	s_and_b64 vcc, exec, s[18:19]
	s_cbranch_vccz .LBB0_1091
	s_barrier

; #define PG8_STAGE(bufoff, gbase, voff) do { _Pragma("unroll") for (int _i = 0; _i < 2; ++_i) \
;         __builtin_amdgcn_global_load_lds((const unsigned*)((const char*)(gbase) + (voff)[_i]), (LAS unsigned*)(lds + (bufoff) + ldsw + _i * 8192), 16, 0, 0); } while (0)
; #define PG8_LDA(dst, b, h) do { _Pragma("unroll") for (int m = 0; m < 4; ++m) _Pragma("unroll") for (int k = 0; k < 2; ++k) dst[m][k] = *(const LAS bf16x8*)(lds + PG8_SA(b, h) + aoff + m * 2048 + k * 1024); } while (0)
; #define PG8_LDB(dst, b, h) do { _Pragma("unroll") for (int n = 0; n < 2; ++n) _Pragma("unroll") for (int k = 0; k < 2; ++k) dst[n][k] = *(const LAS bf16x8*)(lds + PG8_SB(b, h) + boff + n * 2048 + k * 1024); } while (0)
; #define PG8_MMA(ai, bj, At, Bt) do { __builtin_amdgcn_s_setprio(1); _Pragma("unroll") for (int m = 0; m < 4; ++m) _Pragma("unroll") for (int n = 0; n < 2; ++n) _Pragma("unroll") for (int k = 0; k < 2; ++k) \
;         acc[ai][bj][m][n] = __builtin_amdgcn_mfma_f32_16x16x32_bf16(Bt[n][k], At[m][k], acc[ai][bj][m][n], 0, 0, 0); __builtin_amdgcn_s_setprio(0); } while (0)
; #define PG8_WAIT_V(n) asm volatile("s_waitcnt vmcnt(" #n ")" ::: "memory")
; #define PG8_WAIT_L(n) asm volatile("s_waitcnt lgkmcnt(" #n ")" ::: "memory")
; #define PG8_BAR __builtin_amdgcn_s_barrier()
; #define PG8_SCHED __builtin_amdgcn_sched_barrier(0)
; template <class Epi, class Map>
; __device__ __forceinline__ void gemm_phase(LAS unsigned char* lds, const Gemm g, const Sched<Map>& S, const Epi& E) {
;     ...
;         for (int t = 0; t < nt; t += 2) {
;             const bool last = (t == nt - 2);
;             const char* a1 = cA + (size_t)(t + 1) * kstep;
;             const char* a2 = last ? nA : cA + (size_t)(t + 2) * kstep; const char* b2 = last ? nB : cB + (size_t)(t + 2) * kstep;
;             const char* a3 = a2 + kstep; const char* b3 = b2 + kstep;
;             PG8_LDB(B0, 0, 0); PG8_LDB(B1, 0, 1); PG8_SCHED; PG8_LDA(At, 0, 0); PG8_STAGE(PG8_SA(1, 1), a1 + hstepA, voffA);
;             PG8_WAIT_V(8); PG8_WAIT_L(0); PG8_BAR; PG8_MMA(0, 0, At, B0); PG8_MMA(0, 1, At, B1); PG8_BAR; PG8_SCHED;
;             PG8_LDA(At, 0, 1); PG8_STAGE(PG8_SB(0, 0), b2, voffB); PG8_STAGE(PG8_SB(0, 1), b2 + hstepB, voffB); PG8_STAGE(PG8_SA(0, 0), a2, voffA);
.LBB0_1161:
	s_add_u32 s30, s28, 0xffe00080
	s_addc_u32 s31, s29, -1
	s_add_i32 s50, 0, 0x10000
	s_cmpk_eq_i32 s49, 0x7c
	s_cselect_b32 s35, s37, s31
	s_cselect_b32 s34, s44, s30
	s_cselect_b32 s31, s45, s48
	s_cselect_b32 s30, s46, s47
	s_add_i32 s52, 0, 0x14000
	v_add_u32_e32 v116, s50, v173
	v_add_u32_e32 v170, s52, v173
	ds_read_b128 v[104:107], v116
	ds_read_b128 v[108:111], v116 offset:1024
	ds_read_b128 v[112:115], v116 offset:2048
	ds_read_b128 v[116:119], v116 offset:3072
	ds_read_b128 v[176:179], v170
	ds_read_b128 v[192:195], v170 offset:1024
	ds_read_b128 v[196:199], v170 offset:2048
	ds_read_b128 v[200:203], v170 offset:3072
	v_lshl_add_u64 v[170:171], s[28:29], 0, v[166:167]
	s_add_i32 m0, s3, 0xc000
	ds_read_b128 v[204:207], v174
	ds_read_b128 v[208:211], v174 offset:1024
	ds_read_b128 v[212:215], v174 offset:2048
	ds_read_b128 v[216:219], v174 offset:3072
	ds_read_b128 v[220:223], v174 offset:4096
	ds_read_b128 v[224:227], v174 offset:5120
	ds_read_b128 v[228:231], v174 offset:6144
	ds_read_b128 v[232:235], v174 offset:7168
	global_load_lds_dwordx4 v[170:171], off
	v_lshl_add_u64 v[170:171], s[28:29], 0, v[168:169]
	s_add_i32 m0, s3, 0xe000
	s_nop 0
	global_load_lds_dwordx4 v[170:171], off
	s_waitcnt vmcnt(8)
	s_waitcnt lgkmcnt(0)
	s_barrier
	s_waitcnt lgkmcnt(0)
	v_mfma_f32_16x16x32_bf16 v[140:143], v[104:107], v[204:207], v[140:143]
	v_mfma_f32_16x16x32_bf16 v[136:139], v[112:115], v[204:207], v[136:139]
	v_mfma_f32_16x16x32_bf16 v[132:135], v[104:107], v[212:215], v[132:135]
	v_mfma_f32_16x16x32_bf16 v[128:131], v[112:115], v[212:215], v[128:131]
	v_mfma_f32_16x16x32_bf16 v[100:103], v[104:107], v[220:223], v[100:103]
	v_mfma_f32_16x16x32_bf16 v[96:99], v[112:115], v[220:223], v[96:99]
	v_mfma_f32_16x16x32_bf16 v[76:79], v[104:107], v[228:231], v[76:79]
	v_mfma_f32_16x16x32_bf16 v[72:75], v[112:115], v[228:231], v[72:75]
	v_mfma_f32_16x16x32_bf16 v[140:143], v[108:111], v[208:211], v[140:143]
	v_mfma_f32_16x16x32_bf16 v[136:139], v[116:119], v[208:211], v[136:139]
	v_mfma_f32_16x16x32_bf16 v[132:135], v[108:111], v[216:219], v[132:135]
	v_mfma_f32_16x16x32_bf16 v[128:131], v[116:119], v[216:219], v[128:131]
	v_mfma_f32_16x16x32_bf16 v[100:103], v[108:111], v[224:227], v[100:103]
	v_mfma_f32_16x16x32_bf16 v[96:99], v[116:119], v[224:227], v[96:99]
	v_mfma_f32_16x16x32_bf16 v[76:79], v[108:111], v[232:235], v[76:79]
	v_mfma_f32_16x16x32_bf16 v[72:75], v[116:119], v[232:235], v[72:75]
	v_mfma_f32_16x16x32_bf16 v[124:127], v[176:179], v[204:207], v[124:127]
	v_mfma_f32_16x16x32_bf16 v[120:123], v[196:199], v[204:207], v[120:123]
	v_mfma_f32_16x16x32_bf16 v[92:95], v[176:179], v[212:215], v[92:95]
	v_mfma_f32_16x16x32_bf16 v[88:91], v[196:199], v[212:215], v[88:91]
	v_mfma_f32_16x16x32_bf16 v[84:87], v[176:179], v[220:223], v[84:87]
	v_mfma_f32_16x16x32_bf16 v[80:83], v[196:199], v[220:223], v[80:83]
	v_mfma_f32_16x16x32_bf16 v[68:71], v[176:179], v[228:231], v[68:71]
	v_mfma_f32_16x16x32_bf16 v[64:67], v[196:199], v[228:231], v[64:67]
	v_mfma_f32_16x16x32_bf16 v[124:127], v[192:195], v[208:211], v[124:127]
	v_mfma_f32_16x16x32_bf16 v[120:123], v[200:203], v[208:211], v[120:123]
	v_mfma_f32_16x16x32_bf16 v[92:95], v[192:195], v[216:219], v[92:95]
	v_mfma_f32_16x16x32_bf16 v[88:91], v[200:203], v[216:219], v[88:91]
	v_mfma_f32_16x16x32_bf16 v[84:87], v[192:195], v[224:227], v[84:87]
	v_mfma_f32_16x16x32_bf16 v[80:83], v[200:203], v[224:227], v[80:83]
	v_mfma_f32_16x16x32_bf16 v[68:71], v[192:195], v[232:235], v[68:71]
	v_mfma_f32_16x16x32_bf16 v[64:67], v[200:203], v[232:235], v[64:67]
	s_barrier
	s_add_i32 s50, s50, s2
	v_lshl_add_u64 v[170:171], s[30:31], 0, v[144:145]
	s_mov_b32 m0, s50
	ds_read_b128 v[204:207], v174 offset:16384
	ds_read_b128 v[208:211], v174 offset:17408
	ds_read_b128 v[212:215], v174 offset:18432
	ds_read_b128 v[216:219], v174 offset:19456
	ds_read_b128 v[220:223], v174 offset:20480
	ds_read_b128 v[224:227], v174 offset:21504
	ds_read_b128 v[228:231], v174 offset:22528
	ds_read_b128 v[232:235], v174 offset:23552
	global_load_lds_dwordx4 v[170:171], off
	s_add_i32 m0, s50, 0x2000
	s_add_u32 s50, s30, 0x200000
	v_lshl_add_u64 v[180:181], s[30:31], 0, v[160:161]
	s_addc_u32 s51, s31, 0
	s_add_i32 s52, s52, s2
	global_load_lds_dwordx4 v[180:181], off
	v_lshl_add_u64 v[236:237], s[50:51], 0, v[144:145]
	s_mov_b32 m0, s52
	v_lshl_add_u64 v[238:239], s[34:35], 0, v[162:163]
	global_load_lds_dwordx4 v[236:237], off
	v_lshl_add_u64 v[236:237], s[50:51], 0, v[160:161]
	s_add_i32 m0, s52, 0x2000
	s_nop 0
	global_load_lds_dwordx4 v[236:237], off
	v_lshl_add_u64 v[236:237], s[34:35], 0, v[164:165]
	s_mov_b32 m0, s3
	s_nop 0
	global_load_lds_dwordx4 v[236:237], off
	s_mov_b32 m0, s4
	s_nop 0
	global_load_lds_dwordx4 v[238:239], off
	s_waitcnt vmcnt(8)
	s_waitcnt lgkmcnt(0)
	s_barrier
; #define PG8_STAGE(bufoff, gbase, voff) do { _Pragma("unroll") for (int _i = 0; _i < 2; ++_i) \
;         __builtin_amdgcn_global_load_lds((const unsigned*)((const char*)(gbase) + (voff)[_i]), (LAS unsigned*)(lds + (bufoff) + ldsw + _i * 8192), 16, 0, 0); } while (0)
; #define PG8_LDA(dst, b, h) do { _Pragma("unroll") for (int m = 0; m < 4; ++m) _Pragma("unroll") for (int k = 0; k < 2; ++k) dst[m][k] = *(const LAS bf16x8*)(lds + PG8_SA(b, h) + aoff + m * 2048 + k * 1024); } while (0)
; #define PG8_LDB(dst, b, h) do { _Pragma("unroll") for (int n = 0; n < 2; ++n) _Pragma("unroll") for (int k = 0; k < 2; ++k) dst[n][k] = *(const LAS bf16x8*)(lds + PG8_SB(b, h) + boff + n * 2048 + k * 1024); } while (0)
; #define PG8_MMA(ai, bj, At, Bt) do { __builtin_amdgcn_s_setprio(1); _Pragma("unroll") for (int m = 0; m < 4; ++m) _Pragma("unroll") for (int n = 0; n < 2; ++n) _Pragma("unroll") for (int k = 0; k < 2; ++k) \
;         acc[ai][bj][m][n] = __builtin_amdgcn_mfma_f32_16x16x32_bf16(Bt[n][k], At[m][k], acc[ai][bj][m][n], 0, 0, 0); __builtin_amdgcn_s_setprio(0); } while (0)
; #define PG8_WAIT_V(n) asm volatile("s_waitcnt vmcnt(" #n ")" ::: "memory")
; #define PG8_WAIT_L(n) asm volatile("s_waitcnt lgkmcnt(" #n ")" ::: "memory")
; #define PG8_BAR __builtin_amdgcn_s_barrier()
; #define PG8_SCHED __builtin_amdgcn_sched_barrier(0)
; template <class Epi, class Map>
; __device__ __forceinline__ void gemm_phase(LAS unsigned char* lds, const Gemm g, const Sched<Map>& S, const Epi& E) {
;     ...
;             PG8_WAIT_V(8); PG8_WAIT_L(0); PG8_BAR; PG8_MMA(1, 0, At, B0); PG8_MMA(1, 1, At, B1); PG8_BAR; PG8_SCHED;
;             PG8_LDB(B0, 1, 0); PG8_LDB(B1, 1, 1); PG8_SCHED; PG8_LDA(At, 1, 0); PG8_STAGE(PG8_SA(0, 1), a2 + hstepA, voffA);
;             PG8_WAIT_V(8); PG8_WAIT_L(0); PG8_BAR; PG8_MMA(0, 0, At, B0); PG8_MMA(0, 1, At, B1); PG8_BAR; PG8_SCHED;
	s_waitcnt lgkmcnt(0)
	v_mfma_f32_16x16x32_bf16 v[60:63], v[104:107], v[204:207], v[60:63]
	v_mfma_f32_16x16x32_bf16 v[56:59], v[112:115], v[204:207], v[56:59]
	v_mfma_f32_16x16x32_bf16 v[48:51], v[104:107], v[212:215], v[48:51]
	v_mfma_f32_16x16x32_bf16 v[40:43], v[112:115], v[212:215], v[40:43]
	v_mfma_f32_16x16x32_bf16 v[32:35], v[104:107], v[220:223], v[32:35]
	v_mfma_f32_16x16x32_bf16 v[24:27], v[112:115], v[220:223], v[24:27]
	v_mfma_f32_16x16x32_bf16 v[16:19], v[104:107], v[228:231], v[16:19]
	v_mfma_f32_16x16x32_bf16 v[8:11], v[112:115], v[228:231], v[8:11]
	v_mfma_f32_16x16x32_bf16 v[60:63], v[108:111], v[208:211], v[60:63]
	v_mfma_f32_16x16x32_bf16 v[56:59], v[116:119], v[208:211], v[56:59]
	v_mfma_f32_16x16x32_bf16 v[48:51], v[108:111], v[216:219], v[48:51]
	v_mfma_f32_16x16x32_bf16 v[40:43], v[116:119], v[216:219], v[40:43]
	v_mfma_f32_16x16x32_bf16 v[32:35], v[108:111], v[224:227], v[32:35]
	v_mfma_f32_16x16x32_bf16 v[24:27], v[116:119], v[224:227], v[24:27]
	v_mfma_f32_16x16x32_bf16 v[16:19], v[108:111], v[232:235], v[16:19]
	v_mfma_f32_16x16x32_bf16 v[8:11], v[116:119], v[232:235], v[8:11]
	v_mfma_f32_16x16x32_bf16 v[52:55], v[176:179], v[204:207], v[52:55]
	v_mfma_f32_16x16x32_bf16 v[44:47], v[196:199], v[204:207], v[44:47]
	v_mfma_f32_16x16x32_bf16 v[36:39], v[176:179], v[212:215], v[36:39]
	v_mfma_f32_16x16x32_bf16 v[28:31], v[196:199], v[212:215], v[28:31]
	v_mfma_f32_16x16x32_bf16 v[20:23], v[176:179], v[220:223], v[20:23]
	v_mfma_f32_16x16x32_bf16 v[12:15], v[196:199], v[220:223], v[12:15]
	v_mfma_f32_16x16x32_bf16 v[4:7], v[176:179], v[228:231], v[4:7]
	v_mfma_f32_16x16x32_bf16 v[0:3], v[196:199], v[228:231], v[0:3]
	v_mfma_f32_16x16x32_bf16 v[52:55], v[192:195], v[208:211], v[52:55]
	v_mfma_f32_16x16x32_bf16 v[44:47], v[200:203], v[208:211], v[44:47]
	v_mfma_f32_16x16x32_bf16 v[36:39], v[192:195], v[216:219], v[36:39]
	v_mfma_f32_16x16x32_bf16 v[28:31], v[200:203], v[216:219], v[28:31]
	v_mfma_f32_16x16x32_bf16 v[20:23], v[192:195], v[224:227], v[20:23]
	v_mfma_f32_16x16x32_bf16 v[12:15], v[200:203], v[224:227], v[12:15]
	v_mfma_f32_16x16x32_bf16 v[4:7], v[192:195], v[232:235], v[4:7]
	v_mfma_f32_16x16x32_bf16 v[0:3], v[200:203], v[232:235], v[0:3]
	s_barrier
	s_add_i32 s50, 0, 0x18000
	s_add_i32 s51, 0, 0x1c000
	v_add_u32_e32 v116, s50, v173
	v_add_u32_e32 v175, s51, v173
	ds_read_b128 v[104:107], v116
	ds_read_b128 v[108:111], v116 offset:1024
	ds_read_b128 v[112:115], v116 offset:2048
	ds_read_b128 v[116:119], v116 offset:3072
	ds_read_b128 v[176:179], v175
	ds_read_b128 v[192:195], v175 offset:1024
	ds_read_b128 v[196:199], v175 offset:2048
	ds_read_b128 v[200:203], v175 offset:3072
	s_add_u32 s34, s34, 0x200000
	s_addc_u32 s35, s35, 0
	s_mov_b32 m0, s5
	v_lshl_add_u64 v[240:241], s[34:35], 0, v[164:165]
	ds_read_b128 v[204:207], v174 offset:32768
	ds_read_b128 v[208:211], v174 offset:33792
	ds_read_b128 v[212:215], v174 offset:34816
	ds_read_b128 v[216:219], v174 offset:35840
	ds_read_b128 v[220:223], v174 offset:36864
	ds_read_b128 v[224:227], v174 offset:37888
	ds_read_b128 v[228:231], v174 offset:38912
	ds_read_b128 v[232:235], v174 offset:39936
	global_load_lds_dwordx4 v[240:241], off
	v_lshl_add_u64 v[240:241], s[34:35], 0, v[162:163]
	s_mov_b32 m0, s6
	s_nop 0
	global_load_lds_dwordx4 v[240:241], off
	s_waitcnt vmcnt(8)
	s_waitcnt lgkmcnt(0)
	s_barrier
	s_waitcnt lgkmcnt(0)
	v_mfma_f32_16x16x32_bf16 v[140:143], v[104:107], v[204:207], v[140:143]
	v_mfma_f32_16x16x32_bf16 v[136:139], v[112:115], v[204:207], v[136:139]
	v_mfma_f32_16x16x32_bf16 v[132:135], v[104:107], v[212:215], v[132:135]
	v_mfma_f32_16x16x32_bf16 v[128:131], v[112:115], v[212:215], v[128:131]
	v_mfma_f32_16x16x32_bf16 v[100:103], v[104:107], v[220:223], v[100:103]
	v_mfma_f32_16x16x32_bf16 v[96:99], v[112:115], v[220:223], v[96:99]
	v_mfma_f32_16x16x32_bf16 v[76:79], v[104:107], v[228:231], v[76:79]
	v_mfma_f32_16x16x32_bf16 v[72:75], v[112:115], v[228:231], v[72:75]
	v_mfma_f32_16x16x32_bf16 v[140:143], v[108:111], v[208:211], v[140:143]
	v_mfma_f32_16x16x32_bf16 v[136:139], v[116:119], v[208:211], v[136:139]
	v_mfma_f32_16x16x32_bf16 v[132:135], v[108:111], v[216:219], v[132:135]
	v_mfma_f32_16x16x32_bf16 v[128:131], v[116:119], v[216:219], v[128:131]
	v_mfma_f32_16x16x32_bf16 v[100:103], v[108:111], v[224:227], v[100:103]
	v_mfma_f32_16x16x32_bf16 v[96:99], v[116:119], v[224:227], v[96:99]
	v_mfma_f32_16x16x32_bf16 v[76:79], v[108:111], v[232:235], v[76:79]
	v_mfma_f32_16x16x32_bf16 v[72:75], v[116:119], v[232:235], v[72:75]
	v_mfma_f32_16x16x32_bf16 v[124:127], v[176:179], v[204:207], v[124:127]
	v_mfma_f32_16x16x32_bf16 v[120:123], v[196:199], v[204:207], v[120:123]
	v_mfma_f32_16x16x32_bf16 v[92:95], v[176:179], v[212:215], v[92:95]
	v_mfma_f32_16x16x32_bf16 v[88:91], v[196:199], v[212:215], v[88:91]
	v_mfma_f32_16x16x32_bf16 v[84:87], v[176:179], v[220:223], v[84:87]
	v_mfma_f32_16x16x32_bf16 v[80:83], v[196:199], v[220:223], v[80:83]
	v_mfma_f32_16x16x32_bf16 v[68:71], v[176:179], v[228:231], v[68:71]
	v_mfma_f32_16x16x32_bf16 v[64:67], v[196:199], v[228:231], v[64:67]
	v_mfma_f32_16x16x32_bf16 v[124:127], v[192:195], v[208:211], v[124:127]
	v_mfma_f32_16x16x32_bf16 v[120:123], v[200:203], v[208:211], v[120:123]
	v_mfma_f32_16x16x32_bf16 v[92:95], v[192:195], v[216:219], v[92:95]
	v_mfma_f32_16x16x32_bf16 v[88:91], v[200:203], v[216:219], v[88:91]
	v_mfma_f32_16x16x32_bf16 v[84:87], v[192:195], v[224:227], v[84:87]
	v_mfma_f32_16x16x32_bf16 v[80:83], v[200:203], v[224:227], v[80:83]
	v_mfma_f32_16x16x32_bf16 v[68:71], v[192:195], v[232:235], v[68:71]
	v_mfma_f32_16x16x32_bf16 v[64:67], v[200:203], v[232:235], v[64:67]
	s_barrier
; #define PG8_STAGE(bufoff, gbase, voff) do { _Pragma("unroll") for (int _i = 0; _i < 2; ++_i) \
;         __builtin_amdgcn_global_load_lds((const unsigned*)((const char*)(gbase) + (voff)[_i]), (LAS unsigned*)(lds + (bufoff) + ldsw + _i * 8192), 16, 0, 0); } while (0)
; #define PG8_LDA(dst, b, h) do { _Pragma("unroll") for (int m = 0; m < 4; ++m) _Pragma("unroll") for (int k = 0; k < 2; ++k) dst[m][k] = *(const LAS bf16x8*)(lds + PG8_SA(b, h) + aoff + m * 2048 + k * 1024); } while (0)
; #define PG8_MMA(ai, bj, At, Bt) do { __builtin_amdgcn_s_setprio(1); _Pragma("unroll") for (int m = 0; m < 4; ++m) _Pragma("unroll") for (int n = 0; n < 2; ++n) _Pragma("unroll") for (int k = 0; k < 2; ++k) \
;         acc[ai][bj][m][n] = __builtin_amdgcn_mfma_f32_16x16x32_bf16(Bt[n][k], At[m][k], acc[ai][bj][m][n], 0, 0, 0); __builtin_amdgcn_s_setprio(0); } while (0)
; #define PG8_WAIT_V(n) asm volatile("s_waitcnt vmcnt(" #n ")" ::: "memory")
; #define PG8_WAIT_L(n) asm volatile("s_waitcnt lgkmcnt(" #n ")" ::: "memory")
; #define PG8_BAR __builtin_amdgcn_s_barrier()
; #define PG8_SCHED __builtin_amdgcn_sched_barrier(0)
; template <class Epi, class Map>
; __device__ __forceinline__ void gemm_phase(LAS unsigned char* lds, const Gemm g, const Sched<Map>& S, const Epi& E) {
;     ...
;             PG8_LDA(At, 1, 1); PG8_STAGE(PG8_SB(1, 0), b3, voffB); PG8_STAGE(PG8_SB(1, 1), b3 + hstepB, voffB); PG8_STAGE(PG8_SA(1, 0), a3, voffA);
;             PG8_WAIT_V(8); PG8_WAIT_L(0); PG8_BAR; PG8_MMA(1, 0, At, B0); PG8_MMA(1, 1, At, B1); PG8_BAR; PG8_SCHED;
;         }
;         if (wr == 0) PG8_BAR;
	s_add_i32 s34, s50, s2
	v_lshl_add_u64 v[170:171], v[170:171], 0, s[82:83]
	s_mov_b32 m0, s34
	ds_read_b128 v[204:207], v174 offset:49152
	ds_read_b128 v[208:211], v174 offset:50176
	ds_read_b128 v[212:215], v174 offset:51200
	ds_read_b128 v[216:219], v174 offset:52224
	ds_read_b128 v[220:223], v174 offset:53248
	ds_read_b128 v[224:227], v174 offset:54272
	ds_read_b128 v[228:231], v174 offset:55296
	ds_read_b128 v[232:235], v174 offset:56320
	global_load_lds_dwordx4 v[170:171], off
	s_add_i32 m0, s34, 0x2000
	s_add_u32 s30, s30, 0x200080
	v_lshl_add_u64 v[170:171], v[180:181], 0, s[82:83]
	s_addc_u32 s31, s31, 0
	s_add_i32 s34, s51, s2
	global_load_lds_dwordx4 v[170:171], off
	v_lshl_add_u64 v[170:171], s[30:31], 0, v[144:145]
	s_mov_b32 m0, s34
	s_nop 0
	global_load_lds_dwordx4 v[170:171], off
	v_lshl_add_u64 v[170:171], s[30:31], 0, v[160:161]
	s_add_i32 m0, s34, 0x2000
	s_nop 0
	global_load_lds_dwordx4 v[170:171], off
	v_lshl_add_u64 v[170:171], v[236:237], 0, s[82:83]
	s_mov_b32 m0, s9
	s_nop 0
	global_load_lds_dwordx4 v[170:171], off
	v_lshl_add_u64 v[170:171], v[238:239], 0, s[82:83]
	s_mov_b32 m0, s10
	s_nop 0
	global_load_lds_dwordx4 v[170:171], off
	s_waitcnt vmcnt(8)
	s_waitcnt lgkmcnt(0)
	s_barrier
	s_waitcnt lgkmcnt(0)
	v_mfma_f32_16x16x32_bf16 v[60:63], v[104:107], v[204:207], v[60:63]
	v_mfma_f32_16x16x32_bf16 v[56:59], v[112:115], v[204:207], v[56:59]
	v_mfma_f32_16x16x32_bf16 v[48:51], v[104:107], v[212:215], v[48:51]
	v_mfma_f32_16x16x32_bf16 v[40:43], v[112:115], v[212:215], v[40:43]
	v_mfma_f32_16x16x32_bf16 v[32:35], v[104:107], v[220:223], v[32:35]
	v_mfma_f32_16x16x32_bf16 v[24:27], v[112:115], v[220:223], v[24:27]
	v_mfma_f32_16x16x32_bf16 v[16:19], v[104:107], v[228:231], v[16:19]
	v_mfma_f32_16x16x32_bf16 v[8:11], v[112:115], v[228:231], v[8:11]
	v_mfma_f32_16x16x32_bf16 v[60:63], v[108:111], v[208:211], v[60:63]
	v_mfma_f32_16x16x32_bf16 v[56:59], v[116:119], v[208:211], v[56:59]
	v_mfma_f32_16x16x32_bf16 v[48:51], v[108:111], v[216:219], v[48:51]
	v_mfma_f32_16x16x32_bf16 v[40:43], v[116:119], v[216:219], v[40:43]
	v_mfma_f32_16x16x32_bf16 v[32:35], v[108:111], v[224:227], v[32:35]
	v_mfma_f32_16x16x32_bf16 v[24:27], v[116:119], v[224:227], v[24:27]
	v_mfma_f32_16x16x32_bf16 v[16:19], v[108:111], v[232:235], v[16:19]
	v_mfma_f32_16x16x32_bf16 v[8:11], v[116:119], v[232:235], v[8:11]
	v_mfma_f32_16x16x32_bf16 v[52:55], v[176:179], v[204:207], v[52:55]
	v_mfma_f32_16x16x32_bf16 v[44:47], v[196:199], v[204:207], v[44:47]
	v_mfma_f32_16x16x32_bf16 v[36:39], v[176:179], v[212:215], v[36:39]
	v_mfma_f32_16x16x32_bf16 v[28:31], v[196:199], v[212:215], v[28:31]
	v_mfma_f32_16x16x32_bf16 v[20:23], v[176:179], v[220:223], v[20:23]
	v_mfma_f32_16x16x32_bf16 v[12:15], v[196:199], v[220:223], v[12:15]
	v_mfma_f32_16x16x32_bf16 v[4:7], v[176:179], v[228:231], v[4:7]
	v_mfma_f32_16x16x32_bf16 v[0:3], v[196:199], v[228:231], v[0:3]
	v_mfma_f32_16x16x32_bf16 v[52:55], v[192:195], v[208:211], v[52:55]
	v_mfma_f32_16x16x32_bf16 v[44:47], v[200:203], v[208:211], v[44:47]
	v_mfma_f32_16x16x32_bf16 v[36:39], v[192:195], v[216:219], v[36:39]
	v_mfma_f32_16x16x32_bf16 v[28:31], v[200:203], v[216:219], v[28:31]
	v_mfma_f32_16x16x32_bf16 v[20:23], v[192:195], v[224:227], v[20:23]
	v_mfma_f32_16x16x32_bf16 v[12:15], v[200:203], v[224:227], v[12:15]
	v_mfma_f32_16x16x32_bf16 v[4:7], v[192:195], v[232:235], v[4:7]
	v_mfma_f32_16x16x32_bf16 v[0:3], v[200:203], v[232:235], v[0:3]
	s_barrier
	s_add_i32 s49, s49, 2
	s_add_u32 s28, s28, 0x100
	s_addc_u32 s29, s29, 0
	s_add_u32 s47, s47, 0x100
	s_addc_u32 s48, s48, 0
	s_cmpk_gt_u32 s49, 0x7d
	s_cbranch_scc0 .LBB0_1161
	s_and_b64 vcc, exec, s[18:19]
	s_cbranch_vccz .LBB0_1164
	s_barrier

; #define PG8_STAGE(bufoff, gbase, voff) do { _Pragma("unroll") for (int _i = 0; _i < 2; ++_i) \
;         __builtin_amdgcn_global_load_lds((const unsigned*)((const char*)(gbase) + (voff)[_i]), (LAS unsigned*)(lds + (bufoff) + ldsw + _i * 8192), 16, 0, 0); } while (0)
; #define PG8_LDA(dst, b, h) do { _Pragma("unroll") for (int m = 0; m < 4; ++m) _Pragma("unroll") for (int k = 0; k < 2; ++k) dst[m][k] = *(const LAS bf16x8*)(lds + PG8_SA(b, h) + aoff + m * 2048 + k * 1024); } while (0)
; #define PG8_LDB(dst, b, h) do { _Pragma("unroll") for (int n = 0; n < 2; ++n) _Pragma("unroll") for (int k = 0; k < 2; ++k) dst[n][k] = *(const LAS bf16x8*)(lds + PG8_SB(b, h) + boff + n * 2048 + k * 1024); } while (0)
; #define PG8_MMA(ai, bj, At, Bt) do { __builtin_amdgcn_s_setprio(1); _Pragma("unroll") for (int m = 0; m < 4; ++m) _Pragma("unroll") for (int n = 0; n < 2; ++n) _Pragma("unroll") for (int k = 0; k < 2; ++k) \
;         acc[ai][bj][m][n] = __builtin_amdgcn_mfma_f32_16x16x32_bf16(Bt[n][k], At[m][k], acc[ai][bj][m][n], 0, 0, 0); __builtin_amdgcn_s_setprio(0); } while (0)
; #define PG8_WAIT_V(n) asm volatile("s_waitcnt vmcnt(" #n ")" ::: "memory")
; #define PG8_WAIT_L(n) asm volatile("s_waitcnt lgkmcnt(" #n ")" ::: "memory")
; #define PG8_BAR __builtin_amdgcn_s_barrier()
; #define PG8_SCHED __builtin_amdgcn_sched_barrier(0)
; template <class Epi, class Map>
; __device__ __forceinline__ void gemm_phase(LAS unsigned char* lds, const Gemm g, const Sched<Map>& S, const Epi& E) {
;     ...
;         for (int t = 0; t < nt; t += 2) {
;             const bool last = (t == nt - 2);
;             const char* a1 = cA + (size_t)(t + 1) * kstep;
;             const char* a2 = last ? nA : cA + (size_t)(t + 2) * kstep; const char* b2 = last ? nB : cB + (size_t)(t + 2) * kstep;
;             const char* a3 = a2 + kstep; const char* b3 = b2 + kstep;
;             PG8_LDB(B0, 0, 0); PG8_LDB(B1, 0, 1); PG8_SCHED; PG8_LDA(At, 0, 0); PG8_STAGE(PG8_SA(1, 1), a1 + hstepA, voffA);
;             PG8_WAIT_V(8); PG8_WAIT_L(0); PG8_BAR; PG8_MMA(0, 0, At, B0); PG8_MMA(0, 1, At, B1); PG8_BAR; PG8_SCHED;
;             PG8_LDA(At, 0, 1); PG8_STAGE(PG8_SB(0, 0), b2, voffB); PG8_STAGE(PG8_SB(0, 1), b2 + hstepB, voffB); PG8_STAGE(PG8_SA(0, 0), a2, voffA);
.LBB0_1183:
	s_add_u32 s30, s28, 0xffe00080
	s_addc_u32 s31, s29, -1
	s_add_i32 s48, 0, 0x10000
	s_cmpk_eq_i32 s47, 0x7c
	s_cselect_b32 s35, s37, s31
	s_cselect_b32 s34, s40, s30
	s_cselect_b32 s31, s41, s46
	s_cselect_b32 s30, s44, s45
	s_add_i32 s50, 0, 0x14000
	v_add_u32_e32 v108, s48, v173
	v_add_u32_e32 v170, s50, v173
	ds_read_b128 v[64:67], v108
	ds_read_b128 v[68:71], v108 offset:1024
	ds_read_b128 v[72:75], v108 offset:2048
	ds_read_b128 v[108:111], v108 offset:3072
	ds_read_b128 v[166:169], v170
	ds_read_b128 v[176:179], v170 offset:1024
	ds_read_b128 v[192:195], v170 offset:2048
	ds_read_b128 v[196:199], v170 offset:3072
	v_lshl_add_u64 v[170:171], s[28:29], 0, v[162:163]
	s_add_i32 m0, s3, 0xc000
	ds_read_b128 v[200:203], v174
	ds_read_b128 v[204:207], v174 offset:1024
	ds_read_b128 v[208:211], v174 offset:2048
	ds_read_b128 v[212:215], v174 offset:3072
	ds_read_b128 v[216:219], v174 offset:4096
	ds_read_b128 v[220:223], v174 offset:5120
	ds_read_b128 v[224:227], v174 offset:6144
	ds_read_b128 v[228:231], v174 offset:7168
	global_load_lds_dwordx4 v[170:171], off
	v_lshl_add_u64 v[170:171], s[28:29], 0, v[164:165]
	s_add_i32 m0, s3, 0xe000
	s_nop 0
	global_load_lds_dwordx4 v[170:171], off
	s_waitcnt vmcnt(8)
	s_waitcnt lgkmcnt(0)
	s_barrier
	s_waitcnt lgkmcnt(0)
	v_mfma_f32_16x16x32_bf16 v[140:143], v[64:67], v[200:203], v[140:143]
	v_mfma_f32_16x16x32_bf16 v[136:139], v[72:75], v[200:203], v[136:139]
	v_mfma_f32_16x16x32_bf16 v[132:135], v[64:67], v[208:211], v[132:135]
	v_mfma_f32_16x16x32_bf16 v[128:131], v[72:75], v[208:211], v[128:131]
	v_mfma_f32_16x16x32_bf16 v[104:107], v[64:67], v[216:219], v[104:107]
	v_mfma_f32_16x16x32_bf16 v[100:103], v[72:75], v[216:219], v[100:103]
	v_mfma_f32_16x16x32_bf16 v[96:99], v[64:67], v[224:227], v[96:99]
	v_mfma_f32_16x16x32_bf16 v[92:95], v[72:75], v[224:227], v[92:95]
	v_mfma_f32_16x16x32_bf16 v[140:143], v[68:71], v[204:207], v[140:143]
	v_mfma_f32_16x16x32_bf16 v[136:139], v[108:111], v[204:207], v[136:139]
	v_mfma_f32_16x16x32_bf16 v[132:135], v[68:71], v[212:215], v[132:135]
	v_mfma_f32_16x16x32_bf16 v[128:131], v[108:111], v[212:215], v[128:131]
	v_mfma_f32_16x16x32_bf16 v[104:107], v[68:71], v[220:223], v[104:107]
	v_mfma_f32_16x16x32_bf16 v[100:103], v[108:111], v[220:223], v[100:103]
	v_mfma_f32_16x16x32_bf16 v[96:99], v[68:71], v[228:231], v[96:99]
	v_mfma_f32_16x16x32_bf16 v[92:95], v[108:111], v[228:231], v[92:95]
	v_mfma_f32_16x16x32_bf16 v[124:127], v[166:169], v[200:203], v[124:127]
	v_mfma_f32_16x16x32_bf16 v[120:123], v[192:195], v[200:203], v[120:123]
	v_mfma_f32_16x16x32_bf16 v[116:119], v[166:169], v[208:211], v[116:119]
	v_mfma_f32_16x16x32_bf16 v[112:115], v[192:195], v[208:211], v[112:115]
	v_mfma_f32_16x16x32_bf16 v[88:91], v[166:169], v[216:219], v[88:91]
	v_mfma_f32_16x16x32_bf16 v[84:87], v[192:195], v[216:219], v[84:87]
	v_mfma_f32_16x16x32_bf16 v[80:83], v[166:169], v[224:227], v[80:83]
	v_mfma_f32_16x16x32_bf16 v[76:79], v[192:195], v[224:227], v[76:79]
	v_mfma_f32_16x16x32_bf16 v[124:127], v[176:179], v[204:207], v[124:127]
	v_mfma_f32_16x16x32_bf16 v[120:123], v[196:199], v[204:207], v[120:123]
	v_mfma_f32_16x16x32_bf16 v[116:119], v[176:179], v[212:215], v[116:119]
	v_mfma_f32_16x16x32_bf16 v[112:115], v[196:199], v[212:215], v[112:115]
	v_mfma_f32_16x16x32_bf16 v[88:91], v[176:179], v[220:223], v[88:91]
	v_mfma_f32_16x16x32_bf16 v[84:87], v[196:199], v[220:223], v[84:87]
	v_mfma_f32_16x16x32_bf16 v[80:83], v[176:179], v[228:231], v[80:83]
	v_mfma_f32_16x16x32_bf16 v[76:79], v[196:199], v[228:231], v[76:79]
	s_barrier
	s_add_i32 s48, s48, s2
	v_lshl_add_u64 v[170:171], s[30:31], 0, v[144:145]
	s_mov_b32 m0, s48
	ds_read_b128 v[200:203], v174 offset:16384
	ds_read_b128 v[204:207], v174 offset:17408
	ds_read_b128 v[208:211], v174 offset:18432
	ds_read_b128 v[212:215], v174 offset:19456
	ds_read_b128 v[216:219], v174 offset:20480
	ds_read_b128 v[220:223], v174 offset:21504
	ds_read_b128 v[224:227], v174 offset:22528
	ds_read_b128 v[228:231], v174 offset:23552
	global_load_lds_dwordx4 v[170:171], off
	s_add_i32 m0, s48, 0x2000
	s_add_u32 s48, s30, 0x200000
	v_lshl_add_u64 v[180:181], s[30:31], 0, v[160:161]
	s_addc_u32 s49, s31, 0
	s_add_i32 s50, s50, s2
	global_load_lds_dwordx4 v[180:181], off
	v_lshl_add_u64 v[232:233], s[48:49], 0, v[144:145]
	s_mov_b32 m0, s50
	v_lshl_add_u64 v[234:235], s[34:35], 0, v[160:161]
	global_load_lds_dwordx4 v[232:233], off
	v_lshl_add_u64 v[232:233], s[48:49], 0, v[160:161]
	s_add_i32 m0, s50, 0x2000
	s_nop 0
	global_load_lds_dwordx4 v[232:233], off
	v_lshl_add_u64 v[232:233], s[34:35], 0, v[144:145]
	s_mov_b32 m0, s3
	s_nop 0
	global_load_lds_dwordx4 v[232:233], off
	s_mov_b32 m0, s4
	s_nop 0
	global_load_lds_dwordx4 v[234:235], off
	s_waitcnt vmcnt(8)
	s_waitcnt lgkmcnt(0)
	s_barrier
; #define PG8_STAGE(bufoff, gbase, voff) do { _Pragma("unroll") for (int _i = 0; _i < 2; ++_i) \
;         __builtin_amdgcn_global_load_lds((const unsigned*)((const char*)(gbase) + (voff)[_i]), (LAS unsigned*)(lds + (bufoff) + ldsw + _i * 8192), 16, 0, 0); } while (0)
; #define PG8_LDA(dst, b, h) do { _Pragma("unroll") for (int m = 0; m < 4; ++m) _Pragma("unroll") for (int k = 0; k < 2; ++k) dst[m][k] = *(const LAS bf16x8*)(lds + PG8_SA(b, h) + aoff + m * 2048 + k * 1024); } while (0)
; #define PG8_LDB(dst, b, h) do { _Pragma("unroll") for (int n = 0; n < 2; ++n) _Pragma("unroll") for (int k = 0; k < 2; ++k) dst[n][k] = *(const LAS bf16x8*)(lds + PG8_SB(b, h) + boff + n * 2048 + k * 1024); } while (0)
; #define PG8_MMA(ai, bj, At, Bt) do { __builtin_amdgcn_s_setprio(1); _Pragma("unroll") for (int m = 0; m < 4; ++m) _Pragma("unroll") for (int n = 0; n < 2; ++n) _Pragma("unroll") for (int k = 0; k < 2; ++k) \
;         acc[ai][bj][m][n] = __builtin_amdgcn_mfma_f32_16x16x32_bf16(Bt[n][k], At[m][k], acc[ai][bj][m][n], 0, 0, 0); __builtin_amdgcn_s_setprio(0); } while (0)
; #define PG8_WAIT_V(n) asm volatile("s_waitcnt vmcnt(" #n ")" ::: "memory")
; #define PG8_WAIT_L(n) asm volatile("s_waitcnt lgkmcnt(" #n ")" ::: "memory")
; #define PG8_BAR __builtin_amdgcn_s_barrier()
; #define PG8_SCHED __builtin_amdgcn_sched_barrier(0)
; template <class Epi, class Map>
; __device__ __forceinline__ void gemm_phase(LAS unsigned char* lds, const Gemm g, const Sched<Map>& S, const Epi& E) {
;     ...
;             PG8_WAIT_V(8); PG8_WAIT_L(0); PG8_BAR; PG8_MMA(1, 0, At, B0); PG8_MMA(1, 1, At, B1); PG8_BAR; PG8_SCHED;
;             PG8_LDB(B0, 1, 0); PG8_LDB(B1, 1, 1); PG8_SCHED; PG8_LDA(At, 1, 0); PG8_STAGE(PG8_SA(0, 1), a2 + hstepA, voffA);
;             PG8_WAIT_V(8); PG8_WAIT_L(0); PG8_BAR; PG8_MMA(0, 0, At, B0); PG8_MMA(0, 1, At, B1); PG8_BAR; PG8_SCHED;
	s_waitcnt lgkmcnt(0)
	v_mfma_f32_16x16x32_bf16 v[60:63], v[64:67], v[200:203], v[60:63]
	v_mfma_f32_16x16x32_bf16 v[56:59], v[72:75], v[200:203], v[56:59]
	v_mfma_f32_16x16x32_bf16 v[52:55], v[64:67], v[208:211], v[52:55]
	v_mfma_f32_16x16x32_bf16 v[48:51], v[72:75], v[208:211], v[48:51]
	v_mfma_f32_16x16x32_bf16 v[28:31], v[64:67], v[216:219], v[28:31]
	v_mfma_f32_16x16x32_bf16 v[24:27], v[72:75], v[216:219], v[24:27]
	v_mfma_f32_16x16x32_bf16 v[20:23], v[64:67], v[224:227], v[20:23]
	v_mfma_f32_16x16x32_bf16 v[8:11], v[72:75], v[224:227], v[8:11]
	v_mfma_f32_16x16x32_bf16 v[60:63], v[68:71], v[204:207], v[60:63]
	v_mfma_f32_16x16x32_bf16 v[56:59], v[108:111], v[204:207], v[56:59]
	v_mfma_f32_16x16x32_bf16 v[52:55], v[68:71], v[212:215], v[52:55]
	v_mfma_f32_16x16x32_bf16 v[48:51], v[108:111], v[212:215], v[48:51]
	v_mfma_f32_16x16x32_bf16 v[28:31], v[68:71], v[220:223], v[28:31]
	v_mfma_f32_16x16x32_bf16 v[24:27], v[108:111], v[220:223], v[24:27]
	v_mfma_f32_16x16x32_bf16 v[20:23], v[68:71], v[228:231], v[20:23]
	v_mfma_f32_16x16x32_bf16 v[8:11], v[108:111], v[228:231], v[8:11]
	v_mfma_f32_16x16x32_bf16 v[44:47], v[166:169], v[200:203], v[44:47]
	v_mfma_f32_16x16x32_bf16 v[40:43], v[192:195], v[200:203], v[40:43]
	v_mfma_f32_16x16x32_bf16 v[36:39], v[166:169], v[208:211], v[36:39]
	v_mfma_f32_16x16x32_bf16 v[32:35], v[192:195], v[208:211], v[32:35]
	v_mfma_f32_16x16x32_bf16 v[16:19], v[166:169], v[216:219], v[16:19]
	v_mfma_f32_16x16x32_bf16 v[12:15], v[192:195], v[216:219], v[12:15]
	v_mfma_f32_16x16x32_bf16 v[4:7], v[166:169], v[224:227], v[4:7]
	v_mfma_f32_16x16x32_bf16 v[0:3], v[192:195], v[224:227], v[0:3]
	v_mfma_f32_16x16x32_bf16 v[44:47], v[176:179], v[204:207], v[44:47]
	v_mfma_f32_16x16x32_bf16 v[40:43], v[196:199], v[204:207], v[40:43]
	v_mfma_f32_16x16x32_bf16 v[36:39], v[176:179], v[212:215], v[36:39]
	v_mfma_f32_16x16x32_bf16 v[32:35], v[196:199], v[212:215], v[32:35]
	v_mfma_f32_16x16x32_bf16 v[16:19], v[176:179], v[220:223], v[16:19]
	v_mfma_f32_16x16x32_bf16 v[12:15], v[196:199], v[220:223], v[12:15]
	v_mfma_f32_16x16x32_bf16 v[4:7], v[176:179], v[228:231], v[4:7]
	v_mfma_f32_16x16x32_bf16 v[0:3], v[196:199], v[228:231], v[0:3]
	s_barrier
	s_add_i32 s48, 0, 0x18000
	s_add_i32 s49, 0, 0x1c000
	v_add_u32_e32 v108, s48, v173
	v_add_u32_e32 v175, s49, v173
	ds_read_b128 v[64:67], v108
	ds_read_b128 v[68:71], v108 offset:1024
	ds_read_b128 v[72:75], v108 offset:2048
	ds_read_b128 v[108:111], v108 offset:3072
	ds_read_b128 v[166:169], v175
	ds_read_b128 v[176:179], v175 offset:1024
	ds_read_b128 v[192:195], v175 offset:2048
	ds_read_b128 v[196:199], v175 offset:3072
	s_add_u32 s34, s34, 0x200000
	s_addc_u32 s35, s35, 0
	s_mov_b32 m0, s5
	v_lshl_add_u64 v[236:237], s[34:35], 0, v[144:145]
	ds_read_b128 v[200:203], v174 offset:32768
	ds_read_b128 v[204:207], v174 offset:33792
	ds_read_b128 v[208:211], v174 offset:34816
	ds_read_b128 v[212:215], v174 offset:35840
	ds_read_b128 v[216:219], v174 offset:36864
	ds_read_b128 v[220:223], v174 offset:37888
	ds_read_b128 v[224:227], v174 offset:38912
	ds_read_b128 v[228:231], v174 offset:39936
	global_load_lds_dwordx4 v[236:237], off
	v_lshl_add_u64 v[236:237], s[34:35], 0, v[160:161]
	s_mov_b32 m0, s6
	s_nop 0
	global_load_lds_dwordx4 v[236:237], off
	s_waitcnt vmcnt(8)
	s_waitcnt lgkmcnt(0)
	s_barrier
	s_waitcnt lgkmcnt(0)
	v_mfma_f32_16x16x32_bf16 v[140:143], v[64:67], v[200:203], v[140:143]
	v_mfma_f32_16x16x32_bf16 v[136:139], v[72:75], v[200:203], v[136:139]
	v_mfma_f32_16x16x32_bf16 v[132:135], v[64:67], v[208:211], v[132:135]
	v_mfma_f32_16x16x32_bf16 v[128:131], v[72:75], v[208:211], v[128:131]
	v_mfma_f32_16x16x32_bf16 v[104:107], v[64:67], v[216:219], v[104:107]
	v_mfma_f32_16x16x32_bf16 v[100:103], v[72:75], v[216:219], v[100:103]
	v_mfma_f32_16x16x32_bf16 v[96:99], v[64:67], v[224:227], v[96:99]
	v_mfma_f32_16x16x32_bf16 v[92:95], v[72:75], v[224:227], v[92:95]
	v_mfma_f32_16x16x32_bf16 v[140:143], v[68:71], v[204:207], v[140:143]
	v_mfma_f32_16x16x32_bf16 v[136:139], v[108:111], v[204:207], v[136:139]
	v_mfma_f32_16x16x32_bf16 v[132:135], v[68:71], v[212:215], v[132:135]
	v_mfma_f32_16x16x32_bf16 v[128:131], v[108:111], v[212:215], v[128:131]
	v_mfma_f32_16x16x32_bf16 v[104:107], v[68:71], v[220:223], v[104:107]
	v_mfma_f32_16x16x32_bf16 v[100:103], v[108:111], v[220:223], v[100:103]
	v_mfma_f32_16x16x32_bf16 v[96:99], v[68:71], v[228:231], v[96:99]
	v_mfma_f32_16x16x32_bf16 v[92:95], v[108:111], v[228:231], v[92:95]
	v_mfma_f32_16x16x32_bf16 v[124:127], v[166:169], v[200:203], v[124:127]
	v_mfma_f32_16x16x32_bf16 v[120:123], v[192:195], v[200:203], v[120:123]
	v_mfma_f32_16x16x32_bf16 v[116:119], v[166:169], v[208:211], v[116:119]
	v_mfma_f32_16x16x32_bf16 v[112:115], v[192:195], v[208:211], v[112:115]
	v_mfma_f32_16x16x32_bf16 v[88:91], v[166:169], v[216:219], v[88:91]
	v_mfma_f32_16x16x32_bf16 v[84:87], v[192:195], v[216:219], v[84:87]
	v_mfma_f32_16x16x32_bf16 v[80:83], v[166:169], v[224:227], v[80:83]
	v_mfma_f32_16x16x32_bf16 v[76:79], v[192:195], v[224:227], v[76:79]
	v_mfma_f32_16x16x32_bf16 v[124:127], v[176:179], v[204:207], v[124:127]
	v_mfma_f32_16x16x32_bf16 v[120:123], v[196:199], v[204:207], v[120:123]
	v_mfma_f32_16x16x32_bf16 v[116:119], v[176:179], v[212:215], v[116:119]
	v_mfma_f32_16x16x32_bf16 v[112:115], v[196:199], v[212:215], v[112:115]
	v_mfma_f32_16x16x32_bf16 v[88:91], v[176:179], v[220:223], v[88:91]
	v_mfma_f32_16x16x32_bf16 v[84:87], v[196:199], v[220:223], v[84:87]
	v_mfma_f32_16x16x32_bf16 v[80:83], v[176:179], v[228:231], v[80:83]
	v_mfma_f32_16x16x32_bf16 v[76:79], v[196:199], v[228:231], v[76:79]
	s_barrier
; #define PG8_STAGE(bufoff, gbase, voff) do { _Pragma("unroll") for (int _i = 0; _i < 2; ++_i) \
;         __builtin_amdgcn_global_load_lds((const unsigned*)((const char*)(gbase) + (voff)[_i]), (LAS unsigned*)(lds + (bufoff) + ldsw + _i * 8192), 16, 0, 0); } while (0)
; #define PG8_LDA(dst, b, h) do { _Pragma("unroll") for (int m = 0; m < 4; ++m) _Pragma("unroll") for (int k = 0; k < 2; ++k) dst[m][k] = *(const LAS bf16x8*)(lds + PG8_SA(b, h) + aoff + m * 2048 + k * 1024); } while (0)
; #define PG8_MMA(ai, bj, At, Bt) do { __builtin_amdgcn_s_setprio(1); _Pragma("unroll") for (int m = 0; m < 4; ++m) _Pragma("unroll") for (int n = 0; n < 2; ++n) _Pragma("unroll") for (int k = 0; k < 2; ++k) \
;         acc[ai][bj][m][n] = __builtin_amdgcn_mfma_f32_16x16x32_bf16(Bt[n][k], At[m][k], acc[ai][bj][m][n], 0, 0, 0); __builtin_amdgcn_s_setprio(0); } while (0)
; #define PG8_WAIT_V(n) asm volatile("s_waitcnt vmcnt(" #n ")" ::: "memory")
; #define PG8_WAIT_L(n) asm volatile("s_waitcnt lgkmcnt(" #n ")" ::: "memory")
; #define PG8_BAR __builtin_amdgcn_s_barrier()
; #define PG8_SCHED __builtin_amdgcn_sched_barrier(0)
; template <class Epi, class Map>
; __device__ __forceinline__ void gemm_phase(LAS unsigned char* lds, const Gemm g, const Sched<Map>& S, const Epi& E) {
;     ...
;             PG8_LDA(At, 1, 1); PG8_STAGE(PG8_SB(1, 0), b3, voffB); PG8_STAGE(PG8_SB(1, 1), b3 + hstepB, voffB); PG8_STAGE(PG8_SA(1, 0), a3, voffA);
;             PG8_WAIT_V(8); PG8_WAIT_L(0); PG8_BAR; PG8_MMA(1, 0, At, B0); PG8_MMA(1, 1, At, B1); PG8_BAR; PG8_SCHED;
;         }
;         if (wr == 0) PG8_BAR;
	s_add_i32 s34, s48, s2
	v_lshl_add_u64 v[170:171], v[170:171], 0, s[82:83]
	s_mov_b32 m0, s34
	ds_read_b128 v[200:203], v174 offset:49152
	ds_read_b128 v[204:207], v174 offset:50176
	ds_read_b128 v[208:211], v174 offset:51200
	ds_read_b128 v[212:215], v174 offset:52224
	ds_read_b128 v[216:219], v174 offset:53248
	ds_read_b128 v[220:223], v174 offset:54272
	ds_read_b128 v[224:227], v174 offset:55296
	ds_read_b128 v[228:231], v174 offset:56320
	global_load_lds_dwordx4 v[170:171], off
	s_add_i32 m0, s34, 0x2000
	s_add_u32 s30, s30, 0x200080
	v_lshl_add_u64 v[170:171], v[180:181], 0, s[82:83]
	s_addc_u32 s31, s31, 0
	s_add_i32 s34, s49, s2
	global_load_lds_dwordx4 v[170:171], off
	v_lshl_add_u64 v[170:171], s[30:31], 0, v[144:145]
	s_mov_b32 m0, s34
	s_nop 0
	global_load_lds_dwordx4 v[170:171], off
	v_lshl_add_u64 v[170:171], s[30:31], 0, v[160:161]
	s_add_i32 m0, s34, 0x2000
	s_nop 0
	global_load_lds_dwordx4 v[170:171], off
	v_lshl_add_u64 v[170:171], v[232:233], 0, s[82:83]
	s_mov_b32 m0, s9
	s_nop 0
	global_load_lds_dwordx4 v[170:171], off
	v_lshl_add_u64 v[170:171], v[234:235], 0, s[82:83]
	s_mov_b32 m0, s10
	s_nop 0
	global_load_lds_dwordx4 v[170:171], off
	s_waitcnt vmcnt(8)
	s_waitcnt lgkmcnt(0)
	s_barrier
	s_waitcnt lgkmcnt(0)
	v_mfma_f32_16x16x32_bf16 v[60:63], v[64:67], v[200:203], v[60:63]
	v_mfma_f32_16x16x32_bf16 v[56:59], v[72:75], v[200:203], v[56:59]
	v_mfma_f32_16x16x32_bf16 v[52:55], v[64:67], v[208:211], v[52:55]
	v_mfma_f32_16x16x32_bf16 v[48:51], v[72:75], v[208:211], v[48:51]
	v_mfma_f32_16x16x32_bf16 v[28:31], v[64:67], v[216:219], v[28:31]
	v_mfma_f32_16x16x32_bf16 v[24:27], v[72:75], v[216:219], v[24:27]
	v_mfma_f32_16x16x32_bf16 v[20:23], v[64:67], v[224:227], v[20:23]
	v_mfma_f32_16x16x32_bf16 v[8:11], v[72:75], v[224:227], v[8:11]
	v_mfma_f32_16x16x32_bf16 v[60:63], v[68:71], v[204:207], v[60:63]
	v_mfma_f32_16x16x32_bf16 v[56:59], v[108:111], v[204:207], v[56:59]
	v_mfma_f32_16x16x32_bf16 v[52:55], v[68:71], v[212:215], v[52:55]
	v_mfma_f32_16x16x32_bf16 v[48:51], v[108:111], v[212:215], v[48:51]
	v_mfma_f32_16x16x32_bf16 v[28:31], v[68:71], v[220:223], v[28:31]
	v_mfma_f32_16x16x32_bf16 v[24:27], v[108:111], v[220:223], v[24:27]
	v_mfma_f32_16x16x32_bf16 v[20:23], v[68:71], v[228:231], v[20:23]
	v_mfma_f32_16x16x32_bf16 v[8:11], v[108:111], v[228:231], v[8:11]
	v_mfma_f32_16x16x32_bf16 v[44:47], v[166:169], v[200:203], v[44:47]
	v_mfma_f32_16x16x32_bf16 v[40:43], v[192:195], v[200:203], v[40:43]
	v_mfma_f32_16x16x32_bf16 v[36:39], v[166:169], v[208:211], v[36:39]
	v_mfma_f32_16x16x32_bf16 v[32:35], v[192:195], v[208:211], v[32:35]
	v_mfma_f32_16x16x32_bf16 v[16:19], v[166:169], v[216:219], v[16:19]
	v_mfma_f32_16x16x32_bf16 v[12:15], v[192:195], v[216:219], v[12:15]
	v_mfma_f32_16x16x32_bf16 v[4:7], v[166:169], v[224:227], v[4:7]
	v_mfma_f32_16x16x32_bf16 v[0:3], v[192:195], v[224:227], v[0:3]
	v_mfma_f32_16x16x32_bf16 v[44:47], v[176:179], v[204:207], v[44:47]
	v_mfma_f32_16x16x32_bf16 v[40:43], v[196:199], v[204:207], v[40:43]
	v_mfma_f32_16x16x32_bf16 v[36:39], v[176:179], v[212:215], v[36:39]
	v_mfma_f32_16x16x32_bf16 v[32:35], v[196:199], v[212:215], v[32:35]
	v_mfma_f32_16x16x32_bf16 v[16:19], v[176:179], v[220:223], v[16:19]
	v_mfma_f32_16x16x32_bf16 v[12:15], v[196:199], v[220:223], v[12:15]
	v_mfma_f32_16x16x32_bf16 v[4:7], v[176:179], v[228:231], v[4:7]
	v_mfma_f32_16x16x32_bf16 v[0:3], v[196:199], v[228:231], v[0:3]
	s_barrier
	s_add_i32 s47, s47, 2
	s_add_u32 s28, s28, 0x100
	s_addc_u32 s29, s29, 0
	s_add_u32 s45, s45, 0x100
	s_addc_u32 s46, s46, 0
	s_cmpk_gt_u32 s47, 0x7d
	s_cbranch_scc0 .LBB0_1183
	s_and_b64 vcc, exec, s[18:19]
	s_cbranch_vccz .LBB0_1186
	s_barrier
